# GEMM K-loops: all per-phase s_setprio flips deleted (16 per iteration in each of the nine loops), on top of the kept version
# speedup vs baseline: 1.0036x; 1.0021x over previous
; #define PG8_STAGE(bufoff, gbase, voff) do { _Pragma("unroll") for (int _i = 0; _i < 2; ++_i) \
;         __builtin_amdgcn_global_load_lds((const unsigned*)((const char*)(gbase) + (voff)[_i]), (LAS unsigned*)(lds + (bufoff) + ldsw + _i * 8192), 16, 0, 0); } while (0)
; #define PG8_LDA(dst, b, h) do { _Pragma("unroll") for (int m = 0; m < 4; ++m) _Pragma("unroll") for (int k = 0; k < 2; ++k) dst[m][k] = *(const LAS bf16x8*)(lds + PG8_SA(b, h) + aoff + m * 2048 + k * 1024); } while (0)
; #define PG8_LDB(dst, b, h) do { _Pragma("unroll") for (int n = 0; n < 2; ++n) _Pragma("unroll") for (int k = 0; k < 2; ++k) dst[n][k] = *(const LAS bf16x8*)(lds + PG8_SB(b, h) + boff + n * 2048 + k * 1024); } while (0)
; #define PG8_MMA(ai, bj, At, Bt) do { __builtin_amdgcn_s_setprio(1); _Pragma("unroll") for (int m = 0; m < 4; ++m) _Pragma("unroll") for (int n = 0; n < 2; ++n) _Pragma("unroll") for (int k = 0; k < 2; ++k) \
;         acc[ai][bj][m][n] = __builtin_amdgcn_mfma_f32_16x16x32_bf16(Bt[n][k], At[m][k], acc[ai][bj][m][n], 0, 0, 0); __builtin_amdgcn_s_setprio(0); } while (0)
; #define PG8_WAIT_V(n) asm volatile("s_waitcnt vmcnt(" #n ")" ::: "memory")
; #define PG8_WAIT_L(n) asm volatile("s_waitcnt lgkmcnt(" #n ")" ::: "memory")
; #define PG8_BAR __builtin_amdgcn_s_barrier()
; #define PG8_SCHED __builtin_amdgcn_sched_barrier(0)
; template <class Epi, bool ALIGN_EPI = PG8_ALIGN>
; __device__ __forceinline__ void gemm_phase(LAS unsigned char* lds, const Gemm g, const StaticOrder& S, const Epi& E) {
;     ...
;             const bool last = (t == nt - 2);
;             const char* a1 = cA + (size_t)(t + 1) * kstep;
;             const char* a2 = last ? nA : cA + (size_t)(t + 2) * kstep; const char* b2 = last ? nB : cB + (size_t)(t + 2) * kstep;
;             const char* a3 = a2 + kstep; const char* b3 = b2 + kstep;
;             PG8_LDB(B0, 0, 0); PG8_LDB(B1, 0, 1); PG8_SCHED; PG8_LDA(At, 0, 0); PG8_STAGE(PG8_SA(1, 1), a1 + hstepA, voffA);
;             PG8_WAIT_V(8); PG8_WAIT_L(0); PG8_BAR; PG8_MMA(0, 0, At, B0); PG8_MMA(0, 1, At, B1); PG8_BAR; PG8_SCHED;
;             PG8_LDA(At, 0, 1); PG8_STAGE(PG8_SB(0, 0), b2, voffB); PG8_STAGE(PG8_SB(0, 1), b2 + hstepB, voffB); PG8_STAGE(PG8_SA(0, 0), a2, voffA);
;             PG8_WAIT_V(8); PG8_WAIT_L(0); PG8_BAR; PG8_MMA(1, 0, At, B0); PG8_MMA(1, 1, At, B1); PG8_BAR; PG8_SCHED;
.LBB0_219:
	s_add_i32 s49, s24, 2
	s_add_u32 s20, s2, 0xfff80080
	s_addc_u32 s21, s3, -1
	s_add_i32 s22, 16, 0x10000
	s_cmp_eq_u32 s46, s24
	s_cselect_b32 s25, s15, s21
	s_cselect_b32 s24, s34, s20
	s_cselect_b32 s51, s17, s37
	s_cselect_b32 s50, s16, s36
	s_add_i32 s20, 16, 0x14000
	v_add_u32_e32 v154, s22, v139
	v_add_u32_e32 v170, s20, v139
	ds_read_b128 v[142:145], v154
	ds_read_b128 v[146:149], v154 offset:1024
	ds_read_b128 v[150:153], v154 offset:2048
	ds_read_b128 v[154:157], v154 offset:3072
	ds_read_b128 v[158:161], v170
	ds_read_b128 v[162:165], v170 offset:1024
	ds_read_b128 v[166:169], v170 offset:2048
	ds_read_b128 v[170:173], v170 offset:3072
	v_lshl_add_u64 v[174:175], s[2:3], 0, v[134:135]
	s_add_i32 m0, s29, 0xc000
	ds_read_b128 v[184:187], v141
	ds_read_b128 v[188:191], v141 offset:1024
	ds_read_b128 v[192:195], v141 offset:2048
	ds_read_b128 v[196:199], v141 offset:3072
	ds_read_b128 v[200:203], v141 offset:4096
	ds_read_b128 v[204:207], v141 offset:5120
	ds_read_b128 v[208:211], v141 offset:6144
	ds_read_b128 v[212:215], v141 offset:7168
	global_load_lds_dwordx4 v[174:175], off
	v_lshl_add_u64 v[174:175], s[2:3], 0, v[136:137]
	s_add_i32 m0, s29, 0xe000
	s_nop 0
	global_load_lds_dwordx4 v[174:175], off
	s_waitcnt vmcnt(8)
	s_waitcnt lgkmcnt(0)
	s_barrier
	s_waitcnt lgkmcnt(0)
	v_mfma_f32_16x16x32_bf16 v[124:127], v[142:145], v[184:187], v[124:127]
	v_mfma_f32_16x16x32_bf16 v[116:119], v[150:153], v[184:187], v[116:119]
	v_mfma_f32_16x16x32_bf16 v[108:111], v[142:145], v[192:195], v[108:111]
	v_mfma_f32_16x16x32_bf16 v[100:103], v[150:153], v[192:195], v[100:103]
	v_mfma_f32_16x16x32_bf16 v[92:95], v[142:145], v[200:203], v[92:95]
	v_mfma_f32_16x16x32_bf16 v[84:87], v[150:153], v[200:203], v[84:87]
	v_mfma_f32_16x16x32_bf16 v[76:79], v[142:145], v[208:211], v[76:79]
	v_mfma_f32_16x16x32_bf16 v[68:71], v[150:153], v[208:211], v[68:71]
	v_mfma_f32_16x16x32_bf16 v[124:127], v[146:149], v[188:191], v[124:127]
	v_mfma_f32_16x16x32_bf16 v[116:119], v[154:157], v[188:191], v[116:119]
	v_mfma_f32_16x16x32_bf16 v[108:111], v[146:149], v[196:199], v[108:111]
	v_mfma_f32_16x16x32_bf16 v[100:103], v[154:157], v[196:199], v[100:103]
	v_mfma_f32_16x16x32_bf16 v[92:95], v[146:149], v[204:207], v[92:95]
	v_mfma_f32_16x16x32_bf16 v[84:87], v[154:157], v[204:207], v[84:87]
	v_mfma_f32_16x16x32_bf16 v[76:79], v[146:149], v[212:215], v[76:79]
	v_mfma_f32_16x16x32_bf16 v[68:71], v[154:157], v[212:215], v[68:71]
	v_mfma_f32_16x16x32_bf16 v[120:123], v[158:161], v[184:187], v[120:123]
	v_mfma_f32_16x16x32_bf16 v[112:115], v[166:169], v[184:187], v[112:115]
	v_mfma_f32_16x16x32_bf16 v[104:107], v[158:161], v[192:195], v[104:107]
	v_mfma_f32_16x16x32_bf16 v[96:99], v[166:169], v[192:195], v[96:99]
	v_mfma_f32_16x16x32_bf16 v[88:91], v[158:161], v[200:203], v[88:91]
	v_mfma_f32_16x16x32_bf16 v[80:83], v[166:169], v[200:203], v[80:83]
	v_mfma_f32_16x16x32_bf16 v[72:75], v[158:161], v[208:211], v[72:75]
	v_mfma_f32_16x16x32_bf16 v[64:67], v[166:169], v[208:211], v[64:67]
	v_mfma_f32_16x16x32_bf16 v[120:123], v[162:165], v[188:191], v[120:123]
	v_mfma_f32_16x16x32_bf16 v[112:115], v[170:173], v[188:191], v[112:115]
	v_mfma_f32_16x16x32_bf16 v[104:107], v[162:165], v[196:199], v[104:107]
	v_mfma_f32_16x16x32_bf16 v[96:99], v[170:173], v[196:199], v[96:99]
	v_mfma_f32_16x16x32_bf16 v[88:91], v[162:165], v[204:207], v[88:91]
	v_mfma_f32_16x16x32_bf16 v[80:83], v[170:173], v[204:207], v[80:83]
	v_mfma_f32_16x16x32_bf16 v[72:75], v[162:165], v[212:215], v[72:75]
	v_mfma_f32_16x16x32_bf16 v[64:67], v[170:173], v[212:215], v[64:67]
	s_barrier
	s_add_i32 s21, s22, s18
	v_lshl_add_u64 v[174:175], s[50:51], 0, v[176:177]
	s_mov_b32 m0, s21
	ds_read_b128 v[184:187], v141 offset:16384
	ds_read_b128 v[188:191], v141 offset:17408
	ds_read_b128 v[192:195], v141 offset:18432
	ds_read_b128 v[196:199], v141 offset:19456
	ds_read_b128 v[200:203], v141 offset:20480
	ds_read_b128 v[204:207], v141 offset:21504
	ds_read_b128 v[208:211], v141 offset:22528
	ds_read_b128 v[212:215], v141 offset:23552
	global_load_lds_dwordx4 v[174:175], off
	s_add_i32 m0, s21, 0x2000
	v_lshl_add_u64 v[216:217], s[50:51], 0, v[128:129]
	s_add_u32 s50, s50, s4
	s_addc_u32 s51, s51, s5
	s_add_i32 s20, s20, s18
	global_load_lds_dwordx4 v[216:217], off
	v_lshl_add_u64 v[218:219], s[50:51], 0, v[176:177]
	s_mov_b32 m0, s20
	v_lshl_add_u64 v[220:221], s[50:51], 0, v[128:129]
	global_load_lds_dwordx4 v[218:219], off
	s_add_i32 m0, s20, 0x2000
	v_lshl_add_u64 v[222:223], s[24:25], 0, v[132:133]
	global_load_lds_dwordx4 v[220:221], off
	s_mov_b32 m0, s29
	v_lshl_add_u64 v[224:225], s[24:25], 0, v[130:131]
	global_load_lds_dwordx4 v[222:223], off
	s_mov_b32 m0, s30
	s_nop 0
	global_load_lds_dwordx4 v[224:225], off
	s_waitcnt vmcnt(8)
	s_waitcnt lgkmcnt(0)
	s_barrier
; #define PG8_STAGE(bufoff, gbase, voff) do { _Pragma("unroll") for (int _i = 0; _i < 2; ++_i) \
;         __builtin_amdgcn_global_load_lds((const unsigned*)((const char*)(gbase) + (voff)[_i]), (LAS unsigned*)(lds + (bufoff) + ldsw + _i * 8192), 16, 0, 0); } while (0)
; #define PG8_LDA(dst, b, h) do { _Pragma("unroll") for (int m = 0; m < 4; ++m) _Pragma("unroll") for (int k = 0; k < 2; ++k) dst[m][k] = *(const LAS bf16x8*)(lds + PG8_SA(b, h) + aoff + m * 2048 + k * 1024); } while (0)
; #define PG8_LDB(dst, b, h) do { _Pragma("unroll") for (int n = 0; n < 2; ++n) _Pragma("unroll") for (int k = 0; k < 2; ++k) dst[n][k] = *(const LAS bf16x8*)(lds + PG8_SB(b, h) + boff + n * 2048 + k * 1024); } while (0)
; #define PG8_MMA(ai, bj, At, Bt) do { __builtin_amdgcn_s_setprio(1); _Pragma("unroll") for (int m = 0; m < 4; ++m) _Pragma("unroll") for (int n = 0; n < 2; ++n) _Pragma("unroll") for (int k = 0; k < 2; ++k) \
;         acc[ai][bj][m][n] = __builtin_amdgcn_mfma_f32_16x16x32_bf16(Bt[n][k], At[m][k], acc[ai][bj][m][n], 0, 0, 0); __builtin_amdgcn_s_setprio(0); } while (0)
; #define PG8_WAIT_V(n) asm volatile("s_waitcnt vmcnt(" #n ")" ::: "memory")
; #define PG8_WAIT_L(n) asm volatile("s_waitcnt lgkmcnt(" #n ")" ::: "memory")
; #define PG8_BAR __builtin_amdgcn_s_barrier()
; #define PG8_SCHED __builtin_amdgcn_sched_barrier(0)
; template <class Epi, bool ALIGN_EPI = PG8_ALIGN>
; __device__ __forceinline__ void gemm_phase(LAS unsigned char* lds, const Gemm g, const StaticOrder& S, const Epi& E) {
;     ...
;             PG8_WAIT_V(8); PG8_WAIT_L(0); PG8_BAR; PG8_MMA(1, 0, At, B0); PG8_MMA(1, 1, At, B1); PG8_BAR; PG8_SCHED;
;             PG8_LDB(B0, 1, 0); PG8_LDB(B1, 1, 1); PG8_SCHED; PG8_LDA(At, 1, 0); PG8_STAGE(PG8_SA(0, 1), a2 + hstepA, voffA);
;             PG8_WAIT_V(8); PG8_WAIT_L(0); PG8_BAR; PG8_MMA(0, 0, At, B0); PG8_MMA(0, 1, At, B1); PG8_BAR; PG8_SCHED;
	s_waitcnt lgkmcnt(0)
	v_mfma_f32_16x16x32_bf16 v[60:63], v[142:145], v[184:187], v[60:63]
	v_mfma_f32_16x16x32_bf16 v[52:55], v[150:153], v[184:187], v[52:55]
	v_mfma_f32_16x16x32_bf16 v[44:47], v[142:145], v[192:195], v[44:47]
	v_mfma_f32_16x16x32_bf16 v[36:39], v[150:153], v[192:195], v[36:39]
	v_mfma_f32_16x16x32_bf16 v[28:31], v[142:145], v[200:203], v[28:31]
	v_mfma_f32_16x16x32_bf16 v[20:23], v[150:153], v[200:203], v[20:23]
	v_mfma_f32_16x16x32_bf16 v[12:15], v[142:145], v[208:211], v[12:15]
	v_mfma_f32_16x16x32_bf16 v[4:7], v[150:153], v[208:211], v[4:7]
	v_mfma_f32_16x16x32_bf16 v[60:63], v[146:149], v[188:191], v[60:63]
	v_mfma_f32_16x16x32_bf16 v[52:55], v[154:157], v[188:191], v[52:55]
	v_mfma_f32_16x16x32_bf16 v[44:47], v[146:149], v[196:199], v[44:47]
	v_mfma_f32_16x16x32_bf16 v[36:39], v[154:157], v[196:199], v[36:39]
	v_mfma_f32_16x16x32_bf16 v[28:31], v[146:149], v[204:207], v[28:31]
	v_mfma_f32_16x16x32_bf16 v[20:23], v[154:157], v[204:207], v[20:23]
	v_mfma_f32_16x16x32_bf16 v[12:15], v[146:149], v[212:215], v[12:15]
	v_mfma_f32_16x16x32_bf16 v[4:7], v[154:157], v[212:215], v[4:7]
	v_mfma_f32_16x16x32_bf16 v[56:59], v[158:161], v[184:187], v[56:59]
	v_mfma_f32_16x16x32_bf16 v[48:51], v[166:169], v[184:187], v[48:51]
	v_mfma_f32_16x16x32_bf16 v[40:43], v[158:161], v[192:195], v[40:43]
	v_mfma_f32_16x16x32_bf16 v[32:35], v[166:169], v[192:195], v[32:35]
	v_mfma_f32_16x16x32_bf16 v[24:27], v[158:161], v[200:203], v[24:27]
	v_mfma_f32_16x16x32_bf16 v[16:19], v[166:169], v[200:203], v[16:19]
	v_mfma_f32_16x16x32_bf16 v[8:11], v[158:161], v[208:211], v[8:11]
	v_mfma_f32_16x16x32_bf16 v[0:3], v[166:169], v[208:211], v[0:3]
	v_mfma_f32_16x16x32_bf16 v[56:59], v[162:165], v[188:191], v[56:59]
	v_mfma_f32_16x16x32_bf16 v[48:51], v[170:173], v[188:191], v[48:51]
	v_mfma_f32_16x16x32_bf16 v[40:43], v[162:165], v[196:199], v[40:43]
	v_mfma_f32_16x16x32_bf16 v[32:35], v[170:173], v[196:199], v[32:35]
	v_mfma_f32_16x16x32_bf16 v[24:27], v[162:165], v[204:207], v[24:27]
	v_mfma_f32_16x16x32_bf16 v[16:19], v[170:173], v[204:207], v[16:19]
	v_mfma_f32_16x16x32_bf16 v[8:11], v[162:165], v[212:215], v[8:11]
	v_mfma_f32_16x16x32_bf16 v[0:3], v[170:173], v[212:215], v[0:3]
	s_barrier
	s_add_i32 s20, 16, 0x18000
	s_add_i32 s21, 16, 0x1c000
	v_add_u32_e32 v154, s20, v139
	v_add_u32_e32 v170, s21, v139
	ds_read_b128 v[142:145], v154
	ds_read_b128 v[146:149], v154 offset:1024
	ds_read_b128 v[150:153], v154 offset:2048
	ds_read_b128 v[154:157], v154 offset:3072
	ds_read_b128 v[158:161], v170
	ds_read_b128 v[162:165], v170 offset:1024
	ds_read_b128 v[166:169], v170 offset:2048
	ds_read_b128 v[170:173], v170 offset:3072
	s_add_u32 s24, s24, 0x80000
	s_addc_u32 s25, s25, 0
	s_mov_b32 m0, s31
	v_lshl_add_u64 v[226:227], s[24:25], 0, v[132:133]
	ds_read_b128 v[184:187], v141 offset:32768
	ds_read_b128 v[188:191], v141 offset:33792
	ds_read_b128 v[192:195], v141 offset:34816
	ds_read_b128 v[196:199], v141 offset:35840
	ds_read_b128 v[200:203], v141 offset:36864
	ds_read_b128 v[204:207], v141 offset:37888
	ds_read_b128 v[208:211], v141 offset:38912
	ds_read_b128 v[212:215], v141 offset:39936
	global_load_lds_dwordx4 v[226:227], off
	v_lshl_add_u64 v[226:227], s[24:25], 0, v[130:131]
	s_mov_b32 m0, s42
	s_nop 0
	global_load_lds_dwordx4 v[226:227], off
	s_waitcnt vmcnt(8)
	s_waitcnt lgkmcnt(0)
	s_barrier
	s_waitcnt lgkmcnt(0)
	v_mfma_f32_16x16x32_bf16 v[124:127], v[142:145], v[184:187], v[124:127]
	v_mfma_f32_16x16x32_bf16 v[116:119], v[150:153], v[184:187], v[116:119]
	v_mfma_f32_16x16x32_bf16 v[108:111], v[142:145], v[192:195], v[108:111]
	v_mfma_f32_16x16x32_bf16 v[100:103], v[150:153], v[192:195], v[100:103]
	v_mfma_f32_16x16x32_bf16 v[92:95], v[142:145], v[200:203], v[92:95]
	v_mfma_f32_16x16x32_bf16 v[84:87], v[150:153], v[200:203], v[84:87]
	v_mfma_f32_16x16x32_bf16 v[76:79], v[142:145], v[208:211], v[76:79]
	v_mfma_f32_16x16x32_bf16 v[68:71], v[150:153], v[208:211], v[68:71]
	v_mfma_f32_16x16x32_bf16 v[124:127], v[146:149], v[188:191], v[124:127]
	v_mfma_f32_16x16x32_bf16 v[116:119], v[154:157], v[188:191], v[116:119]
	v_mfma_f32_16x16x32_bf16 v[108:111], v[146:149], v[196:199], v[108:111]
	v_mfma_f32_16x16x32_bf16 v[100:103], v[154:157], v[196:199], v[100:103]
	v_mfma_f32_16x16x32_bf16 v[92:95], v[146:149], v[204:207], v[92:95]
	v_mfma_f32_16x16x32_bf16 v[84:87], v[154:157], v[204:207], v[84:87]
	v_mfma_f32_16x16x32_bf16 v[76:79], v[146:149], v[212:215], v[76:79]
	v_mfma_f32_16x16x32_bf16 v[68:71], v[154:157], v[212:215], v[68:71]
	v_mfma_f32_16x16x32_bf16 v[120:123], v[158:161], v[184:187], v[120:123]
	v_mfma_f32_16x16x32_bf16 v[112:115], v[166:169], v[184:187], v[112:115]
	v_mfma_f32_16x16x32_bf16 v[104:107], v[158:161], v[192:195], v[104:107]
	v_mfma_f32_16x16x32_bf16 v[96:99], v[166:169], v[192:195], v[96:99]
	v_mfma_f32_16x16x32_bf16 v[88:91], v[158:161], v[200:203], v[88:91]
	v_mfma_f32_16x16x32_bf16 v[80:83], v[166:169], v[200:203], v[80:83]
	v_mfma_f32_16x16x32_bf16 v[72:75], v[158:161], v[208:211], v[72:75]
	v_mfma_f32_16x16x32_bf16 v[64:67], v[166:169], v[208:211], v[64:67]
	v_mfma_f32_16x16x32_bf16 v[120:123], v[162:165], v[188:191], v[120:123]
	v_mfma_f32_16x16x32_bf16 v[112:115], v[170:173], v[188:191], v[112:115]
	v_mfma_f32_16x16x32_bf16 v[104:107], v[162:165], v[196:199], v[104:107]
	v_mfma_f32_16x16x32_bf16 v[96:99], v[170:173], v[196:199], v[96:99]
	v_mfma_f32_16x16x32_bf16 v[88:91], v[162:165], v[204:207], v[88:91]
	v_mfma_f32_16x16x32_bf16 v[80:83], v[170:173], v[204:207], v[80:83]
	v_mfma_f32_16x16x32_bf16 v[72:75], v[162:165], v[212:215], v[72:75]
	v_mfma_f32_16x16x32_bf16 v[64:67], v[170:173], v[212:215], v[64:67]
	s_barrier
; #define PG8_STAGE(bufoff, gbase, voff) do { _Pragma("unroll") for (int _i = 0; _i < 2; ++_i) \
;         __builtin_amdgcn_global_load_lds((const unsigned*)((const char*)(gbase) + (voff)[_i]), (LAS unsigned*)(lds + (bufoff) + ldsw + _i * 8192), 16, 0, 0); } while (0)
; #define PG8_LDA(dst, b, h) do { _Pragma("unroll") for (int m = 0; m < 4; ++m) _Pragma("unroll") for (int k = 0; k < 2; ++k) dst[m][k] = *(const LAS bf16x8*)(lds + PG8_SA(b, h) + aoff + m * 2048 + k * 1024); } while (0)
; #define PG8_MMA(ai, bj, At, Bt) do { __builtin_amdgcn_s_setprio(1); _Pragma("unroll") for (int m = 0; m < 4; ++m) _Pragma("unroll") for (int n = 0; n < 2; ++n) _Pragma("unroll") for (int k = 0; k < 2; ++k) \
;         acc[ai][bj][m][n] = __builtin_amdgcn_mfma_f32_16x16x32_bf16(Bt[n][k], At[m][k], acc[ai][bj][m][n], 0, 0, 0); __builtin_amdgcn_s_setprio(0); } while (0)
; #define PG8_WAIT_V(n) asm volatile("s_waitcnt vmcnt(" #n ")" ::: "memory")
; #define PG8_WAIT_L(n) asm volatile("s_waitcnt lgkmcnt(" #n ")" ::: "memory")
; #define PG8_BAR __builtin_amdgcn_s_barrier()
; #define PG8_SCHED __builtin_amdgcn_sched_barrier(0)
; template <class Epi, bool ALIGN_EPI = PG8_ALIGN>
; __device__ __forceinline__ void gemm_phase(LAS unsigned char* lds, const Gemm g, const StaticOrder& S, const Epi& E) {
;     ...
;             PG8_LDA(At, 1, 1); PG8_STAGE(PG8_SB(1, 0), b3, voffB); PG8_STAGE(PG8_SB(1, 1), b3 + hstepB, voffB); PG8_STAGE(PG8_SA(1, 0), a3, voffA);
;             PG8_WAIT_V(8); PG8_WAIT_L(0); PG8_BAR; PG8_MMA(1, 0, At, B0); PG8_MMA(1, 1, At, B1); PG8_BAR; PG8_SCHED;
;         }
	s_add_i32 s20, s20, s18
	v_lshl_add_u64 v[174:175], v[174:175], 0, s[0:1]
	s_mov_b32 m0, s20
	ds_read_b128 v[184:187], v141 offset:49152
	ds_read_b128 v[188:191], v141 offset:50176
	ds_read_b128 v[192:195], v141 offset:51200
	ds_read_b128 v[196:199], v141 offset:52224
	ds_read_b128 v[200:203], v141 offset:53248
	ds_read_b128 v[204:207], v141 offset:54272
	ds_read_b128 v[208:211], v141 offset:55296
	ds_read_b128 v[212:215], v141 offset:56320
	global_load_lds_dwordx4 v[174:175], off
	v_lshl_add_u64 v[174:175], v[216:217], 0, s[0:1]
	s_add_i32 m0, s20, 0x2000
	s_add_i32 s20, s21, s18
	global_load_lds_dwordx4 v[174:175], off
	v_lshl_add_u64 v[174:175], v[218:219], 0, s[0:1]
	s_mov_b32 m0, s20
	s_nop 0
	global_load_lds_dwordx4 v[174:175], off
	v_lshl_add_u64 v[174:175], v[220:221], 0, s[0:1]
	s_add_i32 m0, s20, 0x2000
	s_nop 0
	global_load_lds_dwordx4 v[174:175], off
	v_lshl_add_u64 v[174:175], v[222:223], 0, s[0:1]
	s_mov_b32 m0, s43
	s_nop 0
	global_load_lds_dwordx4 v[174:175], off
	v_lshl_add_u64 v[174:175], v[224:225], 0, s[0:1]
	s_mov_b32 m0, s44
	s_nop 0
	global_load_lds_dwordx4 v[174:175], off
	s_waitcnt vmcnt(8)
	s_waitcnt lgkmcnt(0)
	s_barrier
	s_waitcnt lgkmcnt(0)
	v_mfma_f32_16x16x32_bf16 v[60:63], v[142:145], v[184:187], v[60:63]
	v_mfma_f32_16x16x32_bf16 v[52:55], v[150:153], v[184:187], v[52:55]
	v_mfma_f32_16x16x32_bf16 v[44:47], v[142:145], v[192:195], v[44:47]
	v_mfma_f32_16x16x32_bf16 v[36:39], v[150:153], v[192:195], v[36:39]
	v_mfma_f32_16x16x32_bf16 v[28:31], v[142:145], v[200:203], v[28:31]
	v_mfma_f32_16x16x32_bf16 v[20:23], v[150:153], v[200:203], v[20:23]
	v_mfma_f32_16x16x32_bf16 v[12:15], v[142:145], v[208:211], v[12:15]
	v_mfma_f32_16x16x32_bf16 v[4:7], v[150:153], v[208:211], v[4:7]
	v_mfma_f32_16x16x32_bf16 v[60:63], v[146:149], v[188:191], v[60:63]
	v_mfma_f32_16x16x32_bf16 v[52:55], v[154:157], v[188:191], v[52:55]
	v_mfma_f32_16x16x32_bf16 v[44:47], v[146:149], v[196:199], v[44:47]
	v_mfma_f32_16x16x32_bf16 v[36:39], v[154:157], v[196:199], v[36:39]
	v_mfma_f32_16x16x32_bf16 v[28:31], v[146:149], v[204:207], v[28:31]
	v_mfma_f32_16x16x32_bf16 v[20:23], v[154:157], v[204:207], v[20:23]
	v_mfma_f32_16x16x32_bf16 v[12:15], v[146:149], v[212:215], v[12:15]
	v_mfma_f32_16x16x32_bf16 v[4:7], v[154:157], v[212:215], v[4:7]
	v_mfma_f32_16x16x32_bf16 v[56:59], v[158:161], v[184:187], v[56:59]
	v_mfma_f32_16x16x32_bf16 v[48:51], v[166:169], v[184:187], v[48:51]
	v_mfma_f32_16x16x32_bf16 v[40:43], v[158:161], v[192:195], v[40:43]
	v_mfma_f32_16x16x32_bf16 v[32:35], v[166:169], v[192:195], v[32:35]
	v_mfma_f32_16x16x32_bf16 v[24:27], v[158:161], v[200:203], v[24:27]
	v_mfma_f32_16x16x32_bf16 v[16:19], v[166:169], v[200:203], v[16:19]
	v_mfma_f32_16x16x32_bf16 v[8:11], v[158:161], v[208:211], v[8:11]
	v_mfma_f32_16x16x32_bf16 v[0:3], v[166:169], v[208:211], v[0:3]
	v_mfma_f32_16x16x32_bf16 v[56:59], v[162:165], v[188:191], v[56:59]
	v_mfma_f32_16x16x32_bf16 v[48:51], v[170:173], v[188:191], v[48:51]
	v_mfma_f32_16x16x32_bf16 v[40:43], v[162:165], v[196:199], v[40:43]
	v_mfma_f32_16x16x32_bf16 v[32:35], v[170:173], v[196:199], v[32:35]
	v_mfma_f32_16x16x32_bf16 v[24:27], v[162:165], v[204:207], v[24:27]
	v_mfma_f32_16x16x32_bf16 v[16:19], v[170:173], v[204:207], v[16:19]
	v_mfma_f32_16x16x32_bf16 v[8:11], v[162:165], v[212:215], v[8:11]
	v_mfma_f32_16x16x32_bf16 v[0:3], v[170:173], v[212:215], v[0:3]
	s_barrier
	s_add_u32 s2, s2, 0x100
	s_addc_u32 s3, s3, 0
	s_add_u32 s36, s36, 0x100
	s_addc_u32 s37, s37, 0
	s_cmp_ge_i32 s49, s45
	s_mov_b32 s24, s49
	s_cbranch_scc0 .LBB0_219

; #define PG8_STAGE(bufoff, gbase, voff) do { _Pragma("unroll") for (int _i = 0; _i < 2; ++_i) \
;         __builtin_amdgcn_global_load_lds((const unsigned*)((const char*)(gbase) + (voff)[_i]), (LAS unsigned*)(lds + (bufoff) + ldsw + _i * 8192), 16, 0, 0); } while (0)
; #define PG8_LDA(dst, b, h) do { _Pragma("unroll") for (int m = 0; m < 4; ++m) _Pragma("unroll") for (int k = 0; k < 2; ++k) dst[m][k] = *(const LAS bf16x8*)(lds + PG8_SA(b, h) + aoff + m * 2048 + k * 1024); } while (0)
; #define PG8_LDB(dst, b, h) do { _Pragma("unroll") for (int n = 0; n < 2; ++n) _Pragma("unroll") for (int k = 0; k < 2; ++k) dst[n][k] = *(const LAS bf16x8*)(lds + PG8_SB(b, h) + boff + n * 2048 + k * 1024); } while (0)
; #define PG8_MMA(ai, bj, At, Bt) do { __builtin_amdgcn_s_setprio(1); _Pragma("unroll") for (int m = 0; m < 4; ++m) _Pragma("unroll") for (int n = 0; n < 2; ++n) _Pragma("unroll") for (int k = 0; k < 2; ++k) \
;         acc[ai][bj][m][n] = __builtin_amdgcn_mfma_f32_16x16x32_bf16(Bt[n][k], At[m][k], acc[ai][bj][m][n], 0, 0, 0); __builtin_amdgcn_s_setprio(0); } while (0)
; #define PG8_WAIT_V(n) asm volatile("s_waitcnt vmcnt(" #n ")" ::: "memory")
; #define PG8_WAIT_L(n) asm volatile("s_waitcnt lgkmcnt(" #n ")" ::: "memory")
; #define PG8_BAR __builtin_amdgcn_s_barrier()
; #define PG8_SCHED __builtin_amdgcn_sched_barrier(0)
; template <class Epi, bool ALIGN_EPI = PG8_ALIGN>
; __device__ __forceinline__ void gemm_phase(LAS unsigned char* lds, const Gemm g, const StaticOrder& S, const Epi& E) {
;     ...
;             const bool last = (t == nt - 2);
;             const char* a1 = cA + (size_t)(t + 1) * kstep;
;             const char* a2 = last ? nA : cA + (size_t)(t + 2) * kstep; const char* b2 = last ? nB : cB + (size_t)(t + 2) * kstep;
;             const char* a3 = a2 + kstep; const char* b3 = b2 + kstep;
;             PG8_LDB(B0, 0, 0); PG8_LDB(B1, 0, 1); PG8_SCHED; PG8_LDA(At, 0, 0); PG8_STAGE(PG8_SA(1, 1), a1 + hstepA, voffA);
;             PG8_WAIT_V(8); PG8_WAIT_L(0); PG8_BAR; PG8_MMA(0, 0, At, B0); PG8_MMA(0, 1, At, B1); PG8_BAR; PG8_SCHED;
;             PG8_LDA(At, 0, 1); PG8_STAGE(PG8_SB(0, 0), b2, voffB); PG8_STAGE(PG8_SB(0, 1), b2 + hstepB, voffB); PG8_STAGE(PG8_SA(0, 0), a2, voffA);
;             PG8_WAIT_V(8); PG8_WAIT_L(0); PG8_BAR; PG8_MMA(1, 0, At, B0); PG8_MMA(1, 1, At, B1); PG8_BAR; PG8_SCHED;
.LBB0_295:
	s_add_i32 s53, s38, 2
	s_add_u32 s36, s24, 0x100
	s_addc_u32 s37, s25, 0
	s_add_i32 s20, 16, 0x10000
	s_cmp_eq_u32 s26, s38
	s_cselect_b32 s39, s3, s37
	s_cselect_b32 s38, s2, s36
	s_cselect_b32 s55, s17, s52
	s_cselect_b32 s54, s16, s51
	s_add_i32 s21, 16, 0x14000
	v_add_u32_e32 v154, s20, v147
	v_add_u32_e32 v170, s21, v147
	ds_read_b128 v[138:141], v154
	ds_read_b128 v[142:145], v154 offset:1024
	ds_read_b128 v[150:153], v154 offset:2048
	ds_read_b128 v[154:157], v154 offset:3072
	ds_read_b128 v[158:161], v170
	ds_read_b128 v[162:165], v170 offset:1024
	ds_read_b128 v[166:169], v170 offset:2048
	ds_read_b128 v[170:173], v170 offset:3072
	v_lshl_add_u64 v[174:175], s[24:25], 0, v[134:135]
	s_add_i32 m0, s31, 0xc000
	ds_read_b128 v[184:187], v149
	ds_read_b128 v[188:191], v149 offset:1024
	ds_read_b128 v[192:195], v149 offset:2048
	ds_read_b128 v[196:199], v149 offset:3072
	ds_read_b128 v[200:203], v149 offset:4096
	ds_read_b128 v[204:207], v149 offset:5120
	ds_read_b128 v[208:211], v149 offset:6144
	ds_read_b128 v[212:215], v149 offset:7168
	global_load_lds_dwordx4 v[174:175], off
	v_lshl_add_u64 v[174:175], s[24:25], 0, v[136:137]
	s_add_i32 m0, s31, 0xe000
	s_nop 0
	global_load_lds_dwordx4 v[174:175], off
	s_waitcnt vmcnt(8)
	s_waitcnt lgkmcnt(0)
	s_barrier
	s_waitcnt lgkmcnt(0)
	v_mfma_f32_16x16x32_bf16 v[124:127], v[138:141], v[184:187], v[124:127]
	v_mfma_f32_16x16x32_bf16 v[120:123], v[150:153], v[184:187], v[120:123]
	v_mfma_f32_16x16x32_bf16 v[116:119], v[138:141], v[192:195], v[116:119]
	v_mfma_f32_16x16x32_bf16 v[112:115], v[150:153], v[192:195], v[112:115]
	v_mfma_f32_16x16x32_bf16 v[104:107], v[138:141], v[200:203], v[104:107]
	v_mfma_f32_16x16x32_bf16 v[96:99], v[150:153], v[200:203], v[96:99]
	v_mfma_f32_16x16x32_bf16 v[88:91], v[138:141], v[208:211], v[88:91]
	v_mfma_f32_16x16x32_bf16 v[80:83], v[150:153], v[208:211], v[80:83]
	v_mfma_f32_16x16x32_bf16 v[124:127], v[142:145], v[188:191], v[124:127]
	v_mfma_f32_16x16x32_bf16 v[120:123], v[154:157], v[188:191], v[120:123]
	v_mfma_f32_16x16x32_bf16 v[116:119], v[142:145], v[196:199], v[116:119]
	v_mfma_f32_16x16x32_bf16 v[112:115], v[154:157], v[196:199], v[112:115]
	v_mfma_f32_16x16x32_bf16 v[104:107], v[142:145], v[204:207], v[104:107]
	v_mfma_f32_16x16x32_bf16 v[96:99], v[154:157], v[204:207], v[96:99]
	v_mfma_f32_16x16x32_bf16 v[88:91], v[142:145], v[212:215], v[88:91]
	v_mfma_f32_16x16x32_bf16 v[80:83], v[154:157], v[212:215], v[80:83]
	v_mfma_f32_16x16x32_bf16 v[108:111], v[158:161], v[184:187], v[108:111]
	v_mfma_f32_16x16x32_bf16 v[100:103], v[166:169], v[184:187], v[100:103]
	v_mfma_f32_16x16x32_bf16 v[92:95], v[158:161], v[192:195], v[92:95]
	v_mfma_f32_16x16x32_bf16 v[84:87], v[166:169], v[192:195], v[84:87]
	v_mfma_f32_16x16x32_bf16 v[76:79], v[158:161], v[200:203], v[76:79]
	v_mfma_f32_16x16x32_bf16 v[72:75], v[166:169], v[200:203], v[72:75]
	v_mfma_f32_16x16x32_bf16 v[68:71], v[158:161], v[208:211], v[68:71]
	v_mfma_f32_16x16x32_bf16 v[64:67], v[166:169], v[208:211], v[64:67]
	v_mfma_f32_16x16x32_bf16 v[108:111], v[162:165], v[188:191], v[108:111]
	v_mfma_f32_16x16x32_bf16 v[100:103], v[170:173], v[188:191], v[100:103]
	v_mfma_f32_16x16x32_bf16 v[92:95], v[162:165], v[196:199], v[92:95]
	v_mfma_f32_16x16x32_bf16 v[84:87], v[170:173], v[196:199], v[84:87]
	v_mfma_f32_16x16x32_bf16 v[76:79], v[162:165], v[204:207], v[76:79]
	v_mfma_f32_16x16x32_bf16 v[72:75], v[170:173], v[204:207], v[72:75]
	v_mfma_f32_16x16x32_bf16 v[68:71], v[162:165], v[212:215], v[68:71]
	v_mfma_f32_16x16x32_bf16 v[64:67], v[170:173], v[212:215], v[64:67]
	s_barrier
	s_add_i32 s20, s20, s18
	v_lshl_add_u64 v[174:175], s[54:55], 0, v[176:177]
	s_mov_b32 m0, s20
	ds_read_b128 v[184:187], v149 offset:16384
	ds_read_b128 v[188:191], v149 offset:17408
	ds_read_b128 v[192:195], v149 offset:18432
	ds_read_b128 v[196:199], v149 offset:19456
	ds_read_b128 v[200:203], v149 offset:20480
	ds_read_b128 v[204:207], v149 offset:21504
	ds_read_b128 v[208:211], v149 offset:22528
	ds_read_b128 v[212:215], v149 offset:23552
	global_load_lds_dwordx4 v[174:175], off
	s_add_i32 m0, s20, 0x2000
	s_add_u32 s24, s54, s6
	v_lshl_add_u64 v[216:217], s[54:55], 0, v[128:129]
	s_addc_u32 s25, s55, s7
	s_add_i32 s20, s21, s18
	global_load_lds_dwordx4 v[216:217], off
	v_lshl_add_u64 v[218:219], s[24:25], 0, v[176:177]
	s_mov_b32 m0, s20
	v_lshl_add_u64 v[220:221], s[24:25], 0, v[128:129]
	global_load_lds_dwordx4 v[218:219], off
	s_add_i32 m0, s20, 0x2000
	v_lshl_add_u64 v[222:223], s[38:39], 0, v[132:133]
	global_load_lds_dwordx4 v[220:221], off
	s_mov_b32 m0, s31
	v_lshl_add_u64 v[224:225], s[38:39], 0, v[130:131]
	global_load_lds_dwordx4 v[222:223], off
	s_mov_b32 m0, s40
	s_nop 0
	global_load_lds_dwordx4 v[224:225], off
	s_waitcnt vmcnt(8)
	s_waitcnt lgkmcnt(0)
	s_barrier
; #define PG8_STAGE(bufoff, gbase, voff) do { _Pragma("unroll") for (int _i = 0; _i < 2; ++_i) \
;         __builtin_amdgcn_global_load_lds((const unsigned*)((const char*)(gbase) + (voff)[_i]), (LAS unsigned*)(lds + (bufoff) + ldsw + _i * 8192), 16, 0, 0); } while (0)
; #define PG8_LDA(dst, b, h) do { _Pragma("unroll") for (int m = 0; m < 4; ++m) _Pragma("unroll") for (int k = 0; k < 2; ++k) dst[m][k] = *(const LAS bf16x8*)(lds + PG8_SA(b, h) + aoff + m * 2048 + k * 1024); } while (0)
; #define PG8_LDB(dst, b, h) do { _Pragma("unroll") for (int n = 0; n < 2; ++n) _Pragma("unroll") for (int k = 0; k < 2; ++k) dst[n][k] = *(const LAS bf16x8*)(lds + PG8_SB(b, h) + boff + n * 2048 + k * 1024); } while (0)
; #define PG8_MMA(ai, bj, At, Bt) do { __builtin_amdgcn_s_setprio(1); _Pragma("unroll") for (int m = 0; m < 4; ++m) _Pragma("unroll") for (int n = 0; n < 2; ++n) _Pragma("unroll") for (int k = 0; k < 2; ++k) \
;         acc[ai][bj][m][n] = __builtin_amdgcn_mfma_f32_16x16x32_bf16(Bt[n][k], At[m][k], acc[ai][bj][m][n], 0, 0, 0); __builtin_amdgcn_s_setprio(0); } while (0)
; #define PG8_WAIT_V(n) asm volatile("s_waitcnt vmcnt(" #n ")" ::: "memory")
; #define PG8_WAIT_L(n) asm volatile("s_waitcnt lgkmcnt(" #n ")" ::: "memory")
; #define PG8_BAR __builtin_amdgcn_s_barrier()
; #define PG8_SCHED __builtin_amdgcn_sched_barrier(0)
; template <class Epi, bool ALIGN_EPI = PG8_ALIGN>
; __device__ __forceinline__ void gemm_phase(LAS unsigned char* lds, const Gemm g, const StaticOrder& S, const Epi& E) {
;     ...
;             PG8_WAIT_V(8); PG8_WAIT_L(0); PG8_BAR; PG8_MMA(1, 0, At, B0); PG8_MMA(1, 1, At, B1); PG8_BAR; PG8_SCHED;
;             PG8_LDB(B0, 1, 0); PG8_LDB(B1, 1, 1); PG8_SCHED; PG8_LDA(At, 1, 0); PG8_STAGE(PG8_SA(0, 1), a2 + hstepA, voffA);
;             PG8_WAIT_V(8); PG8_WAIT_L(0); PG8_BAR; PG8_MMA(0, 0, At, B0); PG8_MMA(0, 1, At, B1); PG8_BAR; PG8_SCHED;
	s_waitcnt lgkmcnt(0)
	v_mfma_f32_16x16x32_bf16 v[60:63], v[138:141], v[184:187], v[60:63]
	v_mfma_f32_16x16x32_bf16 v[56:59], v[150:153], v[184:187], v[56:59]
	v_mfma_f32_16x16x32_bf16 v[52:55], v[138:141], v[192:195], v[52:55]
	v_mfma_f32_16x16x32_bf16 v[48:51], v[150:153], v[192:195], v[48:51]
	v_mfma_f32_16x16x32_bf16 v[40:43], v[138:141], v[200:203], v[40:43]
	v_mfma_f32_16x16x32_bf16 v[32:35], v[150:153], v[200:203], v[32:35]
	v_mfma_f32_16x16x32_bf16 v[24:27], v[138:141], v[208:211], v[24:27]
	v_mfma_f32_16x16x32_bf16 v[16:19], v[150:153], v[208:211], v[16:19]
	v_mfma_f32_16x16x32_bf16 v[60:63], v[142:145], v[188:191], v[60:63]
	v_mfma_f32_16x16x32_bf16 v[56:59], v[154:157], v[188:191], v[56:59]
	v_mfma_f32_16x16x32_bf16 v[52:55], v[142:145], v[196:199], v[52:55]
	v_mfma_f32_16x16x32_bf16 v[48:51], v[154:157], v[196:199], v[48:51]
	v_mfma_f32_16x16x32_bf16 v[40:43], v[142:145], v[204:207], v[40:43]
	v_mfma_f32_16x16x32_bf16 v[32:35], v[154:157], v[204:207], v[32:35]
	v_mfma_f32_16x16x32_bf16 v[24:27], v[142:145], v[212:215], v[24:27]
	v_mfma_f32_16x16x32_bf16 v[16:19], v[154:157], v[212:215], v[16:19]
	v_mfma_f32_16x16x32_bf16 v[44:47], v[158:161], v[184:187], v[44:47]
	v_mfma_f32_16x16x32_bf16 v[36:39], v[166:169], v[184:187], v[36:39]
	v_mfma_f32_16x16x32_bf16 v[28:31], v[158:161], v[192:195], v[28:31]
	v_mfma_f32_16x16x32_bf16 v[20:23], v[166:169], v[192:195], v[20:23]
	v_mfma_f32_16x16x32_bf16 v[12:15], v[158:161], v[200:203], v[12:15]
	v_mfma_f32_16x16x32_bf16 v[8:11], v[166:169], v[200:203], v[8:11]
	v_mfma_f32_16x16x32_bf16 v[4:7], v[158:161], v[208:211], v[4:7]
	v_mfma_f32_16x16x32_bf16 v[0:3], v[166:169], v[208:211], v[0:3]
	v_mfma_f32_16x16x32_bf16 v[44:47], v[162:165], v[188:191], v[44:47]
	v_mfma_f32_16x16x32_bf16 v[36:39], v[170:173], v[188:191], v[36:39]
	v_mfma_f32_16x16x32_bf16 v[28:31], v[162:165], v[196:199], v[28:31]
	v_mfma_f32_16x16x32_bf16 v[20:23], v[170:173], v[196:199], v[20:23]
	v_mfma_f32_16x16x32_bf16 v[12:15], v[162:165], v[204:207], v[12:15]
	v_mfma_f32_16x16x32_bf16 v[8:11], v[170:173], v[204:207], v[8:11]
	v_mfma_f32_16x16x32_bf16 v[4:7], v[162:165], v[212:215], v[4:7]
	v_mfma_f32_16x16x32_bf16 v[0:3], v[170:173], v[212:215], v[0:3]
	s_barrier
	s_add_i32 s20, 16, 0x18000
	s_add_i32 s21, 16, 0x1c000
	v_add_u32_e32 v154, s20, v147
	v_add_u32_e32 v170, s21, v147
	ds_read_b128 v[138:141], v154
	ds_read_b128 v[142:145], v154 offset:1024
	ds_read_b128 v[150:153], v154 offset:2048
	ds_read_b128 v[154:157], v154 offset:3072
	ds_read_b128 v[158:161], v170
	ds_read_b128 v[162:165], v170 offset:1024
	ds_read_b128 v[166:169], v170 offset:2048
	ds_read_b128 v[170:173], v170 offset:3072
	s_add_u32 s24, s38, 0x160000
	s_addc_u32 s25, s39, 0
	s_mov_b32 m0, s41
	v_lshl_add_u64 v[226:227], s[24:25], 0, v[132:133]
	ds_read_b128 v[184:187], v149 offset:32768
	ds_read_b128 v[188:191], v149 offset:33792
	ds_read_b128 v[192:195], v149 offset:34816
	ds_read_b128 v[196:199], v149 offset:35840
	ds_read_b128 v[200:203], v149 offset:36864
	ds_read_b128 v[204:207], v149 offset:37888
	ds_read_b128 v[208:211], v149 offset:38912
	ds_read_b128 v[212:215], v149 offset:39936
	global_load_lds_dwordx4 v[226:227], off
	v_lshl_add_u64 v[226:227], s[24:25], 0, v[130:131]
	s_mov_b32 m0, s44
	s_nop 0
	global_load_lds_dwordx4 v[226:227], off
	s_waitcnt vmcnt(8)
	s_waitcnt lgkmcnt(0)
	s_barrier
	s_waitcnt lgkmcnt(0)
	v_mfma_f32_16x16x32_bf16 v[124:127], v[138:141], v[184:187], v[124:127]
	v_mfma_f32_16x16x32_bf16 v[120:123], v[150:153], v[184:187], v[120:123]
	v_mfma_f32_16x16x32_bf16 v[116:119], v[138:141], v[192:195], v[116:119]
	v_mfma_f32_16x16x32_bf16 v[112:115], v[150:153], v[192:195], v[112:115]
	v_mfma_f32_16x16x32_bf16 v[104:107], v[138:141], v[200:203], v[104:107]
	v_mfma_f32_16x16x32_bf16 v[96:99], v[150:153], v[200:203], v[96:99]
	v_mfma_f32_16x16x32_bf16 v[88:91], v[138:141], v[208:211], v[88:91]
	v_mfma_f32_16x16x32_bf16 v[80:83], v[150:153], v[208:211], v[80:83]
	v_mfma_f32_16x16x32_bf16 v[124:127], v[142:145], v[188:191], v[124:127]
	v_mfma_f32_16x16x32_bf16 v[120:123], v[154:157], v[188:191], v[120:123]
	v_mfma_f32_16x16x32_bf16 v[116:119], v[142:145], v[196:199], v[116:119]
	v_mfma_f32_16x16x32_bf16 v[112:115], v[154:157], v[196:199], v[112:115]
	v_mfma_f32_16x16x32_bf16 v[104:107], v[142:145], v[204:207], v[104:107]
	v_mfma_f32_16x16x32_bf16 v[96:99], v[154:157], v[204:207], v[96:99]
	v_mfma_f32_16x16x32_bf16 v[88:91], v[142:145], v[212:215], v[88:91]
	v_mfma_f32_16x16x32_bf16 v[80:83], v[154:157], v[212:215], v[80:83]
	v_mfma_f32_16x16x32_bf16 v[108:111], v[158:161], v[184:187], v[108:111]
	v_mfma_f32_16x16x32_bf16 v[100:103], v[166:169], v[184:187], v[100:103]
	v_mfma_f32_16x16x32_bf16 v[92:95], v[158:161], v[192:195], v[92:95]
	v_mfma_f32_16x16x32_bf16 v[84:87], v[166:169], v[192:195], v[84:87]
	v_mfma_f32_16x16x32_bf16 v[76:79], v[158:161], v[200:203], v[76:79]
	v_mfma_f32_16x16x32_bf16 v[72:75], v[166:169], v[200:203], v[72:75]
	v_mfma_f32_16x16x32_bf16 v[68:71], v[158:161], v[208:211], v[68:71]
	v_mfma_f32_16x16x32_bf16 v[64:67], v[166:169], v[208:211], v[64:67]
	v_mfma_f32_16x16x32_bf16 v[108:111], v[162:165], v[188:191], v[108:111]
	v_mfma_f32_16x16x32_bf16 v[100:103], v[170:173], v[188:191], v[100:103]
	v_mfma_f32_16x16x32_bf16 v[92:95], v[162:165], v[196:199], v[92:95]
	v_mfma_f32_16x16x32_bf16 v[84:87], v[170:173], v[196:199], v[84:87]
	v_mfma_f32_16x16x32_bf16 v[76:79], v[162:165], v[204:207], v[76:79]
	v_mfma_f32_16x16x32_bf16 v[72:75], v[170:173], v[204:207], v[72:75]
	v_mfma_f32_16x16x32_bf16 v[68:71], v[162:165], v[212:215], v[68:71]
	v_mfma_f32_16x16x32_bf16 v[64:67], v[170:173], v[212:215], v[64:67]
	s_barrier
; #define PG8_STAGE(bufoff, gbase, voff) do { _Pragma("unroll") for (int _i = 0; _i < 2; ++_i) \
;         __builtin_amdgcn_global_load_lds((const unsigned*)((const char*)(gbase) + (voff)[_i]), (LAS unsigned*)(lds + (bufoff) + ldsw + _i * 8192), 16, 0, 0); } while (0)
; #define PG8_LDA(dst, b, h) do { _Pragma("unroll") for (int m = 0; m < 4; ++m) _Pragma("unroll") for (int k = 0; k < 2; ++k) dst[m][k] = *(const LAS bf16x8*)(lds + PG8_SA(b, h) + aoff + m * 2048 + k * 1024); } while (0)
; #define PG8_MMA(ai, bj, At, Bt) do { __builtin_amdgcn_s_setprio(1); _Pragma("unroll") for (int m = 0; m < 4; ++m) _Pragma("unroll") for (int n = 0; n < 2; ++n) _Pragma("unroll") for (int k = 0; k < 2; ++k) \
;         acc[ai][bj][m][n] = __builtin_amdgcn_mfma_f32_16x16x32_bf16(Bt[n][k], At[m][k], acc[ai][bj][m][n], 0, 0, 0); __builtin_amdgcn_s_setprio(0); } while (0)
; #define PG8_WAIT_V(n) asm volatile("s_waitcnt vmcnt(" #n ")" ::: "memory")
; #define PG8_WAIT_L(n) asm volatile("s_waitcnt lgkmcnt(" #n ")" ::: "memory")
; #define PG8_BAR __builtin_amdgcn_s_barrier()
; #define PG8_SCHED __builtin_amdgcn_sched_barrier(0)
;     __device__ __forceinline__ void operator()(const f32x4 (&acc)[2][2][4][2], const Unit& u, int wr, int wc, int fr, int fq) const {
;     ...
;                 for (int bj = 0; bj < 2; ++bj) { const f32x4 v0 = acc[ai][bj][m][0] * sc, v1 = acc[ai][bj][m][1] * sc;
; template <class Epi, bool ALIGN_EPI = PG8_ALIGN>
; __device__ __forceinline__ void gemm_phase(LAS unsigned char* lds, const Gemm g, const StaticOrder& S, const Epi& E) {
;     ...
;             PG8_LDA(At, 1, 1); PG8_STAGE(PG8_SB(1, 0), b3, voffB); PG8_STAGE(PG8_SB(1, 1), b3 + hstepB, voffB); PG8_STAGE(PG8_SA(1, 0), a3, voffA);
;             PG8_WAIT_V(8); PG8_WAIT_L(0); PG8_BAR; PG8_MMA(1, 0, At, B0); PG8_MMA(1, 1, At, B1); PG8_BAR; PG8_SCHED;
	s_add_i32 s20, s20, s18
	v_lshl_add_u64 v[174:175], v[174:175], 0, s[0:1]
	s_mov_b32 m0, s20
	ds_read_b128 v[184:187], v149 offset:49152
	ds_read_b128 v[188:191], v149 offset:50176
	ds_read_b128 v[192:195], v149 offset:51200
	ds_read_b128 v[196:199], v149 offset:52224
	ds_read_b128 v[200:203], v149 offset:53248
	ds_read_b128 v[204:207], v149 offset:54272
	ds_read_b128 v[208:211], v149 offset:55296
	ds_read_b128 v[212:215], v149 offset:56320
	global_load_lds_dwordx4 v[174:175], off
	v_lshl_add_u64 v[174:175], v[216:217], 0, s[0:1]
	s_add_i32 m0, s20, 0x2000
	s_add_i32 s20, s21, s18
	global_load_lds_dwordx4 v[174:175], off
	v_lshl_add_u64 v[174:175], v[218:219], 0, s[0:1]
	s_mov_b32 m0, s20
	s_nop 0
	global_load_lds_dwordx4 v[174:175], off
	v_lshl_add_u64 v[174:175], v[220:221], 0, s[0:1]
	s_add_i32 m0, s20, 0x2000
	s_nop 0
	global_load_lds_dwordx4 v[174:175], off
	v_lshl_add_u64 v[174:175], v[222:223], 0, s[0:1]
	s_mov_b32 m0, s45
	s_nop 0
	global_load_lds_dwordx4 v[174:175], off
	v_lshl_add_u64 v[174:175], v[224:225], 0, s[0:1]
	s_mov_b32 m0, s46
	s_nop 0
	global_load_lds_dwordx4 v[174:175], off
	s_waitcnt vmcnt(8)
	s_waitcnt lgkmcnt(0)
	s_barrier
	s_waitcnt lgkmcnt(0)
	v_mfma_f32_16x16x32_bf16 v[60:63], v[138:141], v[184:187], v[60:63]
	v_mfma_f32_16x16x32_bf16 v[56:59], v[150:153], v[184:187], v[56:59]
	v_mfma_f32_16x16x32_bf16 v[52:55], v[138:141], v[192:195], v[52:55]
	v_mfma_f32_16x16x32_bf16 v[48:51], v[150:153], v[192:195], v[48:51]
	v_mfma_f32_16x16x32_bf16 v[40:43], v[138:141], v[200:203], v[40:43]
	v_mfma_f32_16x16x32_bf16 v[32:35], v[150:153], v[200:203], v[32:35]
	v_mfma_f32_16x16x32_bf16 v[24:27], v[138:141], v[208:211], v[24:27]
	v_mfma_f32_16x16x32_bf16 v[16:19], v[150:153], v[208:211], v[16:19]
	v_mfma_f32_16x16x32_bf16 v[60:63], v[142:145], v[188:191], v[60:63]
	v_mfma_f32_16x16x32_bf16 v[56:59], v[154:157], v[188:191], v[56:59]
	v_mfma_f32_16x16x32_bf16 v[52:55], v[142:145], v[196:199], v[52:55]
	v_mfma_f32_16x16x32_bf16 v[48:51], v[154:157], v[196:199], v[48:51]
	v_mfma_f32_16x16x32_bf16 v[40:43], v[142:145], v[204:207], v[40:43]
	v_mfma_f32_16x16x32_bf16 v[32:35], v[154:157], v[204:207], v[32:35]
	v_mfma_f32_16x16x32_bf16 v[24:27], v[142:145], v[212:215], v[24:27]
	v_mfma_f32_16x16x32_bf16 v[16:19], v[154:157], v[212:215], v[16:19]
	v_mfma_f32_16x16x32_bf16 v[44:47], v[158:161], v[184:187], v[44:47]
	v_mfma_f32_16x16x32_bf16 v[36:39], v[166:169], v[184:187], v[36:39]
	v_mfma_f32_16x16x32_bf16 v[28:31], v[158:161], v[192:195], v[28:31]
	v_mfma_f32_16x16x32_bf16 v[20:23], v[166:169], v[192:195], v[20:23]
	v_mfma_f32_16x16x32_bf16 v[12:15], v[158:161], v[200:203], v[12:15]
	v_mfma_f32_16x16x32_bf16 v[8:11], v[166:169], v[200:203], v[8:11]
	v_mfma_f32_16x16x32_bf16 v[4:7], v[158:161], v[208:211], v[4:7]
	v_mfma_f32_16x16x32_bf16 v[0:3], v[166:169], v[208:211], v[0:3]
	v_mfma_f32_16x16x32_bf16 v[44:47], v[162:165], v[188:191], v[44:47]
	v_mfma_f32_16x16x32_bf16 v[36:39], v[170:173], v[188:191], v[36:39]
	v_mfma_f32_16x16x32_bf16 v[28:31], v[162:165], v[196:199], v[28:31]
	v_mfma_f32_16x16x32_bf16 v[20:23], v[170:173], v[196:199], v[20:23]
	v_mfma_f32_16x16x32_bf16 v[12:15], v[162:165], v[204:207], v[12:15]
	v_mfma_f32_16x16x32_bf16 v[8:11], v[170:173], v[204:207], v[8:11]
	v_mfma_f32_16x16x32_bf16 v[4:7], v[162:165], v[212:215], v[4:7]
	v_mfma_f32_16x16x32_bf16 v[0:3], v[170:173], v[212:215], v[0:3]
	s_barrier
	s_add_u32 s51, s51, 0x100
	s_addc_u32 s52, s52, 0
	s_cmp_ge_i32 s53, s47
	s_mov_b64 s[24:25], s[36:37]
	s_mov_b32 s38, s53
	s_cbranch_scc0 .LBB0_295
	v_pk_mul_f32 v[126:127], v[126:127], 0.5 op_sel_hi:[1,0]
	v_pk_mul_f32 v[124:125], v[124:125], 0.5 op_sel_hi:[1,0]
	v_pk_mul_f32 v[122:123], v[122:123], 0.5 op_sel_hi:[1,0]
	v_pk_mul_f32 v[120:121], v[120:121], 0.5 op_sel_hi:[1,0]
	v_pk_mul_f32 v[138:139], v[110:111], 0.5 op_sel_hi:[1,0]
	v_pk_mul_f32 v[140:141], v[108:109], 0.5 op_sel_hi:[1,0]
	v_pk_mul_f32 v[142:143], v[102:103], 0.5 op_sel_hi:[1,0]
	v_pk_mul_f32 v[144:145], v[100:101], 0.5 op_sel_hi:[1,0]
	v_pk_mul_f32 v[100:101], v[118:119], 0.5 op_sel_hi:[1,0]
	v_pk_mul_f32 v[102:103], v[116:117], 0.5 op_sel_hi:[1,0]
	v_pk_mul_f32 v[108:109], v[114:115], 0.5 op_sel_hi:[1,0]
	v_pk_mul_f32 v[110:111], v[112:113], 0.5 op_sel_hi:[1,0]
	v_pk_mul_f32 v[112:113], v[94:95], 0.5 op_sel_hi:[1,0]
	v_pk_mul_f32 v[114:115], v[92:93], 0.5 op_sel_hi:[1,0]
	v_pk_mul_f32 v[116:117], v[86:87], 0.5 op_sel_hi:[1,0]
	v_pk_mul_f32 v[118:119], v[84:85], 0.5 op_sel_hi:[1,0]
	v_pk_mul_f32 v[84:85], v[106:107], 0.5 op_sel_hi:[1,0]
	v_pk_mul_f32 v[86:87], v[104:105], 0.5 op_sel_hi:[1,0]
	v_pk_mul_f32 v[92:93], v[98:99], 0.5 op_sel_hi:[1,0]
	v_pk_mul_f32 v[94:95], v[96:97], 0.5 op_sel_hi:[1,0]
	v_pk_mul_f32 v[96:97], v[78:79], 0.5 op_sel_hi:[1,0]
	v_pk_mul_f32 v[98:99], v[76:77], 0.5 op_sel_hi:[1,0]
	v_pk_mul_f32 v[104:105], v[74:75], 0.5 op_sel_hi:[1,0]
	v_pk_mul_f32 v[106:107], v[72:73], 0.5 op_sel_hi:[1,0]
	v_pk_mul_f32 v[72:73], v[90:91], 0.5 op_sel_hi:[1,0]
	v_pk_mul_f32 v[74:75], v[88:89], 0.5 op_sel_hi:[1,0]
	v_pk_mul_f32 v[76:77], v[82:83], 0.5 op_sel_hi:[1,0]
	v_pk_mul_f32 v[78:79], v[80:81], 0.5 op_sel_hi:[1,0]
	v_pk_mul_f32 v[70:71], v[70:71], 0.5 op_sel_hi:[1,0]
	v_pk_mul_f32 v[68:69], v[68:69], 0.5 op_sel_hi:[1,0]
	v_pk_mul_f32 v[66:67], v[66:67], 0.5 op_sel_hi:[1,0]
	v_pk_mul_f32 v[64:65], v[64:65], 0.5 op_sel_hi:[1,0]
	v_pk_mul_f32 v[62:63], v[62:63], 0.5 op_sel_hi:[1,0]
	v_pk_mul_f32 v[60:61], v[60:61], 0.5 op_sel_hi:[1,0]
	v_pk_mul_f32 v[58:59], v[58:59], 0.5 op_sel_hi:[1,0]
	v_pk_mul_f32 v[56:57], v[56:57], 0.5 op_sel_hi:[1,0]
	v_pk_mul_f32 v[80:81], v[46:47], 0.5 op_sel_hi:[1,0]
	v_pk_mul_f32 v[82:83], v[44:45], 0.5 op_sel_hi:[1,0]
	v_pk_mul_f32 v[88:89], v[38:39], 0.5 op_sel_hi:[1,0]
	v_pk_mul_f32 v[90:91], v[36:37], 0.5 op_sel_hi:[1,0]
	v_pk_mul_f32 v[36:37], v[54:55], 0.5 op_sel_hi:[1,0]
	v_pk_mul_f32 v[38:39], v[52:53], 0.5 op_sel_hi:[1,0]
	v_pk_mul_f32 v[44:45], v[50:51], 0.5 op_sel_hi:[1,0]
	v_pk_mul_f32 v[46:47], v[48:49], 0.5 op_sel_hi:[1,0]
	v_pk_mul_f32 v[48:49], v[30:31], 0.5 op_sel_hi:[1,0]
	v_pk_mul_f32 v[50:51], v[28:29], 0.5 op_sel_hi:[1,0]
	v_pk_mul_f32 v[52:53], v[22:23], 0.5 op_sel_hi:[1,0]
	v_pk_mul_f32 v[54:55], v[20:21], 0.5 op_sel_hi:[1,0]
	v_pk_mul_f32 v[20:21], v[42:43], 0.5 op_sel_hi:[1,0]
	v_pk_mul_f32 v[22:23], v[40:41], 0.5 op_sel_hi:[1,0]
	v_pk_mul_f32 v[28:29], v[34:35], 0.5 op_sel_hi:[1,0]
	v_pk_mul_f32 v[30:31], v[32:33], 0.5 op_sel_hi:[1,0]
	v_pk_mul_f32 v[32:33], v[14:15], 0.5 op_sel_hi:[1,0]
	v_pk_mul_f32 v[34:35], v[12:13], 0.5 op_sel_hi:[1,0]
	v_pk_mul_f32 v[40:41], v[10:11], 0.5 op_sel_hi:[1,0]
	v_pk_mul_f32 v[42:43], v[8:9], 0.5 op_sel_hi:[1,0]
	v_pk_mul_f32 v[8:9], v[26:27], 0.5 op_sel_hi:[1,0]
	v_pk_mul_f32 v[10:11], v[24:25], 0.5 op_sel_hi:[1,0]
	v_pk_mul_f32 v[12:13], v[18:19], 0.5 op_sel_hi:[1,0]
	v_pk_mul_f32 v[14:15], v[16:17], 0.5 op_sel_hi:[1,0]
	v_pk_mul_f32 v[6:7], v[6:7], 0.5 op_sel_hi:[1,0]
	v_pk_mul_f32 v[4:5], v[4:5], 0.5 op_sel_hi:[1,0]
	v_pk_mul_f32 v[2:3], v[2:3], 0.5 op_sel_hi:[1,0]
	v_pk_mul_f32 v[0:1], v[0:1], 0.5 op_sel_hi:[1,0]

; #define PG8_STAGE(bufoff, gbase, voff) do { _Pragma("unroll") for (int _i = 0; _i < 2; ++_i) \
;         __builtin_amdgcn_global_load_lds((const unsigned*)((const char*)(gbase) + (voff)[_i]), (LAS unsigned*)(lds + (bufoff) + ldsw + _i * 8192), 16, 0, 0); } while (0)
; #define PG8_LDA(dst, b, h) do { _Pragma("unroll") for (int m = 0; m < 4; ++m) _Pragma("unroll") for (int k = 0; k < 2; ++k) dst[m][k] = *(const LAS bf16x8*)(lds + PG8_SA(b, h) + aoff + m * 2048 + k * 1024); } while (0)
; #define PG8_LDB(dst, b, h) do { _Pragma("unroll") for (int n = 0; n < 2; ++n) _Pragma("unroll") for (int k = 0; k < 2; ++k) dst[n][k] = *(const LAS bf16x8*)(lds + PG8_SB(b, h) + boff + n * 2048 + k * 1024); } while (0)
; #define PG8_MMA(ai, bj, At, Bt) do { __builtin_amdgcn_s_setprio(1); _Pragma("unroll") for (int m = 0; m < 4; ++m) _Pragma("unroll") for (int n = 0; n < 2; ++n) _Pragma("unroll") for (int k = 0; k < 2; ++k) \
;         acc[ai][bj][m][n] = __builtin_amdgcn_mfma_f32_16x16x32_bf16(Bt[n][k], At[m][k], acc[ai][bj][m][n], 0, 0, 0); __builtin_amdgcn_s_setprio(0); } while (0)
; #define PG8_WAIT_V(n) asm volatile("s_waitcnt vmcnt(" #n ")" ::: "memory")
; #define PG8_WAIT_L(n) asm volatile("s_waitcnt lgkmcnt(" #n ")" ::: "memory")
; #define PG8_BAR __builtin_amdgcn_s_barrier()
; #define PG8_SCHED __builtin_amdgcn_sched_barrier(0)
; template <class Epi, bool ALIGN_EPI = PG8_ALIGN>
; __device__ __forceinline__ void gemm_phase(LAS unsigned char* lds, const Gemm g, const StaticOrder& S, const Epi& E) {
;     ...
;         for (int t = 0; t < nt; t += 2) {
;             const bool last = (t == nt - 2);
;             const char* a1 = cA + (size_t)(t + 1) * kstep;
;             const char* a2 = last ? nA : cA + (size_t)(t + 2) * kstep; const char* b2 = last ? nB : cB + (size_t)(t + 2) * kstep;
;             const char* a3 = a2 + kstep; const char* b3 = b2 + kstep;
;             PG8_LDB(B0, 0, 0); PG8_LDB(B1, 0, 1); PG8_SCHED; PG8_LDA(At, 0, 0); PG8_STAGE(PG8_SA(1, 1), a1 + hstepA, voffA);
;             PG8_WAIT_V(8); PG8_WAIT_L(0); PG8_BAR; PG8_MMA(0, 0, At, B0); PG8_MMA(0, 1, At, B1); PG8_BAR; PG8_SCHED;
;             PG8_LDA(At, 0, 1); PG8_STAGE(PG8_SB(0, 0), b2, voffB); PG8_STAGE(PG8_SB(0, 1), b2 + hstepB, voffB); PG8_STAGE(PG8_SA(0, 0), a2, voffA);
;             PG8_WAIT_V(8); PG8_WAIT_L(0); PG8_BAR; PG8_MMA(1, 0, At, B0); PG8_MMA(1, 1, At, B1); PG8_BAR; PG8_SCHED;
.LBB0_458:
	s_add_i32 s51, s38, 2
	s_add_u32 s20, s4, 0xfff80080
	s_addc_u32 s21, s5, -1
	s_add_i32 s22, 16, 0x10000
	s_cmp_eq_u32 s45, s38
	s_cselect_b32 s39, s17, s21
	s_cselect_b32 s38, s50, s20
	s_cselect_b32 s53, s25, s41
	s_cselect_b32 s52, s24, s40
	s_add_i32 s20, 16, 0x14000
	v_add_u32_e32 v154, s22, v139
	v_add_u32_e32 v170, s20, v139
	ds_read_b128 v[142:145], v154
	ds_read_b128 v[146:149], v154 offset:1024
	ds_read_b128 v[150:153], v154 offset:2048
	ds_read_b128 v[154:157], v154 offset:3072
	ds_read_b128 v[158:161], v170
	ds_read_b128 v[162:165], v170 offset:1024
	ds_read_b128 v[166:169], v170 offset:2048
	ds_read_b128 v[170:173], v170 offset:3072
	v_lshl_add_u64 v[174:175], s[4:5], 0, v[134:135]
	s_add_i32 m0, s29, 0xc000
	ds_read_b128 v[184:187], v141
	ds_read_b128 v[188:191], v141 offset:1024
	ds_read_b128 v[192:195], v141 offset:2048
	ds_read_b128 v[196:199], v141 offset:3072
	ds_read_b128 v[200:203], v141 offset:4096
	ds_read_b128 v[204:207], v141 offset:5120
	ds_read_b128 v[208:211], v141 offset:6144
	ds_read_b128 v[212:215], v141 offset:7168
	global_load_lds_dwordx4 v[174:175], off
	v_lshl_add_u64 v[174:175], s[4:5], 0, v[136:137]
	s_add_i32 m0, s29, 0xe000
	s_nop 0
	global_load_lds_dwordx4 v[174:175], off
	s_waitcnt vmcnt(8)
	s_waitcnt lgkmcnt(0)
	s_barrier
	s_waitcnt lgkmcnt(0)
	v_mfma_f32_16x16x32_bf16 v[120:123], v[142:145], v[184:187], v[120:123]
	v_mfma_f32_16x16x32_bf16 v[124:127], v[150:153], v[184:187], v[124:127]
	v_mfma_f32_16x16x32_bf16 v[108:111], v[142:145], v[192:195], v[108:111]
	v_mfma_f32_16x16x32_bf16 v[104:107], v[150:153], v[192:195], v[104:107]
	v_mfma_f32_16x16x32_bf16 v[92:95], v[142:145], v[200:203], v[92:95]
	v_mfma_f32_16x16x32_bf16 v[88:91], v[150:153], v[200:203], v[88:91]
	v_mfma_f32_16x16x32_bf16 v[76:79], v[142:145], v[208:211], v[76:79]
	v_mfma_f32_16x16x32_bf16 v[72:75], v[150:153], v[208:211], v[72:75]
	v_mfma_f32_16x16x32_bf16 v[120:123], v[146:149], v[188:191], v[120:123]
	v_mfma_f32_16x16x32_bf16 v[124:127], v[154:157], v[188:191], v[124:127]
	v_mfma_f32_16x16x32_bf16 v[108:111], v[146:149], v[196:199], v[108:111]
	v_mfma_f32_16x16x32_bf16 v[104:107], v[154:157], v[196:199], v[104:107]
	v_mfma_f32_16x16x32_bf16 v[92:95], v[146:149], v[204:207], v[92:95]
	v_mfma_f32_16x16x32_bf16 v[88:91], v[154:157], v[204:207], v[88:91]
	v_mfma_f32_16x16x32_bf16 v[76:79], v[146:149], v[212:215], v[76:79]
	v_mfma_f32_16x16x32_bf16 v[72:75], v[154:157], v[212:215], v[72:75]
	v_mfma_f32_16x16x32_bf16 v[116:119], v[158:161], v[184:187], v[116:119]
	v_mfma_f32_16x16x32_bf16 v[112:115], v[166:169], v[184:187], v[112:115]
	v_mfma_f32_16x16x32_bf16 v[100:103], v[158:161], v[192:195], v[100:103]
	v_mfma_f32_16x16x32_bf16 v[96:99], v[166:169], v[192:195], v[96:99]
	v_mfma_f32_16x16x32_bf16 v[84:87], v[158:161], v[200:203], v[84:87]
	v_mfma_f32_16x16x32_bf16 v[80:83], v[166:169], v[200:203], v[80:83]
	v_mfma_f32_16x16x32_bf16 v[68:71], v[158:161], v[208:211], v[68:71]
	v_mfma_f32_16x16x32_bf16 v[64:67], v[166:169], v[208:211], v[64:67]
	v_mfma_f32_16x16x32_bf16 v[116:119], v[162:165], v[188:191], v[116:119]
	v_mfma_f32_16x16x32_bf16 v[112:115], v[170:173], v[188:191], v[112:115]
	v_mfma_f32_16x16x32_bf16 v[100:103], v[162:165], v[196:199], v[100:103]
	v_mfma_f32_16x16x32_bf16 v[96:99], v[170:173], v[196:199], v[96:99]
	v_mfma_f32_16x16x32_bf16 v[84:87], v[162:165], v[204:207], v[84:87]
	v_mfma_f32_16x16x32_bf16 v[80:83], v[170:173], v[204:207], v[80:83]
	v_mfma_f32_16x16x32_bf16 v[68:71], v[162:165], v[212:215], v[68:71]
	v_mfma_f32_16x16x32_bf16 v[64:67], v[170:173], v[212:215], v[64:67]
	s_barrier
	s_add_i32 s21, s22, s18
	v_lshl_add_u64 v[174:175], s[52:53], 0, v[176:177]
	s_mov_b32 m0, s21
	ds_read_b128 v[184:187], v141 offset:16384
	ds_read_b128 v[188:191], v141 offset:17408
	ds_read_b128 v[192:195], v141 offset:18432
	ds_read_b128 v[196:199], v141 offset:19456
	ds_read_b128 v[200:203], v141 offset:20480
	ds_read_b128 v[204:207], v141 offset:21504
	ds_read_b128 v[208:211], v141 offset:22528
	ds_read_b128 v[212:215], v141 offset:23552
	global_load_lds_dwordx4 v[174:175], off
	s_add_i32 m0, s21, 0x2000
	v_lshl_add_u64 v[216:217], s[52:53], 0, v[128:129]
	s_add_u32 s52, s52, s6
	s_addc_u32 s53, s53, s7
	s_add_i32 s20, s20, s18
	global_load_lds_dwordx4 v[216:217], off
	v_lshl_add_u64 v[218:219], s[52:53], 0, v[176:177]
	s_mov_b32 m0, s20
	v_lshl_add_u64 v[220:221], s[52:53], 0, v[128:129]
	global_load_lds_dwordx4 v[218:219], off
	s_add_i32 m0, s20, 0x2000
	v_lshl_add_u64 v[222:223], s[38:39], 0, v[132:133]
	global_load_lds_dwordx4 v[220:221], off
	s_mov_b32 m0, s29
	v_lshl_add_u64 v[224:225], s[38:39], 0, v[130:131]
	global_load_lds_dwordx4 v[222:223], off
	s_mov_b32 m0, s30
	s_nop 0
	global_load_lds_dwordx4 v[224:225], off
	s_waitcnt vmcnt(8)
	s_waitcnt lgkmcnt(0)
	s_barrier
; #define PG8_STAGE(bufoff, gbase, voff) do { _Pragma("unroll") for (int _i = 0; _i < 2; ++_i) \
;         __builtin_amdgcn_global_load_lds((const unsigned*)((const char*)(gbase) + (voff)[_i]), (LAS unsigned*)(lds + (bufoff) + ldsw + _i * 8192), 16, 0, 0); } while (0)
; #define PG8_LDA(dst, b, h) do { _Pragma("unroll") for (int m = 0; m < 4; ++m) _Pragma("unroll") for (int k = 0; k < 2; ++k) dst[m][k] = *(const LAS bf16x8*)(lds + PG8_SA(b, h) + aoff + m * 2048 + k * 1024); } while (0)
; #define PG8_LDB(dst, b, h) do { _Pragma("unroll") for (int n = 0; n < 2; ++n) _Pragma("unroll") for (int k = 0; k < 2; ++k) dst[n][k] = *(const LAS bf16x8*)(lds + PG8_SB(b, h) + boff + n * 2048 + k * 1024); } while (0)
; #define PG8_MMA(ai, bj, At, Bt) do { __builtin_amdgcn_s_setprio(1); _Pragma("unroll") for (int m = 0; m < 4; ++m) _Pragma("unroll") for (int n = 0; n < 2; ++n) _Pragma("unroll") for (int k = 0; k < 2; ++k) \
;         acc[ai][bj][m][n] = __builtin_amdgcn_mfma_f32_16x16x32_bf16(Bt[n][k], At[m][k], acc[ai][bj][m][n], 0, 0, 0); __builtin_amdgcn_s_setprio(0); } while (0)
; #define PG8_WAIT_V(n) asm volatile("s_waitcnt vmcnt(" #n ")" ::: "memory")
; #define PG8_WAIT_L(n) asm volatile("s_waitcnt lgkmcnt(" #n ")" ::: "memory")
; #define PG8_BAR __builtin_amdgcn_s_barrier()
; #define PG8_SCHED __builtin_amdgcn_sched_barrier(0)
; template <class Epi, bool ALIGN_EPI = PG8_ALIGN>
; __device__ __forceinline__ void gemm_phase(LAS unsigned char* lds, const Gemm g, const StaticOrder& S, const Epi& E) {
;     ...
;             PG8_WAIT_V(8); PG8_WAIT_L(0); PG8_BAR; PG8_MMA(1, 0, At, B0); PG8_MMA(1, 1, At, B1); PG8_BAR; PG8_SCHED;
;             PG8_LDB(B0, 1, 0); PG8_LDB(B1, 1, 1); PG8_SCHED; PG8_LDA(At, 1, 0); PG8_STAGE(PG8_SA(0, 1), a2 + hstepA, voffA);
;             PG8_WAIT_V(8); PG8_WAIT_L(0); PG8_BAR; PG8_MMA(0, 0, At, B0); PG8_MMA(0, 1, At, B1); PG8_BAR; PG8_SCHED;
	s_waitcnt lgkmcnt(0)
	v_mfma_f32_16x16x32_bf16 v[60:63], v[142:145], v[184:187], v[60:63]
	v_mfma_f32_16x16x32_bf16 v[56:59], v[150:153], v[184:187], v[56:59]
	v_mfma_f32_16x16x32_bf16 v[44:47], v[142:145], v[192:195], v[44:47]
	v_mfma_f32_16x16x32_bf16 v[40:43], v[150:153], v[192:195], v[40:43]
	v_mfma_f32_16x16x32_bf16 v[28:31], v[142:145], v[200:203], v[28:31]
	v_mfma_f32_16x16x32_bf16 v[24:27], v[150:153], v[200:203], v[24:27]
	v_mfma_f32_16x16x32_bf16 v[12:15], v[142:145], v[208:211], v[12:15]
	v_mfma_f32_16x16x32_bf16 v[8:11], v[150:153], v[208:211], v[8:11]
	v_mfma_f32_16x16x32_bf16 v[60:63], v[146:149], v[188:191], v[60:63]
	v_mfma_f32_16x16x32_bf16 v[56:59], v[154:157], v[188:191], v[56:59]
	v_mfma_f32_16x16x32_bf16 v[44:47], v[146:149], v[196:199], v[44:47]
	v_mfma_f32_16x16x32_bf16 v[40:43], v[154:157], v[196:199], v[40:43]
	v_mfma_f32_16x16x32_bf16 v[28:31], v[146:149], v[204:207], v[28:31]
	v_mfma_f32_16x16x32_bf16 v[24:27], v[154:157], v[204:207], v[24:27]
	v_mfma_f32_16x16x32_bf16 v[12:15], v[146:149], v[212:215], v[12:15]
	v_mfma_f32_16x16x32_bf16 v[8:11], v[154:157], v[212:215], v[8:11]
	v_mfma_f32_16x16x32_bf16 v[52:55], v[158:161], v[184:187], v[52:55]
	v_mfma_f32_16x16x32_bf16 v[48:51], v[166:169], v[184:187], v[48:51]
	v_mfma_f32_16x16x32_bf16 v[36:39], v[158:161], v[192:195], v[36:39]
	v_mfma_f32_16x16x32_bf16 v[32:35], v[166:169], v[192:195], v[32:35]
	v_mfma_f32_16x16x32_bf16 v[20:23], v[158:161], v[200:203], v[20:23]
	v_mfma_f32_16x16x32_bf16 v[16:19], v[166:169], v[200:203], v[16:19]
	v_mfma_f32_16x16x32_bf16 v[4:7], v[158:161], v[208:211], v[4:7]
	v_mfma_f32_16x16x32_bf16 v[0:3], v[166:169], v[208:211], v[0:3]
	v_mfma_f32_16x16x32_bf16 v[52:55], v[162:165], v[188:191], v[52:55]
	v_mfma_f32_16x16x32_bf16 v[48:51], v[170:173], v[188:191], v[48:51]
	v_mfma_f32_16x16x32_bf16 v[36:39], v[162:165], v[196:199], v[36:39]
	v_mfma_f32_16x16x32_bf16 v[32:35], v[170:173], v[196:199], v[32:35]
	v_mfma_f32_16x16x32_bf16 v[20:23], v[162:165], v[204:207], v[20:23]
	v_mfma_f32_16x16x32_bf16 v[16:19], v[170:173], v[204:207], v[16:19]
	v_mfma_f32_16x16x32_bf16 v[4:7], v[162:165], v[212:215], v[4:7]
	v_mfma_f32_16x16x32_bf16 v[0:3], v[170:173], v[212:215], v[0:3]
	s_barrier
	s_add_i32 s20, 16, 0x18000
	s_add_i32 s21, 16, 0x1c000
	v_add_u32_e32 v154, s20, v139
	v_add_u32_e32 v170, s21, v139
	ds_read_b128 v[142:145], v154
	ds_read_b128 v[146:149], v154 offset:1024
	ds_read_b128 v[150:153], v154 offset:2048
	ds_read_b128 v[154:157], v154 offset:3072
	ds_read_b128 v[158:161], v170
	ds_read_b128 v[162:165], v170 offset:1024
	ds_read_b128 v[166:169], v170 offset:2048
	ds_read_b128 v[170:173], v170 offset:3072
	s_add_u32 s38, s38, 0x80000
	s_addc_u32 s39, s39, 0
	s_mov_b32 m0, s31
	v_lshl_add_u64 v[226:227], s[38:39], 0, v[132:133]
	ds_read_b128 v[184:187], v141 offset:32768
	ds_read_b128 v[188:191], v141 offset:33792
	ds_read_b128 v[192:195], v141 offset:34816
	ds_read_b128 v[196:199], v141 offset:35840
	ds_read_b128 v[200:203], v141 offset:36864
	ds_read_b128 v[204:207], v141 offset:37888
	ds_read_b128 v[208:211], v141 offset:38912
	ds_read_b128 v[212:215], v141 offset:39936
	global_load_lds_dwordx4 v[226:227], off
	v_lshl_add_u64 v[226:227], s[38:39], 0, v[130:131]
	s_mov_b32 m0, s42
	s_nop 0
	global_load_lds_dwordx4 v[226:227], off
	s_waitcnt vmcnt(8)
	s_waitcnt lgkmcnt(0)
	s_barrier
	s_waitcnt lgkmcnt(0)
	v_mfma_f32_16x16x32_bf16 v[120:123], v[142:145], v[184:187], v[120:123]
	v_mfma_f32_16x16x32_bf16 v[124:127], v[150:153], v[184:187], v[124:127]
	v_mfma_f32_16x16x32_bf16 v[108:111], v[142:145], v[192:195], v[108:111]
	v_mfma_f32_16x16x32_bf16 v[104:107], v[150:153], v[192:195], v[104:107]
	v_mfma_f32_16x16x32_bf16 v[92:95], v[142:145], v[200:203], v[92:95]
	v_mfma_f32_16x16x32_bf16 v[88:91], v[150:153], v[200:203], v[88:91]
	v_mfma_f32_16x16x32_bf16 v[76:79], v[142:145], v[208:211], v[76:79]
	v_mfma_f32_16x16x32_bf16 v[72:75], v[150:153], v[208:211], v[72:75]
	v_mfma_f32_16x16x32_bf16 v[120:123], v[146:149], v[188:191], v[120:123]
	v_mfma_f32_16x16x32_bf16 v[124:127], v[154:157], v[188:191], v[124:127]
	v_mfma_f32_16x16x32_bf16 v[108:111], v[146:149], v[196:199], v[108:111]
	v_mfma_f32_16x16x32_bf16 v[104:107], v[154:157], v[196:199], v[104:107]
	v_mfma_f32_16x16x32_bf16 v[92:95], v[146:149], v[204:207], v[92:95]
	v_mfma_f32_16x16x32_bf16 v[88:91], v[154:157], v[204:207], v[88:91]
	v_mfma_f32_16x16x32_bf16 v[76:79], v[146:149], v[212:215], v[76:79]
	v_mfma_f32_16x16x32_bf16 v[72:75], v[154:157], v[212:215], v[72:75]
	v_mfma_f32_16x16x32_bf16 v[116:119], v[158:161], v[184:187], v[116:119]
	v_mfma_f32_16x16x32_bf16 v[112:115], v[166:169], v[184:187], v[112:115]
	v_mfma_f32_16x16x32_bf16 v[100:103], v[158:161], v[192:195], v[100:103]
	v_mfma_f32_16x16x32_bf16 v[96:99], v[166:169], v[192:195], v[96:99]
	v_mfma_f32_16x16x32_bf16 v[84:87], v[158:161], v[200:203], v[84:87]
	v_mfma_f32_16x16x32_bf16 v[80:83], v[166:169], v[200:203], v[80:83]
	v_mfma_f32_16x16x32_bf16 v[68:71], v[158:161], v[208:211], v[68:71]
	v_mfma_f32_16x16x32_bf16 v[64:67], v[166:169], v[208:211], v[64:67]
	v_mfma_f32_16x16x32_bf16 v[116:119], v[162:165], v[188:191], v[116:119]
	v_mfma_f32_16x16x32_bf16 v[112:115], v[170:173], v[188:191], v[112:115]
	v_mfma_f32_16x16x32_bf16 v[100:103], v[162:165], v[196:199], v[100:103]
	v_mfma_f32_16x16x32_bf16 v[96:99], v[170:173], v[196:199], v[96:99]
	v_mfma_f32_16x16x32_bf16 v[84:87], v[162:165], v[204:207], v[84:87]
	v_mfma_f32_16x16x32_bf16 v[80:83], v[170:173], v[204:207], v[80:83]
	v_mfma_f32_16x16x32_bf16 v[68:71], v[162:165], v[212:215], v[68:71]
	v_mfma_f32_16x16x32_bf16 v[64:67], v[170:173], v[212:215], v[64:67]
	s_barrier
; #define PG8_STAGE(bufoff, gbase, voff) do { _Pragma("unroll") for (int _i = 0; _i < 2; ++_i) \
;         __builtin_amdgcn_global_load_lds((const unsigned*)((const char*)(gbase) + (voff)[_i]), (LAS unsigned*)(lds + (bufoff) + ldsw + _i * 8192), 16, 0, 0); } while (0)
; #define PG8_LDA(dst, b, h) do { _Pragma("unroll") for (int m = 0; m < 4; ++m) _Pragma("unroll") for (int k = 0; k < 2; ++k) dst[m][k] = *(const LAS bf16x8*)(lds + PG8_SA(b, h) + aoff + m * 2048 + k * 1024); } while (0)
; #define PG8_MMA(ai, bj, At, Bt) do { __builtin_amdgcn_s_setprio(1); _Pragma("unroll") for (int m = 0; m < 4; ++m) _Pragma("unroll") for (int n = 0; n < 2; ++n) _Pragma("unroll") for (int k = 0; k < 2; ++k) \
;         acc[ai][bj][m][n] = __builtin_amdgcn_mfma_f32_16x16x32_bf16(Bt[n][k], At[m][k], acc[ai][bj][m][n], 0, 0, 0); __builtin_amdgcn_s_setprio(0); } while (0)
; #define PG8_WAIT_V(n) asm volatile("s_waitcnt vmcnt(" #n ")" ::: "memory")
; #define PG8_WAIT_L(n) asm volatile("s_waitcnt lgkmcnt(" #n ")" ::: "memory")
; #define PG8_BAR __builtin_amdgcn_s_barrier()
; #define PG8_SCHED __builtin_amdgcn_sched_barrier(0)
; template <class Epi, bool ALIGN_EPI = PG8_ALIGN>
; __device__ __forceinline__ void gemm_phase(LAS unsigned char* lds, const Gemm g, const StaticOrder& S, const Epi& E) {
;     ...
;             PG8_LDA(At, 1, 1); PG8_STAGE(PG8_SB(1, 0), b3, voffB); PG8_STAGE(PG8_SB(1, 1), b3 + hstepB, voffB); PG8_STAGE(PG8_SA(1, 0), a3, voffA);
;             PG8_WAIT_V(8); PG8_WAIT_L(0); PG8_BAR; PG8_MMA(1, 0, At, B0); PG8_MMA(1, 1, At, B1); PG8_BAR; PG8_SCHED;
;         }
	s_add_i32 s20, s20, s18
	v_lshl_add_u64 v[174:175], v[174:175], 0, s[0:1]
	s_mov_b32 m0, s20
	ds_read_b128 v[184:187], v141 offset:49152
	ds_read_b128 v[188:191], v141 offset:50176
	ds_read_b128 v[192:195], v141 offset:51200
	ds_read_b128 v[196:199], v141 offset:52224
	ds_read_b128 v[200:203], v141 offset:53248
	ds_read_b128 v[204:207], v141 offset:54272
	ds_read_b128 v[208:211], v141 offset:55296
	ds_read_b128 v[212:215], v141 offset:56320
	global_load_lds_dwordx4 v[174:175], off
	v_lshl_add_u64 v[174:175], v[216:217], 0, s[0:1]
	s_add_i32 m0, s20, 0x2000
	s_add_i32 s20, s21, s18
	global_load_lds_dwordx4 v[174:175], off
	v_lshl_add_u64 v[174:175], v[218:219], 0, s[0:1]
	s_mov_b32 m0, s20
	s_nop 0
	global_load_lds_dwordx4 v[174:175], off
	v_lshl_add_u64 v[174:175], v[220:221], 0, s[0:1]
	s_add_i32 m0, s20, 0x2000
	s_nop 0
	global_load_lds_dwordx4 v[174:175], off
	v_lshl_add_u64 v[174:175], v[222:223], 0, s[0:1]
	s_mov_b32 m0, s34
	s_nop 0
	global_load_lds_dwordx4 v[174:175], off
	v_lshl_add_u64 v[174:175], v[224:225], 0, s[0:1]
	s_mov_b32 m0, s43
	s_nop 0
	global_load_lds_dwordx4 v[174:175], off
	s_waitcnt vmcnt(8)
	s_waitcnt lgkmcnt(0)
	s_barrier
	s_waitcnt lgkmcnt(0)
	v_mfma_f32_16x16x32_bf16 v[60:63], v[142:145], v[184:187], v[60:63]
	v_mfma_f32_16x16x32_bf16 v[56:59], v[150:153], v[184:187], v[56:59]
	v_mfma_f32_16x16x32_bf16 v[44:47], v[142:145], v[192:195], v[44:47]
	v_mfma_f32_16x16x32_bf16 v[40:43], v[150:153], v[192:195], v[40:43]
	v_mfma_f32_16x16x32_bf16 v[28:31], v[142:145], v[200:203], v[28:31]
	v_mfma_f32_16x16x32_bf16 v[24:27], v[150:153], v[200:203], v[24:27]
	v_mfma_f32_16x16x32_bf16 v[12:15], v[142:145], v[208:211], v[12:15]
	v_mfma_f32_16x16x32_bf16 v[8:11], v[150:153], v[208:211], v[8:11]
	v_mfma_f32_16x16x32_bf16 v[60:63], v[146:149], v[188:191], v[60:63]
	v_mfma_f32_16x16x32_bf16 v[56:59], v[154:157], v[188:191], v[56:59]
	v_mfma_f32_16x16x32_bf16 v[44:47], v[146:149], v[196:199], v[44:47]
	v_mfma_f32_16x16x32_bf16 v[40:43], v[154:157], v[196:199], v[40:43]
	v_mfma_f32_16x16x32_bf16 v[28:31], v[146:149], v[204:207], v[28:31]
	v_mfma_f32_16x16x32_bf16 v[24:27], v[154:157], v[204:207], v[24:27]
	v_mfma_f32_16x16x32_bf16 v[12:15], v[146:149], v[212:215], v[12:15]
	v_mfma_f32_16x16x32_bf16 v[8:11], v[154:157], v[212:215], v[8:11]
	v_mfma_f32_16x16x32_bf16 v[52:55], v[158:161], v[184:187], v[52:55]
	v_mfma_f32_16x16x32_bf16 v[48:51], v[166:169], v[184:187], v[48:51]
	v_mfma_f32_16x16x32_bf16 v[36:39], v[158:161], v[192:195], v[36:39]
	v_mfma_f32_16x16x32_bf16 v[32:35], v[166:169], v[192:195], v[32:35]
	v_mfma_f32_16x16x32_bf16 v[20:23], v[158:161], v[200:203], v[20:23]
	v_mfma_f32_16x16x32_bf16 v[16:19], v[166:169], v[200:203], v[16:19]
	v_mfma_f32_16x16x32_bf16 v[4:7], v[158:161], v[208:211], v[4:7]
	v_mfma_f32_16x16x32_bf16 v[0:3], v[166:169], v[208:211], v[0:3]
	v_mfma_f32_16x16x32_bf16 v[52:55], v[162:165], v[188:191], v[52:55]
	v_mfma_f32_16x16x32_bf16 v[48:51], v[170:173], v[188:191], v[48:51]
	v_mfma_f32_16x16x32_bf16 v[36:39], v[162:165], v[196:199], v[36:39]
	v_mfma_f32_16x16x32_bf16 v[32:35], v[170:173], v[196:199], v[32:35]
	v_mfma_f32_16x16x32_bf16 v[20:23], v[162:165], v[204:207], v[20:23]
	v_mfma_f32_16x16x32_bf16 v[16:19], v[170:173], v[204:207], v[16:19]
	v_mfma_f32_16x16x32_bf16 v[4:7], v[162:165], v[212:215], v[4:7]
	v_mfma_f32_16x16x32_bf16 v[0:3], v[170:173], v[212:215], v[0:3]
	s_barrier
	s_add_u32 s4, s4, 0x100
	s_addc_u32 s5, s5, 0
	s_add_u32 s40, s40, 0x100
	s_addc_u32 s41, s41, 0
	s_cmp_ge_i32 s51, s44
	s_mov_b32 s38, s51
	s_cbranch_scc0 .LBB0_458

; #define PG8_STAGE(bufoff, gbase, voff) do { _Pragma("unroll") for (int _i = 0; _i < 2; ++_i) \
;         __builtin_amdgcn_global_load_lds((const unsigned*)((const char*)(gbase) + (voff)[_i]), (LAS unsigned*)(lds + (bufoff) + ldsw + _i * 8192), 16, 0, 0); } while (0)
; #define PG8_LDA(dst, b, h) do { _Pragma("unroll") for (int m = 0; m < 4; ++m) _Pragma("unroll") for (int k = 0; k < 2; ++k) dst[m][k] = *(const LAS bf16x8*)(lds + PG8_SA(b, h) + aoff + m * 2048 + k * 1024); } while (0)
; #define PG8_LDB(dst, b, h) do { _Pragma("unroll") for (int n = 0; n < 2; ++n) _Pragma("unroll") for (int k = 0; k < 2; ++k) dst[n][k] = *(const LAS bf16x8*)(lds + PG8_SB(b, h) + boff + n * 2048 + k * 1024); } while (0)
; #define PG8_MMA(ai, bj, At, Bt) do { __builtin_amdgcn_s_setprio(1); _Pragma("unroll") for (int m = 0; m < 4; ++m) _Pragma("unroll") for (int n = 0; n < 2; ++n) _Pragma("unroll") for (int k = 0; k < 2; ++k) \
;         acc[ai][bj][m][n] = __builtin_amdgcn_mfma_f32_16x16x32_bf16(Bt[n][k], At[m][k], acc[ai][bj][m][n], 0, 0, 0); __builtin_amdgcn_s_setprio(0); } while (0)
; #define PG8_WAIT_V(n) asm volatile("s_waitcnt vmcnt(" #n ")" ::: "memory")
; #define PG8_WAIT_L(n) asm volatile("s_waitcnt lgkmcnt(" #n ")" ::: "memory")
; #define PG8_BAR __builtin_amdgcn_s_barrier()
; #define PG8_SCHED __builtin_amdgcn_sched_barrier(0)
; template <class Epi, bool ALIGN_EPI = PG8_ALIGN>
; __device__ __forceinline__ void gemm_phase(LAS unsigned char* lds, const Gemm g, const StaticOrder& S, const Epi& E) {
;     ...
;         for (int t = 0; t < nt; t += 2) {
;             const bool last = (t == nt - 2);
;             const char* a1 = cA + (size_t)(t + 1) * kstep;
;             const char* a2 = last ? nA : cA + (size_t)(t + 2) * kstep; const char* b2 = last ? nB : cB + (size_t)(t + 2) * kstep;
;             const char* a3 = a2 + kstep; const char* b3 = b2 + kstep;
;             PG8_LDB(B0, 0, 0); PG8_LDB(B1, 0, 1); PG8_SCHED; PG8_LDA(At, 0, 0); PG8_STAGE(PG8_SA(1, 1), a1 + hstepA, voffA);
;             PG8_WAIT_V(8); PG8_WAIT_L(0); PG8_BAR; PG8_MMA(0, 0, At, B0); PG8_MMA(0, 1, At, B1); PG8_BAR; PG8_SCHED;
;             PG8_LDA(At, 0, 1); PG8_STAGE(PG8_SB(0, 0), b2, voffB); PG8_STAGE(PG8_SB(0, 1), b2 + hstepB, voffB); PG8_STAGE(PG8_SA(0, 0), a2, voffA);
;             PG8_WAIT_V(8); PG8_WAIT_L(0); PG8_BAR; PG8_MMA(1, 0, At, B0); PG8_MMA(1, 1, At, B1); PG8_BAR; PG8_SCHED;
.LBB0_481:
	s_add_i32 s53, s38, 2
	s_add_u32 s20, s4, 0xffff0080
	s_addc_u32 s21, s5, -1
	s_add_i32 s22, 16, 0x10000
	s_cmp_eq_u32 s47, s38
	s_cselect_b32 s39, s17, s21
	s_cselect_b32 s38, s52, s20
	s_cselect_b32 s55, s25, s41
	s_cselect_b32 s54, s24, s40
	s_add_i32 s20, 16, 0x14000
	v_add_u32_e32 v154, s22, v139
	v_add_u32_e32 v170, s20, v139
	ds_read_b128 v[142:145], v154
	ds_read_b128 v[146:149], v154 offset:1024
	ds_read_b128 v[150:153], v154 offset:2048
	ds_read_b128 v[154:157], v154 offset:3072
	ds_read_b128 v[158:161], v170
	ds_read_b128 v[162:165], v170 offset:1024
	ds_read_b128 v[166:169], v170 offset:2048
	ds_read_b128 v[170:173], v170 offset:3072
	v_lshl_add_u64 v[174:175], s[4:5], 0, v[134:135]
	s_add_i32 m0, s26, 0xc000
	ds_read_b128 v[184:187], v141
	ds_read_b128 v[188:191], v141 offset:1024
	ds_read_b128 v[192:195], v141 offset:2048
	ds_read_b128 v[196:199], v141 offset:3072
	ds_read_b128 v[200:203], v141 offset:4096
	ds_read_b128 v[204:207], v141 offset:5120
	ds_read_b128 v[208:211], v141 offset:6144
	ds_read_b128 v[212:215], v141 offset:7168
	global_load_lds_dwordx4 v[174:175], off
	v_lshl_add_u64 v[174:175], s[4:5], 0, v[136:137]
	s_add_i32 m0, s26, 0xe000
	s_nop 0
	global_load_lds_dwordx4 v[174:175], off
	s_waitcnt vmcnt(8)
	s_waitcnt lgkmcnt(0)
	s_barrier
	s_waitcnt lgkmcnt(0)
	v_mfma_f32_16x16x32_bf16 v[120:123], v[142:145], v[184:187], v[120:123]
	v_mfma_f32_16x16x32_bf16 v[124:127], v[150:153], v[184:187], v[124:127]
	v_mfma_f32_16x16x32_bf16 v[108:111], v[142:145], v[192:195], v[108:111]
	v_mfma_f32_16x16x32_bf16 v[104:107], v[150:153], v[192:195], v[104:107]
	v_mfma_f32_16x16x32_bf16 v[92:95], v[142:145], v[200:203], v[92:95]
	v_mfma_f32_16x16x32_bf16 v[88:91], v[150:153], v[200:203], v[88:91]
	v_mfma_f32_16x16x32_bf16 v[76:79], v[142:145], v[208:211], v[76:79]
	v_mfma_f32_16x16x32_bf16 v[72:75], v[150:153], v[208:211], v[72:75]
	v_mfma_f32_16x16x32_bf16 v[120:123], v[146:149], v[188:191], v[120:123]
	v_mfma_f32_16x16x32_bf16 v[124:127], v[154:157], v[188:191], v[124:127]
	v_mfma_f32_16x16x32_bf16 v[108:111], v[146:149], v[196:199], v[108:111]
	v_mfma_f32_16x16x32_bf16 v[104:107], v[154:157], v[196:199], v[104:107]
	v_mfma_f32_16x16x32_bf16 v[92:95], v[146:149], v[204:207], v[92:95]
	v_mfma_f32_16x16x32_bf16 v[88:91], v[154:157], v[204:207], v[88:91]
	v_mfma_f32_16x16x32_bf16 v[76:79], v[146:149], v[212:215], v[76:79]
	v_mfma_f32_16x16x32_bf16 v[72:75], v[154:157], v[212:215], v[72:75]
	v_mfma_f32_16x16x32_bf16 v[116:119], v[158:161], v[184:187], v[116:119]
	v_mfma_f32_16x16x32_bf16 v[112:115], v[166:169], v[184:187], v[112:115]
	v_mfma_f32_16x16x32_bf16 v[100:103], v[158:161], v[192:195], v[100:103]
	v_mfma_f32_16x16x32_bf16 v[96:99], v[166:169], v[192:195], v[96:99]
	v_mfma_f32_16x16x32_bf16 v[84:87], v[158:161], v[200:203], v[84:87]
	v_mfma_f32_16x16x32_bf16 v[80:83], v[166:169], v[200:203], v[80:83]
	v_mfma_f32_16x16x32_bf16 v[68:71], v[158:161], v[208:211], v[68:71]
	v_mfma_f32_16x16x32_bf16 v[64:67], v[166:169], v[208:211], v[64:67]
	v_mfma_f32_16x16x32_bf16 v[116:119], v[162:165], v[188:191], v[116:119]
	v_mfma_f32_16x16x32_bf16 v[112:115], v[170:173], v[188:191], v[112:115]
	v_mfma_f32_16x16x32_bf16 v[100:103], v[162:165], v[196:199], v[100:103]
	v_mfma_f32_16x16x32_bf16 v[96:99], v[170:173], v[196:199], v[96:99]
	v_mfma_f32_16x16x32_bf16 v[84:87], v[162:165], v[204:207], v[84:87]
	v_mfma_f32_16x16x32_bf16 v[80:83], v[170:173], v[204:207], v[80:83]
	v_mfma_f32_16x16x32_bf16 v[68:71], v[162:165], v[212:215], v[68:71]
	v_mfma_f32_16x16x32_bf16 v[64:67], v[170:173], v[212:215], v[64:67]
	s_barrier
	s_add_i32 s21, s22, s42
	v_lshl_add_u64 v[174:175], s[54:55], 0, v[176:177]
	s_mov_b32 m0, s21
	ds_read_b128 v[184:187], v141 offset:16384
	ds_read_b128 v[188:191], v141 offset:17408
	ds_read_b128 v[192:195], v141 offset:18432
	ds_read_b128 v[196:199], v141 offset:19456
	ds_read_b128 v[200:203], v141 offset:20480
	ds_read_b128 v[204:207], v141 offset:21504
	ds_read_b128 v[208:211], v141 offset:22528
	ds_read_b128 v[212:215], v141 offset:23552
	global_load_lds_dwordx4 v[174:175], off
	s_add_i32 m0, s21, 0x2000
	v_lshl_add_u64 v[216:217], s[54:55], 0, v[128:129]
	s_add_u32 s54, s54, s6
	s_addc_u32 s55, s55, s7
	s_add_i32 s20, s20, s42
	global_load_lds_dwordx4 v[216:217], off
	v_lshl_add_u64 v[218:219], s[54:55], 0, v[176:177]
	s_mov_b32 m0, s20
	v_lshl_add_u64 v[220:221], s[54:55], 0, v[128:129]
	global_load_lds_dwordx4 v[218:219], off
	s_add_i32 m0, s20, 0x2000
	v_lshl_add_u64 v[222:223], s[38:39], 0, v[132:133]
	global_load_lds_dwordx4 v[220:221], off
	s_mov_b32 m0, s26
	v_lshl_add_u64 v[224:225], s[38:39], 0, v[130:131]
	global_load_lds_dwordx4 v[222:223], off
	s_mov_b32 m0, s27
	s_nop 0
	global_load_lds_dwordx4 v[224:225], off
	s_waitcnt vmcnt(8)
	s_waitcnt lgkmcnt(0)
	s_barrier
; #define PG8_STAGE(bufoff, gbase, voff) do { _Pragma("unroll") for (int _i = 0; _i < 2; ++_i) \
;         __builtin_amdgcn_global_load_lds((const unsigned*)((const char*)(gbase) + (voff)[_i]), (LAS unsigned*)(lds + (bufoff) + ldsw + _i * 8192), 16, 0, 0); } while (0)
; #define PG8_LDA(dst, b, h) do { _Pragma("unroll") for (int m = 0; m < 4; ++m) _Pragma("unroll") for (int k = 0; k < 2; ++k) dst[m][k] = *(const LAS bf16x8*)(lds + PG8_SA(b, h) + aoff + m * 2048 + k * 1024); } while (0)
; #define PG8_LDB(dst, b, h) do { _Pragma("unroll") for (int n = 0; n < 2; ++n) _Pragma("unroll") for (int k = 0; k < 2; ++k) dst[n][k] = *(const LAS bf16x8*)(lds + PG8_SB(b, h) + boff + n * 2048 + k * 1024); } while (0)
; #define PG8_MMA(ai, bj, At, Bt) do { __builtin_amdgcn_s_setprio(1); _Pragma("unroll") for (int m = 0; m < 4; ++m) _Pragma("unroll") for (int n = 0; n < 2; ++n) _Pragma("unroll") for (int k = 0; k < 2; ++k) \
;         acc[ai][bj][m][n] = __builtin_amdgcn_mfma_f32_16x16x32_bf16(Bt[n][k], At[m][k], acc[ai][bj][m][n], 0, 0, 0); __builtin_amdgcn_s_setprio(0); } while (0)
; #define PG8_WAIT_V(n) asm volatile("s_waitcnt vmcnt(" #n ")" ::: "memory")
; #define PG8_WAIT_L(n) asm volatile("s_waitcnt lgkmcnt(" #n ")" ::: "memory")
; #define PG8_BAR __builtin_amdgcn_s_barrier()
; #define PG8_SCHED __builtin_amdgcn_sched_barrier(0)
; template <class Epi, bool ALIGN_EPI = PG8_ALIGN>
; __device__ __forceinline__ void gemm_phase(LAS unsigned char* lds, const Gemm g, const StaticOrder& S, const Epi& E) {
;     ...
;             PG8_WAIT_V(8); PG8_WAIT_L(0); PG8_BAR; PG8_MMA(1, 0, At, B0); PG8_MMA(1, 1, At, B1); PG8_BAR; PG8_SCHED;
;             PG8_LDB(B0, 1, 0); PG8_LDB(B1, 1, 1); PG8_SCHED; PG8_LDA(At, 1, 0); PG8_STAGE(PG8_SA(0, 1), a2 + hstepA, voffA);
;             PG8_WAIT_V(8); PG8_WAIT_L(0); PG8_BAR; PG8_MMA(0, 0, At, B0); PG8_MMA(0, 1, At, B1); PG8_BAR; PG8_SCHED;
	s_waitcnt lgkmcnt(0)
	v_mfma_f32_16x16x32_bf16 v[60:63], v[142:145], v[184:187], v[60:63]
	v_mfma_f32_16x16x32_bf16 v[56:59], v[150:153], v[184:187], v[56:59]
	v_mfma_f32_16x16x32_bf16 v[44:47], v[142:145], v[192:195], v[44:47]
	v_mfma_f32_16x16x32_bf16 v[40:43], v[150:153], v[192:195], v[40:43]
	v_mfma_f32_16x16x32_bf16 v[28:31], v[142:145], v[200:203], v[28:31]
	v_mfma_f32_16x16x32_bf16 v[24:27], v[150:153], v[200:203], v[24:27]
	v_mfma_f32_16x16x32_bf16 v[12:15], v[142:145], v[208:211], v[12:15]
	v_mfma_f32_16x16x32_bf16 v[8:11], v[150:153], v[208:211], v[8:11]
	v_mfma_f32_16x16x32_bf16 v[60:63], v[146:149], v[188:191], v[60:63]
	v_mfma_f32_16x16x32_bf16 v[56:59], v[154:157], v[188:191], v[56:59]
	v_mfma_f32_16x16x32_bf16 v[44:47], v[146:149], v[196:199], v[44:47]
	v_mfma_f32_16x16x32_bf16 v[40:43], v[154:157], v[196:199], v[40:43]
	v_mfma_f32_16x16x32_bf16 v[28:31], v[146:149], v[204:207], v[28:31]
	v_mfma_f32_16x16x32_bf16 v[24:27], v[154:157], v[204:207], v[24:27]
	v_mfma_f32_16x16x32_bf16 v[12:15], v[146:149], v[212:215], v[12:15]
	v_mfma_f32_16x16x32_bf16 v[8:11], v[154:157], v[212:215], v[8:11]
	v_mfma_f32_16x16x32_bf16 v[52:55], v[158:161], v[184:187], v[52:55]
	v_mfma_f32_16x16x32_bf16 v[48:51], v[166:169], v[184:187], v[48:51]
	v_mfma_f32_16x16x32_bf16 v[36:39], v[158:161], v[192:195], v[36:39]
	v_mfma_f32_16x16x32_bf16 v[32:35], v[166:169], v[192:195], v[32:35]
	v_mfma_f32_16x16x32_bf16 v[20:23], v[158:161], v[200:203], v[20:23]
	v_mfma_f32_16x16x32_bf16 v[16:19], v[166:169], v[200:203], v[16:19]
	v_mfma_f32_16x16x32_bf16 v[4:7], v[158:161], v[208:211], v[4:7]
	v_mfma_f32_16x16x32_bf16 v[0:3], v[166:169], v[208:211], v[0:3]
	v_mfma_f32_16x16x32_bf16 v[52:55], v[162:165], v[188:191], v[52:55]
	v_mfma_f32_16x16x32_bf16 v[48:51], v[170:173], v[188:191], v[48:51]
	v_mfma_f32_16x16x32_bf16 v[36:39], v[162:165], v[196:199], v[36:39]
	v_mfma_f32_16x16x32_bf16 v[32:35], v[170:173], v[196:199], v[32:35]
	v_mfma_f32_16x16x32_bf16 v[20:23], v[162:165], v[204:207], v[20:23]
	v_mfma_f32_16x16x32_bf16 v[16:19], v[170:173], v[204:207], v[16:19]
	v_mfma_f32_16x16x32_bf16 v[4:7], v[162:165], v[212:215], v[4:7]
	v_mfma_f32_16x16x32_bf16 v[0:3], v[170:173], v[212:215], v[0:3]
	s_barrier
	s_add_i32 s20, 16, 0x18000
	s_add_i32 s21, 16, 0x1c000
	v_add_u32_e32 v154, s20, v139
	v_add_u32_e32 v170, s21, v139
	ds_read_b128 v[142:145], v154
	ds_read_b128 v[146:149], v154 offset:1024
	ds_read_b128 v[150:153], v154 offset:2048
	ds_read_b128 v[154:157], v154 offset:3072
	ds_read_b128 v[158:161], v170
	ds_read_b128 v[162:165], v170 offset:1024
	ds_read_b128 v[166:169], v170 offset:2048
	ds_read_b128 v[170:173], v170 offset:3072
	s_add_u32 s38, s38, 0x10000
	s_addc_u32 s39, s39, 0
	s_mov_b32 m0, s43
	v_lshl_add_u64 v[226:227], s[38:39], 0, v[132:133]
	ds_read_b128 v[184:187], v141 offset:32768
	ds_read_b128 v[188:191], v141 offset:33792
	ds_read_b128 v[192:195], v141 offset:34816
	ds_read_b128 v[196:199], v141 offset:35840
	ds_read_b128 v[200:203], v141 offset:36864
	ds_read_b128 v[204:207], v141 offset:37888
	ds_read_b128 v[208:211], v141 offset:38912
	ds_read_b128 v[212:215], v141 offset:39936
	global_load_lds_dwordx4 v[226:227], off
	v_lshl_add_u64 v[226:227], s[38:39], 0, v[130:131]
	s_mov_b32 m0, s44
	s_nop 0
	global_load_lds_dwordx4 v[226:227], off
	s_waitcnt vmcnt(8)
	s_waitcnt lgkmcnt(0)
	s_barrier
	s_waitcnt lgkmcnt(0)
	v_mfma_f32_16x16x32_bf16 v[120:123], v[142:145], v[184:187], v[120:123]
	v_mfma_f32_16x16x32_bf16 v[124:127], v[150:153], v[184:187], v[124:127]
	v_mfma_f32_16x16x32_bf16 v[108:111], v[142:145], v[192:195], v[108:111]
	v_mfma_f32_16x16x32_bf16 v[104:107], v[150:153], v[192:195], v[104:107]
	v_mfma_f32_16x16x32_bf16 v[92:95], v[142:145], v[200:203], v[92:95]
	v_mfma_f32_16x16x32_bf16 v[88:91], v[150:153], v[200:203], v[88:91]
	v_mfma_f32_16x16x32_bf16 v[76:79], v[142:145], v[208:211], v[76:79]
	v_mfma_f32_16x16x32_bf16 v[72:75], v[150:153], v[208:211], v[72:75]
	v_mfma_f32_16x16x32_bf16 v[120:123], v[146:149], v[188:191], v[120:123]
	v_mfma_f32_16x16x32_bf16 v[124:127], v[154:157], v[188:191], v[124:127]
	v_mfma_f32_16x16x32_bf16 v[108:111], v[146:149], v[196:199], v[108:111]
	v_mfma_f32_16x16x32_bf16 v[104:107], v[154:157], v[196:199], v[104:107]
	v_mfma_f32_16x16x32_bf16 v[92:95], v[146:149], v[204:207], v[92:95]
	v_mfma_f32_16x16x32_bf16 v[88:91], v[154:157], v[204:207], v[88:91]
	v_mfma_f32_16x16x32_bf16 v[76:79], v[146:149], v[212:215], v[76:79]
	v_mfma_f32_16x16x32_bf16 v[72:75], v[154:157], v[212:215], v[72:75]
	v_mfma_f32_16x16x32_bf16 v[116:119], v[158:161], v[184:187], v[116:119]
	v_mfma_f32_16x16x32_bf16 v[112:115], v[166:169], v[184:187], v[112:115]
	v_mfma_f32_16x16x32_bf16 v[100:103], v[158:161], v[192:195], v[100:103]
	v_mfma_f32_16x16x32_bf16 v[96:99], v[166:169], v[192:195], v[96:99]
	v_mfma_f32_16x16x32_bf16 v[84:87], v[158:161], v[200:203], v[84:87]
	v_mfma_f32_16x16x32_bf16 v[80:83], v[166:169], v[200:203], v[80:83]
	v_mfma_f32_16x16x32_bf16 v[68:71], v[158:161], v[208:211], v[68:71]
	v_mfma_f32_16x16x32_bf16 v[64:67], v[166:169], v[208:211], v[64:67]
	v_mfma_f32_16x16x32_bf16 v[116:119], v[162:165], v[188:191], v[116:119]
	v_mfma_f32_16x16x32_bf16 v[112:115], v[170:173], v[188:191], v[112:115]
	v_mfma_f32_16x16x32_bf16 v[100:103], v[162:165], v[196:199], v[100:103]
	v_mfma_f32_16x16x32_bf16 v[96:99], v[170:173], v[196:199], v[96:99]
	v_mfma_f32_16x16x32_bf16 v[84:87], v[162:165], v[204:207], v[84:87]
	v_mfma_f32_16x16x32_bf16 v[80:83], v[170:173], v[204:207], v[80:83]
	v_mfma_f32_16x16x32_bf16 v[68:71], v[162:165], v[212:215], v[68:71]
	v_mfma_f32_16x16x32_bf16 v[64:67], v[170:173], v[212:215], v[64:67]
	s_barrier
; #define PG8_STAGE(bufoff, gbase, voff) do { _Pragma("unroll") for (int _i = 0; _i < 2; ++_i) \
;         __builtin_amdgcn_global_load_lds((const unsigned*)((const char*)(gbase) + (voff)[_i]), (LAS unsigned*)(lds + (bufoff) + ldsw + _i * 8192), 16, 0, 0); } while (0)
; #define PG8_LDA(dst, b, h) do { _Pragma("unroll") for (int m = 0; m < 4; ++m) _Pragma("unroll") for (int k = 0; k < 2; ++k) dst[m][k] = *(const LAS bf16x8*)(lds + PG8_SA(b, h) + aoff + m * 2048 + k * 1024); } while (0)
; #define PG8_MMA(ai, bj, At, Bt) do { __builtin_amdgcn_s_setprio(1); _Pragma("unroll") for (int m = 0; m < 4; ++m) _Pragma("unroll") for (int n = 0; n < 2; ++n) _Pragma("unroll") for (int k = 0; k < 2; ++k) \
;         acc[ai][bj][m][n] = __builtin_amdgcn_mfma_f32_16x16x32_bf16(Bt[n][k], At[m][k], acc[ai][bj][m][n], 0, 0, 0); __builtin_amdgcn_s_setprio(0); } while (0)
; #define PG8_WAIT_V(n) asm volatile("s_waitcnt vmcnt(" #n ")" ::: "memory")
; #define PG8_WAIT_L(n) asm volatile("s_waitcnt lgkmcnt(" #n ")" ::: "memory")
; #define PG8_BAR __builtin_amdgcn_s_barrier()
; #define PG8_SCHED __builtin_amdgcn_sched_barrier(0)
; template <class Epi, bool ALIGN_EPI = PG8_ALIGN>
; __device__ __forceinline__ void gemm_phase(LAS unsigned char* lds, const Gemm g, const StaticOrder& S, const Epi& E) {
;     ...
;             PG8_LDA(At, 1, 1); PG8_STAGE(PG8_SB(1, 0), b3, voffB); PG8_STAGE(PG8_SB(1, 1), b3 + hstepB, voffB); PG8_STAGE(PG8_SA(1, 0), a3, voffA);
;             PG8_WAIT_V(8); PG8_WAIT_L(0); PG8_BAR; PG8_MMA(1, 0, At, B0); PG8_MMA(1, 1, At, B1); PG8_BAR; PG8_SCHED;
;         }
	s_add_i32 s20, s20, s42
	v_lshl_add_u64 v[174:175], v[174:175], 0, s[0:1]
	s_mov_b32 m0, s20
	ds_read_b128 v[184:187], v141 offset:49152
	ds_read_b128 v[188:191], v141 offset:50176
	ds_read_b128 v[192:195], v141 offset:51200
	ds_read_b128 v[196:199], v141 offset:52224
	ds_read_b128 v[200:203], v141 offset:53248
	ds_read_b128 v[204:207], v141 offset:54272
	ds_read_b128 v[208:211], v141 offset:55296
	ds_read_b128 v[212:215], v141 offset:56320
	global_load_lds_dwordx4 v[174:175], off
	v_lshl_add_u64 v[174:175], v[216:217], 0, s[0:1]
	s_add_i32 m0, s20, 0x2000
	s_add_i32 s20, s21, s42
	global_load_lds_dwordx4 v[174:175], off
	v_lshl_add_u64 v[174:175], v[218:219], 0, s[0:1]
	s_mov_b32 m0, s20
	s_nop 0
	global_load_lds_dwordx4 v[174:175], off
	v_lshl_add_u64 v[174:175], v[220:221], 0, s[0:1]
	s_add_i32 m0, s20, 0x2000
	s_nop 0
	global_load_lds_dwordx4 v[174:175], off
	v_lshl_add_u64 v[174:175], v[222:223], 0, s[0:1]
	s_mov_b32 m0, s45
	s_nop 0
	global_load_lds_dwordx4 v[174:175], off
	v_lshl_add_u64 v[174:175], v[224:225], 0, s[0:1]
	s_mov_b32 m0, s46
	s_nop 0
	global_load_lds_dwordx4 v[174:175], off
	s_waitcnt vmcnt(8)
	s_waitcnt lgkmcnt(0)
	s_barrier
	s_waitcnt lgkmcnt(0)
	v_mfma_f32_16x16x32_bf16 v[60:63], v[142:145], v[184:187], v[60:63]
	v_mfma_f32_16x16x32_bf16 v[56:59], v[150:153], v[184:187], v[56:59]
	v_mfma_f32_16x16x32_bf16 v[44:47], v[142:145], v[192:195], v[44:47]
	v_mfma_f32_16x16x32_bf16 v[40:43], v[150:153], v[192:195], v[40:43]
	v_mfma_f32_16x16x32_bf16 v[28:31], v[142:145], v[200:203], v[28:31]
	v_mfma_f32_16x16x32_bf16 v[24:27], v[150:153], v[200:203], v[24:27]
	v_mfma_f32_16x16x32_bf16 v[12:15], v[142:145], v[208:211], v[12:15]
	v_mfma_f32_16x16x32_bf16 v[8:11], v[150:153], v[208:211], v[8:11]
	v_mfma_f32_16x16x32_bf16 v[60:63], v[146:149], v[188:191], v[60:63]
	v_mfma_f32_16x16x32_bf16 v[56:59], v[154:157], v[188:191], v[56:59]
	v_mfma_f32_16x16x32_bf16 v[44:47], v[146:149], v[196:199], v[44:47]
	v_mfma_f32_16x16x32_bf16 v[40:43], v[154:157], v[196:199], v[40:43]
	v_mfma_f32_16x16x32_bf16 v[28:31], v[146:149], v[204:207], v[28:31]
	v_mfma_f32_16x16x32_bf16 v[24:27], v[154:157], v[204:207], v[24:27]
	v_mfma_f32_16x16x32_bf16 v[12:15], v[146:149], v[212:215], v[12:15]
	v_mfma_f32_16x16x32_bf16 v[8:11], v[154:157], v[212:215], v[8:11]
	v_mfma_f32_16x16x32_bf16 v[52:55], v[158:161], v[184:187], v[52:55]
	v_mfma_f32_16x16x32_bf16 v[48:51], v[166:169], v[184:187], v[48:51]
	v_mfma_f32_16x16x32_bf16 v[36:39], v[158:161], v[192:195], v[36:39]
	v_mfma_f32_16x16x32_bf16 v[32:35], v[166:169], v[192:195], v[32:35]
	v_mfma_f32_16x16x32_bf16 v[20:23], v[158:161], v[200:203], v[20:23]
	v_mfma_f32_16x16x32_bf16 v[16:19], v[166:169], v[200:203], v[16:19]
	v_mfma_f32_16x16x32_bf16 v[4:7], v[158:161], v[208:211], v[4:7]
	v_mfma_f32_16x16x32_bf16 v[0:3], v[166:169], v[208:211], v[0:3]
	v_mfma_f32_16x16x32_bf16 v[52:55], v[162:165], v[188:191], v[52:55]
	v_mfma_f32_16x16x32_bf16 v[48:51], v[170:173], v[188:191], v[48:51]
	v_mfma_f32_16x16x32_bf16 v[36:39], v[162:165], v[196:199], v[36:39]
	v_mfma_f32_16x16x32_bf16 v[32:35], v[170:173], v[196:199], v[32:35]
	v_mfma_f32_16x16x32_bf16 v[20:23], v[162:165], v[204:207], v[20:23]
	v_mfma_f32_16x16x32_bf16 v[16:19], v[170:173], v[204:207], v[16:19]
	v_mfma_f32_16x16x32_bf16 v[4:7], v[162:165], v[212:215], v[4:7]
	v_mfma_f32_16x16x32_bf16 v[0:3], v[170:173], v[212:215], v[0:3]
	s_barrier
	s_add_u32 s4, s4, 0x100
	s_addc_u32 s5, s5, 0
	s_add_u32 s40, s40, 0x100
	s_addc_u32 s41, s41, 0
	s_cmp_ge_i32 s53, s34
	s_mov_b32 s38, s53
	s_cbranch_scc0 .LBB0_481

; #define PG8_STAGE(bufoff, gbase, voff) do { _Pragma("unroll") for (int _i = 0; _i < 2; ++_i) \
;         __builtin_amdgcn_global_load_lds((const unsigned*)((const char*)(gbase) + (voff)[_i]), (LAS unsigned*)(lds + (bufoff) + ldsw + _i * 8192), 16, 0, 0); } while (0)
; #define PG8_LDA(dst, b, h) do { _Pragma("unroll") for (int m = 0; m < 4; ++m) _Pragma("unroll") for (int k = 0; k < 2; ++k) dst[m][k] = *(const LAS bf16x8*)(lds + PG8_SA(b, h) + aoff + m * 2048 + k * 1024); } while (0)
; #define PG8_LDB(dst, b, h) do { _Pragma("unroll") for (int n = 0; n < 2; ++n) _Pragma("unroll") for (int k = 0; k < 2; ++k) dst[n][k] = *(const LAS bf16x8*)(lds + PG8_SB(b, h) + boff + n * 2048 + k * 1024); } while (0)
; #define PG8_MMA(ai, bj, At, Bt) do { __builtin_amdgcn_s_setprio(1); _Pragma("unroll") for (int m = 0; m < 4; ++m) _Pragma("unroll") for (int n = 0; n < 2; ++n) _Pragma("unroll") for (int k = 0; k < 2; ++k) \
;         acc[ai][bj][m][n] = __builtin_amdgcn_mfma_f32_16x16x32_bf16(Bt[n][k], At[m][k], acc[ai][bj][m][n], 0, 0, 0); __builtin_amdgcn_s_setprio(0); } while (0)
; #define PG8_WAIT_V(n) asm volatile("s_waitcnt vmcnt(" #n ")" ::: "memory")
; #define PG8_WAIT_L(n) asm volatile("s_waitcnt lgkmcnt(" #n ")" ::: "memory")
; #define PG8_BAR __builtin_amdgcn_s_barrier()
; #define PG8_SCHED __builtin_amdgcn_sched_barrier(0)
; template <class Epi, bool ALIGN_EPI = PG8_ALIGN>
; __device__ __forceinline__ void gemm_phase(LAS unsigned char* lds, const Gemm g, const StaticOrder& S, const Epi& E) {
;     ...
;         for (int t = 0; t < nt; t += 2) {
;             const bool last = (t == nt - 2);
;             const char* a1 = cA + (size_t)(t + 1) * kstep;
;             const char* a2 = last ? nA : cA + (size_t)(t + 2) * kstep; const char* b2 = last ? nB : cB + (size_t)(t + 2) * kstep;
;             const char* a3 = a2 + kstep; const char* b3 = b2 + kstep;
;             PG8_LDB(B0, 0, 0); PG8_LDB(B1, 0, 1); PG8_SCHED; PG8_LDA(At, 0, 0); PG8_STAGE(PG8_SA(1, 1), a1 + hstepA, voffA);
;             PG8_WAIT_V(8); PG8_WAIT_L(0); PG8_BAR; PG8_MMA(0, 0, At, B0); PG8_MMA(0, 1, At, B1); PG8_BAR; PG8_SCHED;
;             PG8_LDA(At, 0, 1); PG8_STAGE(PG8_SB(0, 0), b2, voffB); PG8_STAGE(PG8_SB(0, 1), b2 + hstepB, voffB); PG8_STAGE(PG8_SA(0, 0), a2, voffA);
;             PG8_WAIT_V(8); PG8_WAIT_L(0); PG8_BAR; PG8_MMA(1, 0, At, B0); PG8_MMA(1, 1, At, B1); PG8_BAR; PG8_SCHED;
.LBB0_642:
	s_add_i32 s53, s38, 2
	s_add_u32 s36, s24, 0x100
	s_addc_u32 s37, s25, 0
	s_add_i32 s20, 16, 0x10000
	s_cmp_eq_u32 s48, s38
	s_cselect_b32 s39, s3, s37
	s_cselect_b32 s38, s2, s36
	v_add_u32_e32 v142, s20, v149
	s_cselect_b32 s55, s17, s52
	s_cselect_b32 s54, s16, s51
	s_add_i32 s21, 16, 0x14000
	ds_read_b128 v[138:141], v142
	ds_read_b128 v[152:155], v142 offset:1024
	ds_read_b128 v[156:159], v142 offset:2048
	ds_read_b128 v[160:163], v142 offset:3072
	v_add_u32_e32 v142, s21, v149
	ds_read_b128 v[164:167], v142
	ds_read_b128 v[168:171], v142 offset:1024
	ds_read_b128 v[172:175], v142 offset:2048
	ds_read_b128 v[184:187], v142 offset:3072
	v_lshl_add_u64 v[142:143], s[24:25], 0, v[134:135]
	s_add_i32 m0, s31, 0xc000
	ds_read_b128 v[188:191], v151
	ds_read_b128 v[192:195], v151 offset:1024
	ds_read_b128 v[196:199], v151 offset:2048
	ds_read_b128 v[200:203], v151 offset:3072
	ds_read_b128 v[204:207], v151 offset:4096
	ds_read_b128 v[208:211], v151 offset:5120
	ds_read_b128 v[212:215], v151 offset:6144
	ds_read_b128 v[216:219], v151 offset:7168
	global_load_lds_dwordx4 v[142:143], off
	v_lshl_add_u64 v[142:143], s[24:25], 0, v[136:137]
	s_add_i32 m0, s31, 0xe000
	s_nop 0
	global_load_lds_dwordx4 v[142:143], off
	s_waitcnt vmcnt(8)
	s_waitcnt lgkmcnt(0)
	s_barrier
	s_waitcnt lgkmcnt(0)
	v_mfma_f32_16x16x32_bf16 v[120:123], v[138:141], v[188:191], v[120:123]
	v_mfma_f32_16x16x32_bf16 v[124:127], v[156:159], v[188:191], v[124:127]
	v_mfma_f32_16x16x32_bf16 v[108:111], v[138:141], v[196:199], v[108:111]
	v_mfma_f32_16x16x32_bf16 v[104:107], v[156:159], v[196:199], v[104:107]
	v_mfma_f32_16x16x32_bf16 v[92:95], v[138:141], v[204:207], v[92:95]
	v_mfma_f32_16x16x32_bf16 v[88:91], v[156:159], v[204:207], v[88:91]
	v_mfma_f32_16x16x32_bf16 v[76:79], v[138:141], v[212:215], v[76:79]
	v_mfma_f32_16x16x32_bf16 v[72:75], v[156:159], v[212:215], v[72:75]
	v_mfma_f32_16x16x32_bf16 v[120:123], v[152:155], v[192:195], v[120:123]
	v_mfma_f32_16x16x32_bf16 v[124:127], v[160:163], v[192:195], v[124:127]
	v_mfma_f32_16x16x32_bf16 v[108:111], v[152:155], v[200:203], v[108:111]
	v_mfma_f32_16x16x32_bf16 v[104:107], v[160:163], v[200:203], v[104:107]
	v_mfma_f32_16x16x32_bf16 v[92:95], v[152:155], v[208:211], v[92:95]
	v_mfma_f32_16x16x32_bf16 v[88:91], v[160:163], v[208:211], v[88:91]
	v_mfma_f32_16x16x32_bf16 v[76:79], v[152:155], v[216:219], v[76:79]
	v_mfma_f32_16x16x32_bf16 v[72:75], v[160:163], v[216:219], v[72:75]
	v_mfma_f32_16x16x32_bf16 v[116:119], v[164:167], v[188:191], v[116:119]
	v_mfma_f32_16x16x32_bf16 v[112:115], v[172:175], v[188:191], v[112:115]
	v_mfma_f32_16x16x32_bf16 v[100:103], v[164:167], v[196:199], v[100:103]
	v_mfma_f32_16x16x32_bf16 v[96:99], v[172:175], v[196:199], v[96:99]
	v_mfma_f32_16x16x32_bf16 v[84:87], v[164:167], v[204:207], v[84:87]
	v_mfma_f32_16x16x32_bf16 v[80:83], v[172:175], v[204:207], v[80:83]
	v_mfma_f32_16x16x32_bf16 v[68:71], v[164:167], v[212:215], v[68:71]
	v_mfma_f32_16x16x32_bf16 v[64:67], v[172:175], v[212:215], v[64:67]
	v_mfma_f32_16x16x32_bf16 v[116:119], v[168:171], v[192:195], v[116:119]
	v_mfma_f32_16x16x32_bf16 v[112:115], v[184:187], v[192:195], v[112:115]
	v_mfma_f32_16x16x32_bf16 v[100:103], v[168:171], v[200:203], v[100:103]
	v_mfma_f32_16x16x32_bf16 v[96:99], v[184:187], v[200:203], v[96:99]
	v_mfma_f32_16x16x32_bf16 v[84:87], v[168:171], v[208:211], v[84:87]
	v_mfma_f32_16x16x32_bf16 v[80:83], v[184:187], v[208:211], v[80:83]
	v_mfma_f32_16x16x32_bf16 v[68:71], v[168:171], v[216:219], v[68:71]
	v_mfma_f32_16x16x32_bf16 v[64:67], v[184:187], v[216:219], v[64:67]
	s_barrier
	s_add_i32 s20, s20, s30
	v_lshl_add_u64 v[142:143], s[54:55], 0, v[176:177]
	s_mov_b32 m0, s20
	ds_read_b128 v[188:191], v151 offset:16384
	ds_read_b128 v[192:195], v151 offset:17408
	ds_read_b128 v[196:199], v151 offset:18432
	ds_read_b128 v[200:203], v151 offset:19456
	ds_read_b128 v[204:207], v151 offset:20480
	ds_read_b128 v[208:211], v151 offset:21504
	ds_read_b128 v[212:215], v151 offset:22528
	ds_read_b128 v[216:219], v151 offset:23552
	global_load_lds_dwordx4 v[142:143], off
	s_add_i32 m0, s20, 0x2000
	s_add_u32 s24, s54, s6
	v_lshl_add_u64 v[146:147], s[54:55], 0, v[128:129]
	s_addc_u32 s25, s55, s7
	s_add_i32 s20, s21, s30
	global_load_lds_dwordx4 v[146:147], off
	v_lshl_add_u64 v[220:221], s[24:25], 0, v[176:177]
	s_mov_b32 m0, s20
	v_lshl_add_u64 v[222:223], s[24:25], 0, v[128:129]
	global_load_lds_dwordx4 v[220:221], off
	s_add_i32 m0, s20, 0x2000
	v_lshl_add_u64 v[224:225], s[38:39], 0, v[132:133]
	global_load_lds_dwordx4 v[222:223], off
	s_mov_b32 m0, s31
	v_lshl_add_u64 v[226:227], s[38:39], 0, v[130:131]
	global_load_lds_dwordx4 v[224:225], off
	s_mov_b32 m0, s40
	s_nop 0
	global_load_lds_dwordx4 v[226:227], off
	s_waitcnt vmcnt(8)
	s_waitcnt lgkmcnt(0)
	s_barrier
; #define PG8_STAGE(bufoff, gbase, voff) do { _Pragma("unroll") for (int _i = 0; _i < 2; ++_i) \
;         __builtin_amdgcn_global_load_lds((const unsigned*)((const char*)(gbase) + (voff)[_i]), (LAS unsigned*)(lds + (bufoff) + ldsw + _i * 8192), 16, 0, 0); } while (0)
; #define PG8_LDA(dst, b, h) do { _Pragma("unroll") for (int m = 0; m < 4; ++m) _Pragma("unroll") for (int k = 0; k < 2; ++k) dst[m][k] = *(const LAS bf16x8*)(lds + PG8_SA(b, h) + aoff + m * 2048 + k * 1024); } while (0)
; #define PG8_LDB(dst, b, h) do { _Pragma("unroll") for (int n = 0; n < 2; ++n) _Pragma("unroll") for (int k = 0; k < 2; ++k) dst[n][k] = *(const LAS bf16x8*)(lds + PG8_SB(b, h) + boff + n * 2048 + k * 1024); } while (0)
; #define PG8_MMA(ai, bj, At, Bt) do { __builtin_amdgcn_s_setprio(1); _Pragma("unroll") for (int m = 0; m < 4; ++m) _Pragma("unroll") for (int n = 0; n < 2; ++n) _Pragma("unroll") for (int k = 0; k < 2; ++k) \
;         acc[ai][bj][m][n] = __builtin_amdgcn_mfma_f32_16x16x32_bf16(Bt[n][k], At[m][k], acc[ai][bj][m][n], 0, 0, 0); __builtin_amdgcn_s_setprio(0); } while (0)
; #define PG8_WAIT_V(n) asm volatile("s_waitcnt vmcnt(" #n ")" ::: "memory")
; #define PG8_WAIT_L(n) asm volatile("s_waitcnt lgkmcnt(" #n ")" ::: "memory")
; #define PG8_BAR __builtin_amdgcn_s_barrier()
; #define PG8_SCHED __builtin_amdgcn_sched_barrier(0)
; template <class Epi, bool ALIGN_EPI = PG8_ALIGN>
; __device__ __forceinline__ void gemm_phase(LAS unsigned char* lds, const Gemm g, const StaticOrder& S, const Epi& E) {
;     ...
;             PG8_WAIT_V(8); PG8_WAIT_L(0); PG8_BAR; PG8_MMA(1, 0, At, B0); PG8_MMA(1, 1, At, B1); PG8_BAR; PG8_SCHED;
;             PG8_LDB(B0, 1, 0); PG8_LDB(B1, 1, 1); PG8_SCHED; PG8_LDA(At, 1, 0); PG8_STAGE(PG8_SA(0, 1), a2 + hstepA, voffA);
;             PG8_WAIT_V(8); PG8_WAIT_L(0); PG8_BAR; PG8_MMA(0, 0, At, B0); PG8_MMA(0, 1, At, B1); PG8_BAR; PG8_SCHED;
	s_waitcnt lgkmcnt(0)
	v_mfma_f32_16x16x32_bf16 v[60:63], v[138:141], v[188:191], v[60:63]
	v_mfma_f32_16x16x32_bf16 v[56:59], v[156:159], v[188:191], v[56:59]
	v_mfma_f32_16x16x32_bf16 v[44:47], v[138:141], v[196:199], v[44:47]
	v_mfma_f32_16x16x32_bf16 v[40:43], v[156:159], v[196:199], v[40:43]
	v_mfma_f32_16x16x32_bf16 v[28:31], v[138:141], v[204:207], v[28:31]
	v_mfma_f32_16x16x32_bf16 v[24:27], v[156:159], v[204:207], v[24:27]
	v_mfma_f32_16x16x32_bf16 v[12:15], v[138:141], v[212:215], v[12:15]
	v_mfma_f32_16x16x32_bf16 v[8:11], v[156:159], v[212:215], v[8:11]
	v_mfma_f32_16x16x32_bf16 v[60:63], v[152:155], v[192:195], v[60:63]
	v_mfma_f32_16x16x32_bf16 v[56:59], v[160:163], v[192:195], v[56:59]
	v_mfma_f32_16x16x32_bf16 v[44:47], v[152:155], v[200:203], v[44:47]
	v_mfma_f32_16x16x32_bf16 v[40:43], v[160:163], v[200:203], v[40:43]
	v_mfma_f32_16x16x32_bf16 v[28:31], v[152:155], v[208:211], v[28:31]
	v_mfma_f32_16x16x32_bf16 v[24:27], v[160:163], v[208:211], v[24:27]
	v_mfma_f32_16x16x32_bf16 v[12:15], v[152:155], v[216:219], v[12:15]
	v_mfma_f32_16x16x32_bf16 v[8:11], v[160:163], v[216:219], v[8:11]
	v_mfma_f32_16x16x32_bf16 v[52:55], v[164:167], v[188:191], v[52:55]
	v_mfma_f32_16x16x32_bf16 v[48:51], v[172:175], v[188:191], v[48:51]
	v_mfma_f32_16x16x32_bf16 v[36:39], v[164:167], v[196:199], v[36:39]
	v_mfma_f32_16x16x32_bf16 v[32:35], v[172:175], v[196:199], v[32:35]
	v_mfma_f32_16x16x32_bf16 v[20:23], v[164:167], v[204:207], v[20:23]
	v_mfma_f32_16x16x32_bf16 v[16:19], v[172:175], v[204:207], v[16:19]
	v_mfma_f32_16x16x32_bf16 v[4:7], v[164:167], v[212:215], v[4:7]
	v_mfma_f32_16x16x32_bf16 v[0:3], v[172:175], v[212:215], v[0:3]
	v_mfma_f32_16x16x32_bf16 v[52:55], v[168:171], v[192:195], v[52:55]
	v_mfma_f32_16x16x32_bf16 v[48:51], v[184:187], v[192:195], v[48:51]
	v_mfma_f32_16x16x32_bf16 v[36:39], v[168:171], v[200:203], v[36:39]
	v_mfma_f32_16x16x32_bf16 v[32:35], v[184:187], v[200:203], v[32:35]
	v_mfma_f32_16x16x32_bf16 v[20:23], v[168:171], v[208:211], v[20:23]
	v_mfma_f32_16x16x32_bf16 v[16:19], v[184:187], v[208:211], v[16:19]
	v_mfma_f32_16x16x32_bf16 v[4:7], v[168:171], v[216:219], v[4:7]
	v_mfma_f32_16x16x32_bf16 v[0:3], v[184:187], v[216:219], v[0:3]
	s_barrier
	s_add_i32 s20, 16, 0x18000
	v_add_u32_e32 v144, s20, v149
	s_add_i32 s21, 16, 0x1c000
	ds_read_b128 v[138:141], v144
	ds_read_b128 v[152:155], v144 offset:1024
	ds_read_b128 v[156:159], v144 offset:2048
	ds_read_b128 v[160:163], v144 offset:3072
	v_add_u32_e32 v144, s21, v149
	ds_read_b128 v[164:167], v144
	ds_read_b128 v[168:171], v144 offset:1024
	ds_read_b128 v[172:175], v144 offset:2048
	ds_read_b128 v[184:187], v144 offset:3072
	s_add_u32 s24, s38, 0x110000
	s_addc_u32 s25, s39, 0
	s_mov_b32 m0, s41
	v_lshl_add_u64 v[228:229], s[24:25], 0, v[132:133]
	ds_read_b128 v[188:191], v151 offset:32768
	ds_read_b128 v[192:195], v151 offset:33792
	ds_read_b128 v[196:199], v151 offset:34816
	ds_read_b128 v[200:203], v151 offset:35840
	ds_read_b128 v[204:207], v151 offset:36864
	ds_read_b128 v[208:211], v151 offset:37888
	ds_read_b128 v[212:215], v151 offset:38912
	ds_read_b128 v[216:219], v151 offset:39936
	global_load_lds_dwordx4 v[228:229], off
	v_lshl_add_u64 v[228:229], s[24:25], 0, v[130:131]
	s_mov_b32 m0, s44
	s_nop 0
	global_load_lds_dwordx4 v[228:229], off
	s_waitcnt vmcnt(8)
	s_waitcnt lgkmcnt(0)
	s_barrier
	s_waitcnt lgkmcnt(0)
	v_mfma_f32_16x16x32_bf16 v[120:123], v[138:141], v[188:191], v[120:123]
	v_mfma_f32_16x16x32_bf16 v[124:127], v[156:159], v[188:191], v[124:127]
	v_mfma_f32_16x16x32_bf16 v[108:111], v[138:141], v[196:199], v[108:111]
	v_mfma_f32_16x16x32_bf16 v[104:107], v[156:159], v[196:199], v[104:107]
	v_mfma_f32_16x16x32_bf16 v[92:95], v[138:141], v[204:207], v[92:95]
	v_mfma_f32_16x16x32_bf16 v[88:91], v[156:159], v[204:207], v[88:91]
	v_mfma_f32_16x16x32_bf16 v[76:79], v[138:141], v[212:215], v[76:79]
	v_mfma_f32_16x16x32_bf16 v[72:75], v[156:159], v[212:215], v[72:75]
	v_mfma_f32_16x16x32_bf16 v[120:123], v[152:155], v[192:195], v[120:123]
	v_mfma_f32_16x16x32_bf16 v[124:127], v[160:163], v[192:195], v[124:127]
	v_mfma_f32_16x16x32_bf16 v[108:111], v[152:155], v[200:203], v[108:111]
	v_mfma_f32_16x16x32_bf16 v[104:107], v[160:163], v[200:203], v[104:107]
	v_mfma_f32_16x16x32_bf16 v[92:95], v[152:155], v[208:211], v[92:95]
	v_mfma_f32_16x16x32_bf16 v[88:91], v[160:163], v[208:211], v[88:91]
	v_mfma_f32_16x16x32_bf16 v[76:79], v[152:155], v[216:219], v[76:79]
	v_mfma_f32_16x16x32_bf16 v[72:75], v[160:163], v[216:219], v[72:75]
	v_mfma_f32_16x16x32_bf16 v[116:119], v[164:167], v[188:191], v[116:119]
	v_mfma_f32_16x16x32_bf16 v[112:115], v[172:175], v[188:191], v[112:115]
	v_mfma_f32_16x16x32_bf16 v[100:103], v[164:167], v[196:199], v[100:103]
	v_mfma_f32_16x16x32_bf16 v[96:99], v[172:175], v[196:199], v[96:99]
	v_mfma_f32_16x16x32_bf16 v[84:87], v[164:167], v[204:207], v[84:87]
	v_mfma_f32_16x16x32_bf16 v[80:83], v[172:175], v[204:207], v[80:83]
	v_mfma_f32_16x16x32_bf16 v[68:71], v[164:167], v[212:215], v[68:71]
	v_mfma_f32_16x16x32_bf16 v[64:67], v[172:175], v[212:215], v[64:67]
	v_mfma_f32_16x16x32_bf16 v[116:119], v[168:171], v[192:195], v[116:119]
	v_mfma_f32_16x16x32_bf16 v[112:115], v[184:187], v[192:195], v[112:115]
	v_mfma_f32_16x16x32_bf16 v[100:103], v[168:171], v[200:203], v[100:103]
	v_mfma_f32_16x16x32_bf16 v[96:99], v[184:187], v[200:203], v[96:99]
	v_mfma_f32_16x16x32_bf16 v[84:87], v[168:171], v[208:211], v[84:87]
	v_mfma_f32_16x16x32_bf16 v[80:83], v[184:187], v[208:211], v[80:83]
	v_mfma_f32_16x16x32_bf16 v[68:71], v[168:171], v[216:219], v[68:71]
	v_mfma_f32_16x16x32_bf16 v[64:67], v[184:187], v[216:219], v[64:67]
	s_barrier
; #define PG8_STAGE(bufoff, gbase, voff) do { _Pragma("unroll") for (int _i = 0; _i < 2; ++_i) \
;         __builtin_amdgcn_global_load_lds((const unsigned*)((const char*)(gbase) + (voff)[_i]), (LAS unsigned*)(lds + (bufoff) + ldsw + _i * 8192), 16, 0, 0); } while (0)
; #define PG8_LDA(dst, b, h) do { _Pragma("unroll") for (int m = 0; m < 4; ++m) _Pragma("unroll") for (int k = 0; k < 2; ++k) dst[m][k] = *(const LAS bf16x8*)(lds + PG8_SA(b, h) + aoff + m * 2048 + k * 1024); } while (0)
; #define PG8_MMA(ai, bj, At, Bt) do { __builtin_amdgcn_s_setprio(1); _Pragma("unroll") for (int m = 0; m < 4; ++m) _Pragma("unroll") for (int n = 0; n < 2; ++n) _Pragma("unroll") for (int k = 0; k < 2; ++k) \
;         acc[ai][bj][m][n] = __builtin_amdgcn_mfma_f32_16x16x32_bf16(Bt[n][k], At[m][k], acc[ai][bj][m][n], 0, 0, 0); __builtin_amdgcn_s_setprio(0); } while (0)
; #define PG8_WAIT_V(n) asm volatile("s_waitcnt vmcnt(" #n ")" ::: "memory")
; #define PG8_WAIT_L(n) asm volatile("s_waitcnt lgkmcnt(" #n ")" ::: "memory")
; #define PG8_BAR __builtin_amdgcn_s_barrier()
; #define PG8_SCHED __builtin_amdgcn_sched_barrier(0)
; template <class Epi, bool ALIGN_EPI = PG8_ALIGN>
; __device__ __forceinline__ void gemm_phase(LAS unsigned char* lds, const Gemm g, const StaticOrder& S, const Epi& E) {
;     ...
;             PG8_LDA(At, 1, 1); PG8_STAGE(PG8_SB(1, 0), b3, voffB); PG8_STAGE(PG8_SB(1, 1), b3 + hstepB, voffB); PG8_STAGE(PG8_SA(1, 0), a3, voffA);
;             PG8_WAIT_V(8); PG8_WAIT_L(0); PG8_BAR; PG8_MMA(1, 0, At, B0); PG8_MMA(1, 1, At, B1); PG8_BAR; PG8_SCHED;
;         }
	s_add_i32 s20, s20, s30
	v_lshl_add_u64 v[142:143], v[142:143], 0, s[0:1]
	s_mov_b32 m0, s20
	ds_read_b128 v[188:191], v151 offset:49152
	ds_read_b128 v[192:195], v151 offset:50176
	ds_read_b128 v[196:199], v151 offset:51200
	ds_read_b128 v[200:203], v151 offset:52224
	ds_read_b128 v[204:207], v151 offset:53248
	ds_read_b128 v[208:211], v151 offset:54272
	ds_read_b128 v[212:215], v151 offset:55296
	ds_read_b128 v[216:219], v151 offset:56320
	global_load_lds_dwordx4 v[142:143], off
	v_lshl_add_u64 v[142:143], v[146:147], 0, s[0:1]
	s_add_i32 m0, s20, 0x2000
	s_add_i32 s20, s21, s30
	global_load_lds_dwordx4 v[142:143], off
	v_lshl_add_u64 v[142:143], v[220:221], 0, s[0:1]
	s_mov_b32 m0, s20
	s_nop 0
	global_load_lds_dwordx4 v[142:143], off
	v_lshl_add_u64 v[142:143], v[222:223], 0, s[0:1]
	s_add_i32 m0, s20, 0x2000
	s_nop 0
	global_load_lds_dwordx4 v[142:143], off
	v_lshl_add_u64 v[142:143], v[224:225], 0, s[0:1]
	s_mov_b32 m0, s45
	s_nop 0
	global_load_lds_dwordx4 v[142:143], off
	v_lshl_add_u64 v[142:143], v[226:227], 0, s[0:1]
	s_mov_b32 m0, s46
	s_nop 0
	global_load_lds_dwordx4 v[142:143], off
	s_waitcnt vmcnt(8)
	s_waitcnt lgkmcnt(0)
	s_barrier
	s_waitcnt lgkmcnt(0)
	v_mfma_f32_16x16x32_bf16 v[60:63], v[138:141], v[188:191], v[60:63]
	v_mfma_f32_16x16x32_bf16 v[56:59], v[156:159], v[188:191], v[56:59]
	v_mfma_f32_16x16x32_bf16 v[44:47], v[138:141], v[196:199], v[44:47]
	v_mfma_f32_16x16x32_bf16 v[40:43], v[156:159], v[196:199], v[40:43]
	v_mfma_f32_16x16x32_bf16 v[28:31], v[138:141], v[204:207], v[28:31]
	v_mfma_f32_16x16x32_bf16 v[24:27], v[156:159], v[204:207], v[24:27]
	v_mfma_f32_16x16x32_bf16 v[12:15], v[138:141], v[212:215], v[12:15]
	v_mfma_f32_16x16x32_bf16 v[8:11], v[156:159], v[212:215], v[8:11]
	v_mfma_f32_16x16x32_bf16 v[60:63], v[152:155], v[192:195], v[60:63]
	v_mfma_f32_16x16x32_bf16 v[56:59], v[160:163], v[192:195], v[56:59]
	v_mfma_f32_16x16x32_bf16 v[44:47], v[152:155], v[200:203], v[44:47]
	v_mfma_f32_16x16x32_bf16 v[40:43], v[160:163], v[200:203], v[40:43]
	v_mfma_f32_16x16x32_bf16 v[28:31], v[152:155], v[208:211], v[28:31]
	v_mfma_f32_16x16x32_bf16 v[24:27], v[160:163], v[208:211], v[24:27]
	v_mfma_f32_16x16x32_bf16 v[12:15], v[152:155], v[216:219], v[12:15]
	v_mfma_f32_16x16x32_bf16 v[8:11], v[160:163], v[216:219], v[8:11]
	v_mfma_f32_16x16x32_bf16 v[52:55], v[164:167], v[188:191], v[52:55]
	v_mfma_f32_16x16x32_bf16 v[48:51], v[172:175], v[188:191], v[48:51]
	v_mfma_f32_16x16x32_bf16 v[36:39], v[164:167], v[196:199], v[36:39]
	v_mfma_f32_16x16x32_bf16 v[32:35], v[172:175], v[196:199], v[32:35]
	v_mfma_f32_16x16x32_bf16 v[20:23], v[164:167], v[204:207], v[20:23]
	v_mfma_f32_16x16x32_bf16 v[16:19], v[172:175], v[204:207], v[16:19]
	v_mfma_f32_16x16x32_bf16 v[4:7], v[164:167], v[212:215], v[4:7]
	v_mfma_f32_16x16x32_bf16 v[0:3], v[172:175], v[212:215], v[0:3]
	v_mfma_f32_16x16x32_bf16 v[52:55], v[168:171], v[192:195], v[52:55]
	v_mfma_f32_16x16x32_bf16 v[48:51], v[184:187], v[192:195], v[48:51]
	v_mfma_f32_16x16x32_bf16 v[36:39], v[168:171], v[200:203], v[36:39]
	v_mfma_f32_16x16x32_bf16 v[32:35], v[184:187], v[200:203], v[32:35]
	v_mfma_f32_16x16x32_bf16 v[20:23], v[168:171], v[208:211], v[20:23]
	v_mfma_f32_16x16x32_bf16 v[16:19], v[184:187], v[208:211], v[16:19]
	v_mfma_f32_16x16x32_bf16 v[4:7], v[168:171], v[216:219], v[4:7]
	v_mfma_f32_16x16x32_bf16 v[0:3], v[184:187], v[216:219], v[0:3]
	s_barrier
	s_add_u32 s51, s51, 0x100
	s_addc_u32 s52, s52, 0
	s_cmp_ge_i32 s53, s47
	s_mov_b64 s[24:25], s[36:37]
	s_mov_b32 s38, s53
	s_cbranch_scc0 .LBB0_642

; #define PG8_STAGE(bufoff, gbase, voff) do { _Pragma("unroll") for (int _i = 0; _i < 2; ++_i) \
;         __builtin_amdgcn_global_load_lds((const unsigned*)((const char*)(gbase) + (voff)[_i]), (LAS unsigned*)(lds + (bufoff) + ldsw + _i * 8192), 16, 0, 0); } while (0)
; #define PG8_LDA(dst, b, h) do { _Pragma("unroll") for (int m = 0; m < 4; ++m) _Pragma("unroll") for (int k = 0; k < 2; ++k) dst[m][k] = *(const LAS bf16x8*)(lds + PG8_SA(b, h) + aoff + m * 2048 + k * 1024); } while (0)
; #define PG8_LDB(dst, b, h) do { _Pragma("unroll") for (int n = 0; n < 2; ++n) _Pragma("unroll") for (int k = 0; k < 2; ++k) dst[n][k] = *(const LAS bf16x8*)(lds + PG8_SB(b, h) + boff + n * 2048 + k * 1024); } while (0)
; #define PG8_MMA(ai, bj, At, Bt) do { __builtin_amdgcn_s_setprio(1); _Pragma("unroll") for (int m = 0; m < 4; ++m) _Pragma("unroll") for (int n = 0; n < 2; ++n) _Pragma("unroll") for (int k = 0; k < 2; ++k) \
;         acc[ai][bj][m][n] = __builtin_amdgcn_mfma_f32_16x16x32_bf16(Bt[n][k], At[m][k], acc[ai][bj][m][n], 0, 0, 0); __builtin_amdgcn_s_setprio(0); } while (0)
; #define PG8_WAIT_V(n) asm volatile("s_waitcnt vmcnt(" #n ")" ::: "memory")
; #define PG8_WAIT_L(n) asm volatile("s_waitcnt lgkmcnt(" #n ")" ::: "memory")
; #define PG8_BAR __builtin_amdgcn_s_barrier()
; #define PG8_SCHED __builtin_amdgcn_sched_barrier(0)
; template <class Epi, bool ALIGN_EPI = PG8_ALIGN>
; __device__ __forceinline__ void gemm_phase(LAS unsigned char* lds, const Gemm g, const StaticOrder& S, const Epi& E) {
;     ...
;         for (int t = 0; t < nt; t += 2) {
;             const bool last = (t == nt - 2);
;             const char* a1 = cA + (size_t)(t + 1) * kstep;
;             const char* a2 = last ? nA : cA + (size_t)(t + 2) * kstep; const char* b2 = last ? nB : cB + (size_t)(t + 2) * kstep;
;             const char* a3 = a2 + kstep; const char* b3 = b2 + kstep;
;             PG8_LDB(B0, 0, 0); PG8_LDB(B1, 0, 1); PG8_SCHED; PG8_LDA(At, 0, 0); PG8_STAGE(PG8_SA(1, 1), a1 + hstepA, voffA);
;             PG8_WAIT_V(8); PG8_WAIT_L(0); PG8_BAR; PG8_MMA(0, 0, At, B0); PG8_MMA(0, 1, At, B1); PG8_BAR; PG8_SCHED;
;             PG8_LDA(At, 0, 1); PG8_STAGE(PG8_SB(0, 0), b2, voffB); PG8_STAGE(PG8_SB(0, 1), b2 + hstepB, voffB); PG8_STAGE(PG8_SA(0, 0), a2, voffA);
;             PG8_WAIT_V(8); PG8_WAIT_L(0); PG8_BAR; PG8_MMA(1, 0, At, B0); PG8_MMA(1, 1, At, B1); PG8_BAR; PG8_SCHED;
.LBB0_663:
	s_add_i32 s53, s38, 2
	s_add_u32 s36, s24, 0x100
	s_addc_u32 s37, s25, 0
	s_add_i32 s20, 16, 0x10000
	s_cmp_eq_u32 s48, s38
	s_cselect_b32 s39, s3, s37
	s_cselect_b32 s38, s2, s36
	v_add_u32_e32 v138, s20, v143
	s_cselect_b32 s55, s17, s52
	s_cselect_b32 s54, s16, s34
	s_add_i32 s21, 16, 0x14000
	ds_read_b128 v[152:155], v138
	ds_read_b128 v[156:159], v138 offset:1024
	ds_read_b128 v[160:163], v138 offset:2048
	ds_read_b128 v[164:167], v138 offset:3072
	v_add_u32_e32 v138, s21, v143
	ds_read_b128 v[168:171], v138
	ds_read_b128 v[172:175], v138 offset:1024
	ds_read_b128 v[184:187], v138 offset:2048
	ds_read_b128 v[188:191], v138 offset:3072
	v_lshl_add_u64 v[140:141], s[24:25], 0, v[134:135]
	s_add_i32 m0, s31, 0xc000
	ds_read_b128 v[192:195], v151
	ds_read_b128 v[196:199], v151 offset:1024
	ds_read_b128 v[200:203], v151 offset:2048
	ds_read_b128 v[204:207], v151 offset:3072
	ds_read_b128 v[208:211], v151 offset:4096
	ds_read_b128 v[212:215], v151 offset:5120
	ds_read_b128 v[216:219], v151 offset:6144
	ds_read_b128 v[220:223], v151 offset:7168
	global_load_lds_dwordx4 v[140:141], off
	v_lshl_add_u64 v[140:141], s[24:25], 0, v[136:137]
	s_add_i32 m0, s31, 0xe000
	s_nop 0
	global_load_lds_dwordx4 v[140:141], off
	s_waitcnt vmcnt(8)
	s_waitcnt lgkmcnt(0)
	s_barrier
	s_waitcnt lgkmcnt(0)
	v_mfma_f32_16x16x32_bf16 v[120:123], v[152:155], v[192:195], v[120:123]
	v_mfma_f32_16x16x32_bf16 v[124:127], v[160:163], v[192:195], v[124:127]
	v_mfma_f32_16x16x32_bf16 v[108:111], v[152:155], v[200:203], v[108:111]
	v_mfma_f32_16x16x32_bf16 v[104:107], v[160:163], v[200:203], v[104:107]
	v_mfma_f32_16x16x32_bf16 v[92:95], v[152:155], v[208:211], v[92:95]
	v_mfma_f32_16x16x32_bf16 v[88:91], v[160:163], v[208:211], v[88:91]
	v_mfma_f32_16x16x32_bf16 v[76:79], v[152:155], v[216:219], v[76:79]
	v_mfma_f32_16x16x32_bf16 v[72:75], v[160:163], v[216:219], v[72:75]
	v_mfma_f32_16x16x32_bf16 v[120:123], v[156:159], v[196:199], v[120:123]
	v_mfma_f32_16x16x32_bf16 v[124:127], v[164:167], v[196:199], v[124:127]
	v_mfma_f32_16x16x32_bf16 v[108:111], v[156:159], v[204:207], v[108:111]
	v_mfma_f32_16x16x32_bf16 v[104:107], v[164:167], v[204:207], v[104:107]
	v_mfma_f32_16x16x32_bf16 v[92:95], v[156:159], v[212:215], v[92:95]
	v_mfma_f32_16x16x32_bf16 v[88:91], v[164:167], v[212:215], v[88:91]
	v_mfma_f32_16x16x32_bf16 v[76:79], v[156:159], v[220:223], v[76:79]
	v_mfma_f32_16x16x32_bf16 v[72:75], v[164:167], v[220:223], v[72:75]
	v_mfma_f32_16x16x32_bf16 v[116:119], v[168:171], v[192:195], v[116:119]
	v_mfma_f32_16x16x32_bf16 v[112:115], v[184:187], v[192:195], v[112:115]
	v_mfma_f32_16x16x32_bf16 v[100:103], v[168:171], v[200:203], v[100:103]
	v_mfma_f32_16x16x32_bf16 v[96:99], v[184:187], v[200:203], v[96:99]
	v_mfma_f32_16x16x32_bf16 v[84:87], v[168:171], v[208:211], v[84:87]
	v_mfma_f32_16x16x32_bf16 v[80:83], v[184:187], v[208:211], v[80:83]
	v_mfma_f32_16x16x32_bf16 v[68:71], v[168:171], v[216:219], v[68:71]
	v_mfma_f32_16x16x32_bf16 v[64:67], v[184:187], v[216:219], v[64:67]
	v_mfma_f32_16x16x32_bf16 v[116:119], v[172:175], v[196:199], v[116:119]
	v_mfma_f32_16x16x32_bf16 v[112:115], v[188:191], v[196:199], v[112:115]
	v_mfma_f32_16x16x32_bf16 v[100:103], v[172:175], v[204:207], v[100:103]
	v_mfma_f32_16x16x32_bf16 v[96:99], v[188:191], v[204:207], v[96:99]
	v_mfma_f32_16x16x32_bf16 v[84:87], v[172:175], v[212:215], v[84:87]
	v_mfma_f32_16x16x32_bf16 v[80:83], v[188:191], v[212:215], v[80:83]
	v_mfma_f32_16x16x32_bf16 v[68:71], v[172:175], v[220:223], v[68:71]
	v_mfma_f32_16x16x32_bf16 v[64:67], v[188:191], v[220:223], v[64:67]
	s_barrier
	s_add_i32 s20, s20, s30
	v_lshl_add_u64 v[140:141], s[54:55], 0, v[176:177]
	s_mov_b32 m0, s20
	ds_read_b128 v[192:195], v151 offset:16384
	ds_read_b128 v[196:199], v151 offset:17408
	ds_read_b128 v[200:203], v151 offset:18432
	ds_read_b128 v[204:207], v151 offset:19456
	ds_read_b128 v[208:211], v151 offset:20480
	ds_read_b128 v[212:215], v151 offset:21504
	ds_read_b128 v[216:219], v151 offset:22528
	ds_read_b128 v[220:223], v151 offset:23552
	global_load_lds_dwordx4 v[140:141], off
	s_add_i32 m0, s20, 0x2000
	s_add_u32 s24, s54, s6
	v_lshl_add_u64 v[144:145], s[54:55], 0, v[128:129]
	s_addc_u32 s25, s55, s7
	s_add_i32 s20, s21, s30
	global_load_lds_dwordx4 v[144:145], off
	v_lshl_add_u64 v[148:149], s[24:25], 0, v[176:177]
	s_mov_b32 m0, s20
	v_lshl_add_u64 v[224:225], s[24:25], 0, v[128:129]
	global_load_lds_dwordx4 v[148:149], off
	s_add_i32 m0, s20, 0x2000
	v_lshl_add_u64 v[226:227], s[38:39], 0, v[132:133]
	global_load_lds_dwordx4 v[224:225], off
	s_mov_b32 m0, s31
	v_lshl_add_u64 v[228:229], s[38:39], 0, v[130:131]
	global_load_lds_dwordx4 v[226:227], off
	s_mov_b32 m0, s40
	s_nop 0
	global_load_lds_dwordx4 v[228:229], off
	s_waitcnt vmcnt(8)
	s_waitcnt lgkmcnt(0)
	s_barrier
; #define PG8_STAGE(bufoff, gbase, voff) do { _Pragma("unroll") for (int _i = 0; _i < 2; ++_i) \
;         __builtin_amdgcn_global_load_lds((const unsigned*)((const char*)(gbase) + (voff)[_i]), (LAS unsigned*)(lds + (bufoff) + ldsw + _i * 8192), 16, 0, 0); } while (0)
; #define PG8_LDA(dst, b, h) do { _Pragma("unroll") for (int m = 0; m < 4; ++m) _Pragma("unroll") for (int k = 0; k < 2; ++k) dst[m][k] = *(const LAS bf16x8*)(lds + PG8_SA(b, h) + aoff + m * 2048 + k * 1024); } while (0)
; #define PG8_LDB(dst, b, h) do { _Pragma("unroll") for (int n = 0; n < 2; ++n) _Pragma("unroll") for (int k = 0; k < 2; ++k) dst[n][k] = *(const LAS bf16x8*)(lds + PG8_SB(b, h) + boff + n * 2048 + k * 1024); } while (0)
; #define PG8_MMA(ai, bj, At, Bt) do { __builtin_amdgcn_s_setprio(1); _Pragma("unroll") for (int m = 0; m < 4; ++m) _Pragma("unroll") for (int n = 0; n < 2; ++n) _Pragma("unroll") for (int k = 0; k < 2; ++k) \
;         acc[ai][bj][m][n] = __builtin_amdgcn_mfma_f32_16x16x32_bf16(Bt[n][k], At[m][k], acc[ai][bj][m][n], 0, 0, 0); __builtin_amdgcn_s_setprio(0); } while (0)
; #define PG8_WAIT_V(n) asm volatile("s_waitcnt vmcnt(" #n ")" ::: "memory")
; #define PG8_WAIT_L(n) asm volatile("s_waitcnt lgkmcnt(" #n ")" ::: "memory")
; #define PG8_BAR __builtin_amdgcn_s_barrier()
; #define PG8_SCHED __builtin_amdgcn_sched_barrier(0)
; template <class Epi, bool ALIGN_EPI = PG8_ALIGN>
; __device__ __forceinline__ void gemm_phase(LAS unsigned char* lds, const Gemm g, const StaticOrder& S, const Epi& E) {
;     ...
;             PG8_WAIT_V(8); PG8_WAIT_L(0); PG8_BAR; PG8_MMA(1, 0, At, B0); PG8_MMA(1, 1, At, B1); PG8_BAR; PG8_SCHED;
;             PG8_LDB(B0, 1, 0); PG8_LDB(B1, 1, 1); PG8_SCHED; PG8_LDA(At, 1, 0); PG8_STAGE(PG8_SA(0, 1), a2 + hstepA, voffA);
;             PG8_WAIT_V(8); PG8_WAIT_L(0); PG8_BAR; PG8_MMA(0, 0, At, B0); PG8_MMA(0, 1, At, B1); PG8_BAR; PG8_SCHED;
	s_waitcnt lgkmcnt(0)
	v_mfma_f32_16x16x32_bf16 v[60:63], v[152:155], v[192:195], v[60:63]
	v_mfma_f32_16x16x32_bf16 v[56:59], v[160:163], v[192:195], v[56:59]
	v_mfma_f32_16x16x32_bf16 v[44:47], v[152:155], v[200:203], v[44:47]
	v_mfma_f32_16x16x32_bf16 v[40:43], v[160:163], v[200:203], v[40:43]
	v_mfma_f32_16x16x32_bf16 v[28:31], v[152:155], v[208:211], v[28:31]
	v_mfma_f32_16x16x32_bf16 v[24:27], v[160:163], v[208:211], v[24:27]
	v_mfma_f32_16x16x32_bf16 v[12:15], v[152:155], v[216:219], v[12:15]
	v_mfma_f32_16x16x32_bf16 v[8:11], v[160:163], v[216:219], v[8:11]
	v_mfma_f32_16x16x32_bf16 v[60:63], v[156:159], v[196:199], v[60:63]
	v_mfma_f32_16x16x32_bf16 v[56:59], v[164:167], v[196:199], v[56:59]
	v_mfma_f32_16x16x32_bf16 v[44:47], v[156:159], v[204:207], v[44:47]
	v_mfma_f32_16x16x32_bf16 v[40:43], v[164:167], v[204:207], v[40:43]
	v_mfma_f32_16x16x32_bf16 v[28:31], v[156:159], v[212:215], v[28:31]
	v_mfma_f32_16x16x32_bf16 v[24:27], v[164:167], v[212:215], v[24:27]
	v_mfma_f32_16x16x32_bf16 v[12:15], v[156:159], v[220:223], v[12:15]
	v_mfma_f32_16x16x32_bf16 v[8:11], v[164:167], v[220:223], v[8:11]
	v_mfma_f32_16x16x32_bf16 v[52:55], v[168:171], v[192:195], v[52:55]
	v_mfma_f32_16x16x32_bf16 v[48:51], v[184:187], v[192:195], v[48:51]
	v_mfma_f32_16x16x32_bf16 v[36:39], v[168:171], v[200:203], v[36:39]
	v_mfma_f32_16x16x32_bf16 v[32:35], v[184:187], v[200:203], v[32:35]
	v_mfma_f32_16x16x32_bf16 v[20:23], v[168:171], v[208:211], v[20:23]
	v_mfma_f32_16x16x32_bf16 v[16:19], v[184:187], v[208:211], v[16:19]
	v_mfma_f32_16x16x32_bf16 v[4:7], v[168:171], v[216:219], v[4:7]
	v_mfma_f32_16x16x32_bf16 v[0:3], v[184:187], v[216:219], v[0:3]
	v_mfma_f32_16x16x32_bf16 v[52:55], v[172:175], v[196:199], v[52:55]
	v_mfma_f32_16x16x32_bf16 v[48:51], v[188:191], v[196:199], v[48:51]
	v_mfma_f32_16x16x32_bf16 v[36:39], v[172:175], v[204:207], v[36:39]
	v_mfma_f32_16x16x32_bf16 v[32:35], v[188:191], v[204:207], v[32:35]
	v_mfma_f32_16x16x32_bf16 v[20:23], v[172:175], v[212:215], v[20:23]
	v_mfma_f32_16x16x32_bf16 v[16:19], v[188:191], v[212:215], v[16:19]
	v_mfma_f32_16x16x32_bf16 v[4:7], v[172:175], v[220:223], v[4:7]
	v_mfma_f32_16x16x32_bf16 v[0:3], v[188:191], v[220:223], v[0:3]
	s_barrier
	s_add_i32 s20, 16, 0x18000
	v_add_u32_e32 v138, s20, v143
	s_add_i32 s21, 16, 0x1c000
	ds_read_b128 v[152:155], v138
	ds_read_b128 v[156:159], v138 offset:1024
	ds_read_b128 v[160:163], v138 offset:2048
	ds_read_b128 v[164:167], v138 offset:3072
	v_add_u32_e32 v138, s21, v143
	ds_read_b128 v[168:171], v138
	ds_read_b128 v[172:175], v138 offset:1024
	ds_read_b128 v[184:187], v138 offset:2048
	ds_read_b128 v[188:191], v138 offset:3072
	s_add_u32 s24, s38, 0x110000
	s_addc_u32 s25, s39, 0
	s_mov_b32 m0, s41
	v_lshl_add_u64 v[230:231], s[24:25], 0, v[132:133]
	ds_read_b128 v[192:195], v151 offset:32768
	ds_read_b128 v[196:199], v151 offset:33792
	ds_read_b128 v[200:203], v151 offset:34816
	ds_read_b128 v[204:207], v151 offset:35840
	ds_read_b128 v[208:211], v151 offset:36864
	ds_read_b128 v[212:215], v151 offset:37888
	ds_read_b128 v[216:219], v151 offset:38912
	ds_read_b128 v[220:223], v151 offset:39936
	global_load_lds_dwordx4 v[230:231], off
	v_lshl_add_u64 v[230:231], s[24:25], 0, v[130:131]
	s_mov_b32 m0, s44
	s_nop 0
	global_load_lds_dwordx4 v[230:231], off
	s_waitcnt vmcnt(8)
	s_waitcnt lgkmcnt(0)
	s_barrier
	s_waitcnt lgkmcnt(0)
	v_mfma_f32_16x16x32_bf16 v[120:123], v[152:155], v[192:195], v[120:123]
	v_mfma_f32_16x16x32_bf16 v[124:127], v[160:163], v[192:195], v[124:127]
	v_mfma_f32_16x16x32_bf16 v[108:111], v[152:155], v[200:203], v[108:111]
	v_mfma_f32_16x16x32_bf16 v[104:107], v[160:163], v[200:203], v[104:107]
	v_mfma_f32_16x16x32_bf16 v[92:95], v[152:155], v[208:211], v[92:95]
	v_mfma_f32_16x16x32_bf16 v[88:91], v[160:163], v[208:211], v[88:91]
	v_mfma_f32_16x16x32_bf16 v[76:79], v[152:155], v[216:219], v[76:79]
	v_mfma_f32_16x16x32_bf16 v[72:75], v[160:163], v[216:219], v[72:75]
	v_mfma_f32_16x16x32_bf16 v[120:123], v[156:159], v[196:199], v[120:123]
	v_mfma_f32_16x16x32_bf16 v[124:127], v[164:167], v[196:199], v[124:127]
	v_mfma_f32_16x16x32_bf16 v[108:111], v[156:159], v[204:207], v[108:111]
	v_mfma_f32_16x16x32_bf16 v[104:107], v[164:167], v[204:207], v[104:107]
	v_mfma_f32_16x16x32_bf16 v[92:95], v[156:159], v[212:215], v[92:95]
	v_mfma_f32_16x16x32_bf16 v[88:91], v[164:167], v[212:215], v[88:91]
	v_mfma_f32_16x16x32_bf16 v[76:79], v[156:159], v[220:223], v[76:79]
	v_mfma_f32_16x16x32_bf16 v[72:75], v[164:167], v[220:223], v[72:75]
	v_mfma_f32_16x16x32_bf16 v[116:119], v[168:171], v[192:195], v[116:119]
	v_mfma_f32_16x16x32_bf16 v[112:115], v[184:187], v[192:195], v[112:115]
	v_mfma_f32_16x16x32_bf16 v[100:103], v[168:171], v[200:203], v[100:103]
	v_mfma_f32_16x16x32_bf16 v[96:99], v[184:187], v[200:203], v[96:99]
	v_mfma_f32_16x16x32_bf16 v[84:87], v[168:171], v[208:211], v[84:87]
	v_mfma_f32_16x16x32_bf16 v[80:83], v[184:187], v[208:211], v[80:83]
	v_mfma_f32_16x16x32_bf16 v[68:71], v[168:171], v[216:219], v[68:71]
	v_mfma_f32_16x16x32_bf16 v[64:67], v[184:187], v[216:219], v[64:67]
	v_mfma_f32_16x16x32_bf16 v[116:119], v[172:175], v[196:199], v[116:119]
	v_mfma_f32_16x16x32_bf16 v[112:115], v[188:191], v[196:199], v[112:115]
	v_mfma_f32_16x16x32_bf16 v[100:103], v[172:175], v[204:207], v[100:103]
	v_mfma_f32_16x16x32_bf16 v[96:99], v[188:191], v[204:207], v[96:99]
	v_mfma_f32_16x16x32_bf16 v[84:87], v[172:175], v[212:215], v[84:87]
	v_mfma_f32_16x16x32_bf16 v[80:83], v[188:191], v[212:215], v[80:83]
	v_mfma_f32_16x16x32_bf16 v[68:71], v[172:175], v[220:223], v[68:71]
	v_mfma_f32_16x16x32_bf16 v[64:67], v[188:191], v[220:223], v[64:67]
	s_barrier
; #define PG8_STAGE(bufoff, gbase, voff) do { _Pragma("unroll") for (int _i = 0; _i < 2; ++_i) \
;         __builtin_amdgcn_global_load_lds((const unsigned*)((const char*)(gbase) + (voff)[_i]), (LAS unsigned*)(lds + (bufoff) + ldsw + _i * 8192), 16, 0, 0); } while (0)
; #define PG8_LDA(dst, b, h) do { _Pragma("unroll") for (int m = 0; m < 4; ++m) _Pragma("unroll") for (int k = 0; k < 2; ++k) dst[m][k] = *(const LAS bf16x8*)(lds + PG8_SA(b, h) + aoff + m * 2048 + k * 1024); } while (0)
; #define PG8_MMA(ai, bj, At, Bt) do { __builtin_amdgcn_s_setprio(1); _Pragma("unroll") for (int m = 0; m < 4; ++m) _Pragma("unroll") for (int n = 0; n < 2; ++n) _Pragma("unroll") for (int k = 0; k < 2; ++k) \
;         acc[ai][bj][m][n] = __builtin_amdgcn_mfma_f32_16x16x32_bf16(Bt[n][k], At[m][k], acc[ai][bj][m][n], 0, 0, 0); __builtin_amdgcn_s_setprio(0); } while (0)
; #define PG8_WAIT_V(n) asm volatile("s_waitcnt vmcnt(" #n ")" ::: "memory")
; #define PG8_WAIT_L(n) asm volatile("s_waitcnt lgkmcnt(" #n ")" ::: "memory")
; #define PG8_BAR __builtin_amdgcn_s_barrier()
; #define PG8_SCHED __builtin_amdgcn_sched_barrier(0)
; template <class Epi, bool ALIGN_EPI = PG8_ALIGN>
; __device__ __forceinline__ void gemm_phase(LAS unsigned char* lds, const Gemm g, const StaticOrder& S, const Epi& E) {
;     ...
;             PG8_LDA(At, 1, 1); PG8_STAGE(PG8_SB(1, 0), b3, voffB); PG8_STAGE(PG8_SB(1, 1), b3 + hstepB, voffB); PG8_STAGE(PG8_SA(1, 0), a3, voffA);
;             PG8_WAIT_V(8); PG8_WAIT_L(0); PG8_BAR; PG8_MMA(1, 0, At, B0); PG8_MMA(1, 1, At, B1); PG8_BAR; PG8_SCHED;
;         }
	s_add_i32 s20, s20, s30
	v_lshl_add_u64 v[140:141], v[140:141], 0, s[0:1]
	s_mov_b32 m0, s20
	ds_read_b128 v[192:195], v151 offset:49152
	ds_read_b128 v[196:199], v151 offset:50176
	ds_read_b128 v[200:203], v151 offset:51200
	ds_read_b128 v[204:207], v151 offset:52224
	ds_read_b128 v[208:211], v151 offset:53248
	ds_read_b128 v[212:215], v151 offset:54272
	ds_read_b128 v[216:219], v151 offset:55296
	ds_read_b128 v[220:223], v151 offset:56320
	global_load_lds_dwordx4 v[140:141], off
	v_lshl_add_u64 v[140:141], v[144:145], 0, s[0:1]
	s_add_i32 m0, s20, 0x2000
	s_add_i32 s20, s21, s30
	global_load_lds_dwordx4 v[140:141], off
	v_lshl_add_u64 v[140:141], v[148:149], 0, s[0:1]
	s_mov_b32 m0, s20
	s_nop 0
	global_load_lds_dwordx4 v[140:141], off
	v_lshl_add_u64 v[140:141], v[224:225], 0, s[0:1]
	s_add_i32 m0, s20, 0x2000
	s_nop 0
	global_load_lds_dwordx4 v[140:141], off
	v_lshl_add_u64 v[140:141], v[226:227], 0, s[0:1]
	s_mov_b32 m0, s45
	s_nop 0
	global_load_lds_dwordx4 v[140:141], off
	v_lshl_add_u64 v[140:141], v[228:229], 0, s[0:1]
	s_mov_b32 m0, s46
	s_nop 0
	global_load_lds_dwordx4 v[140:141], off
	s_waitcnt vmcnt(8)
	s_waitcnt lgkmcnt(0)
	s_barrier
	s_waitcnt lgkmcnt(0)
	v_mfma_f32_16x16x32_bf16 v[60:63], v[152:155], v[192:195], v[60:63]
	v_mfma_f32_16x16x32_bf16 v[56:59], v[160:163], v[192:195], v[56:59]
	v_mfma_f32_16x16x32_bf16 v[44:47], v[152:155], v[200:203], v[44:47]
	v_mfma_f32_16x16x32_bf16 v[40:43], v[160:163], v[200:203], v[40:43]
	v_mfma_f32_16x16x32_bf16 v[28:31], v[152:155], v[208:211], v[28:31]
	v_mfma_f32_16x16x32_bf16 v[24:27], v[160:163], v[208:211], v[24:27]
	v_mfma_f32_16x16x32_bf16 v[12:15], v[152:155], v[216:219], v[12:15]
	v_mfma_f32_16x16x32_bf16 v[8:11], v[160:163], v[216:219], v[8:11]
	v_mfma_f32_16x16x32_bf16 v[60:63], v[156:159], v[196:199], v[60:63]
	v_mfma_f32_16x16x32_bf16 v[56:59], v[164:167], v[196:199], v[56:59]
	v_mfma_f32_16x16x32_bf16 v[44:47], v[156:159], v[204:207], v[44:47]
	v_mfma_f32_16x16x32_bf16 v[40:43], v[164:167], v[204:207], v[40:43]
	v_mfma_f32_16x16x32_bf16 v[28:31], v[156:159], v[212:215], v[28:31]
	v_mfma_f32_16x16x32_bf16 v[24:27], v[164:167], v[212:215], v[24:27]
	v_mfma_f32_16x16x32_bf16 v[12:15], v[156:159], v[220:223], v[12:15]
	v_mfma_f32_16x16x32_bf16 v[8:11], v[164:167], v[220:223], v[8:11]
	v_mfma_f32_16x16x32_bf16 v[52:55], v[168:171], v[192:195], v[52:55]
	v_mfma_f32_16x16x32_bf16 v[48:51], v[184:187], v[192:195], v[48:51]
	v_mfma_f32_16x16x32_bf16 v[36:39], v[168:171], v[200:203], v[36:39]
	v_mfma_f32_16x16x32_bf16 v[32:35], v[184:187], v[200:203], v[32:35]
	v_mfma_f32_16x16x32_bf16 v[20:23], v[168:171], v[208:211], v[20:23]
	v_mfma_f32_16x16x32_bf16 v[16:19], v[184:187], v[208:211], v[16:19]
	v_mfma_f32_16x16x32_bf16 v[4:7], v[168:171], v[216:219], v[4:7]
	v_mfma_f32_16x16x32_bf16 v[0:3], v[184:187], v[216:219], v[0:3]
	v_mfma_f32_16x16x32_bf16 v[52:55], v[172:175], v[196:199], v[52:55]
	v_mfma_f32_16x16x32_bf16 v[48:51], v[188:191], v[196:199], v[48:51]
	v_mfma_f32_16x16x32_bf16 v[36:39], v[172:175], v[204:207], v[36:39]
	v_mfma_f32_16x16x32_bf16 v[32:35], v[188:191], v[204:207], v[32:35]
	v_mfma_f32_16x16x32_bf16 v[20:23], v[172:175], v[212:215], v[20:23]
	v_mfma_f32_16x16x32_bf16 v[16:19], v[188:191], v[212:215], v[16:19]
	v_mfma_f32_16x16x32_bf16 v[4:7], v[172:175], v[220:223], v[4:7]
	v_mfma_f32_16x16x32_bf16 v[0:3], v[188:191], v[220:223], v[0:3]
	s_barrier
	s_add_u32 s34, s34, 0x100
	s_addc_u32 s52, s52, 0
	s_cmp_ge_i32 s53, s47
	s_mov_b64 s[24:25], s[36:37]
	s_mov_b32 s38, s53
	s_cbranch_scc0 .LBB0_663

; #define PG8_STAGE(bufoff, gbase, voff) do { _Pragma("unroll") for (int _i = 0; _i < 2; ++_i) \
;         __builtin_amdgcn_global_load_lds((const unsigned*)((const char*)(gbase) + (voff)[_i]), (LAS unsigned*)(lds + (bufoff) + ldsw + _i * 8192), 16, 0, 0); } while (0)
; #define PG8_LDA(dst, b, h) do { _Pragma("unroll") for (int m = 0; m < 4; ++m) _Pragma("unroll") for (int k = 0; k < 2; ++k) dst[m][k] = *(const LAS bf16x8*)(lds + PG8_SA(b, h) + aoff + m * 2048 + k * 1024); } while (0)
; #define PG8_LDB(dst, b, h) do { _Pragma("unroll") for (int n = 0; n < 2; ++n) _Pragma("unroll") for (int k = 0; k < 2; ++k) dst[n][k] = *(const LAS bf16x8*)(lds + PG8_SB(b, h) + boff + n * 2048 + k * 1024); } while (0)
; #define PG8_MMA(ai, bj, At, Bt) do { __builtin_amdgcn_s_setprio(1); _Pragma("unroll") for (int m = 0; m < 4; ++m) _Pragma("unroll") for (int n = 0; n < 2; ++n) _Pragma("unroll") for (int k = 0; k < 2; ++k) \
;         acc[ai][bj][m][n] = __builtin_amdgcn_mfma_f32_16x16x32_bf16(Bt[n][k], At[m][k], acc[ai][bj][m][n], 0, 0, 0); __builtin_amdgcn_s_setprio(0); } while (0)
; #define PG8_WAIT_V(n) asm volatile("s_waitcnt vmcnt(" #n ")" ::: "memory")
; #define PG8_WAIT_L(n) asm volatile("s_waitcnt lgkmcnt(" #n ")" ::: "memory")
; #define PG8_BAR __builtin_amdgcn_s_barrier()
; #define PG8_SCHED __builtin_amdgcn_sched_barrier(0)
; template <class Epi, bool ALIGN_EPI = PG8_ALIGN>
; __device__ __forceinline__ void gemm_phase(LAS unsigned char* lds, const Gemm g, const StaticOrder& S, const Epi& E) {
;     ...
;         for (int t = 0; t < nt; t += 2) {
;             const bool last = (t == nt - 2);
;             const char* a1 = cA + (size_t)(t + 1) * kstep;
;             const char* a2 = last ? nA : cA + (size_t)(t + 2) * kstep; const char* b2 = last ? nB : cB + (size_t)(t + 2) * kstep;
;             const char* a3 = a2 + kstep; const char* b3 = b2 + kstep;
;             PG8_LDB(B0, 0, 0); PG8_LDB(B1, 0, 1); PG8_SCHED; PG8_LDA(At, 0, 0); PG8_STAGE(PG8_SA(1, 1), a1 + hstepA, voffA);
;             PG8_WAIT_V(8); PG8_WAIT_L(0); PG8_BAR; PG8_MMA(0, 0, At, B0); PG8_MMA(0, 1, At, B1); PG8_BAR; PG8_SCHED;
;             PG8_LDA(At, 0, 1); PG8_STAGE(PG8_SB(0, 0), b2, voffB); PG8_STAGE(PG8_SB(0, 1), b2 + hstepB, voffB); PG8_STAGE(PG8_SA(0, 0), a2, voffA);
;             PG8_WAIT_V(8); PG8_WAIT_L(0); PG8_BAR; PG8_MMA(1, 0, At, B0); PG8_MMA(1, 1, At, B1); PG8_BAR; PG8_SCHED;
.LBB0_901:
	s_add_i32 s53, s40, 2
	s_add_u32 s20, s4, 0xfff80080
	s_addc_u32 s21, s5, -1
	s_add_i32 s22, 16, 0x10000
	s_cmp_eq_u32 s47, s40
	s_cselect_b32 s41, s25, s21
	s_cselect_b32 s40, s52, s20
	s_cselect_b32 s21, s37, s43
	s_cselect_b32 s20, s36, s42
	s_add_i32 s23, 16, 0x14000
	v_add_u32_e32 v154, s22, v139
	v_add_u32_e32 v170, s23, v139
	ds_read_b128 v[142:145], v154
	ds_read_b128 v[146:149], v154 offset:1024
	ds_read_b128 v[150:153], v154 offset:2048
	ds_read_b128 v[154:157], v154 offset:3072
	ds_read_b128 v[158:161], v170
	ds_read_b128 v[162:165], v170 offset:1024
	ds_read_b128 v[166:169], v170 offset:2048
	ds_read_b128 v[170:173], v170 offset:3072
	v_lshl_add_u64 v[174:175], s[4:5], 0, v[134:135]
	s_add_i32 m0, s29, 0xc000
	ds_read_b128 v[184:187], v141
	ds_read_b128 v[188:191], v141 offset:1024
	ds_read_b128 v[192:195], v141 offset:2048
	ds_read_b128 v[196:199], v141 offset:3072
	ds_read_b128 v[200:203], v141 offset:4096
	ds_read_b128 v[204:207], v141 offset:5120
	ds_read_b128 v[208:211], v141 offset:6144
	ds_read_b128 v[212:215], v141 offset:7168
	global_load_lds_dwordx4 v[174:175], off
	v_lshl_add_u64 v[174:175], s[4:5], 0, v[136:137]
	s_add_i32 m0, s29, 0xe000
	s_nop 0
	global_load_lds_dwordx4 v[174:175], off
	s_waitcnt vmcnt(8)
	s_waitcnt lgkmcnt(0)
	s_barrier
	s_waitcnt lgkmcnt(0)
	v_mfma_f32_16x16x32_bf16 v[120:123], v[142:145], v[184:187], v[120:123]
	v_mfma_f32_16x16x32_bf16 v[124:127], v[150:153], v[184:187], v[124:127]
	v_mfma_f32_16x16x32_bf16 v[108:111], v[142:145], v[192:195], v[108:111]
	v_mfma_f32_16x16x32_bf16 v[104:107], v[150:153], v[192:195], v[104:107]
	v_mfma_f32_16x16x32_bf16 v[92:95], v[142:145], v[200:203], v[92:95]
	v_mfma_f32_16x16x32_bf16 v[88:91], v[150:153], v[200:203], v[88:91]
	v_mfma_f32_16x16x32_bf16 v[76:79], v[142:145], v[208:211], v[76:79]
	v_mfma_f32_16x16x32_bf16 v[72:75], v[150:153], v[208:211], v[72:75]
	v_mfma_f32_16x16x32_bf16 v[120:123], v[146:149], v[188:191], v[120:123]
	v_mfma_f32_16x16x32_bf16 v[124:127], v[154:157], v[188:191], v[124:127]
	v_mfma_f32_16x16x32_bf16 v[108:111], v[146:149], v[196:199], v[108:111]
	v_mfma_f32_16x16x32_bf16 v[104:107], v[154:157], v[196:199], v[104:107]
	v_mfma_f32_16x16x32_bf16 v[92:95], v[146:149], v[204:207], v[92:95]
	v_mfma_f32_16x16x32_bf16 v[88:91], v[154:157], v[204:207], v[88:91]
	v_mfma_f32_16x16x32_bf16 v[76:79], v[146:149], v[212:215], v[76:79]
	v_mfma_f32_16x16x32_bf16 v[72:75], v[154:157], v[212:215], v[72:75]
	v_mfma_f32_16x16x32_bf16 v[116:119], v[158:161], v[184:187], v[116:119]
	v_mfma_f32_16x16x32_bf16 v[112:115], v[166:169], v[184:187], v[112:115]
	v_mfma_f32_16x16x32_bf16 v[100:103], v[158:161], v[192:195], v[100:103]
	v_mfma_f32_16x16x32_bf16 v[96:99], v[166:169], v[192:195], v[96:99]
	v_mfma_f32_16x16x32_bf16 v[84:87], v[158:161], v[200:203], v[84:87]
	v_mfma_f32_16x16x32_bf16 v[80:83], v[166:169], v[200:203], v[80:83]
	v_mfma_f32_16x16x32_bf16 v[68:71], v[158:161], v[208:211], v[68:71]
	v_mfma_f32_16x16x32_bf16 v[64:67], v[166:169], v[208:211], v[64:67]
	v_mfma_f32_16x16x32_bf16 v[116:119], v[162:165], v[188:191], v[116:119]
	v_mfma_f32_16x16x32_bf16 v[112:115], v[170:173], v[188:191], v[112:115]
	v_mfma_f32_16x16x32_bf16 v[100:103], v[162:165], v[196:199], v[100:103]
	v_mfma_f32_16x16x32_bf16 v[96:99], v[170:173], v[196:199], v[96:99]
	v_mfma_f32_16x16x32_bf16 v[84:87], v[162:165], v[204:207], v[84:87]
	v_mfma_f32_16x16x32_bf16 v[80:83], v[170:173], v[204:207], v[80:83]
	v_mfma_f32_16x16x32_bf16 v[68:71], v[162:165], v[212:215], v[68:71]
	v_mfma_f32_16x16x32_bf16 v[64:67], v[170:173], v[212:215], v[64:67]
	s_barrier
	s_add_i32 s22, s22, s18
	v_lshl_add_u64 v[174:175], s[20:21], 0, v[176:177]
	s_mov_b32 m0, s22
	ds_read_b128 v[184:187], v141 offset:16384
	ds_read_b128 v[188:191], v141 offset:17408
	ds_read_b128 v[192:195], v141 offset:18432
	ds_read_b128 v[196:199], v141 offset:19456
	ds_read_b128 v[200:203], v141 offset:20480
	ds_read_b128 v[204:207], v141 offset:21504
	ds_read_b128 v[208:211], v141 offset:22528
	ds_read_b128 v[212:215], v141 offset:23552
	global_load_lds_dwordx4 v[174:175], off
	s_add_i32 m0, s22, 0x2000
	v_lshl_add_u64 v[180:181], s[20:21], 0, v[128:129]
	s_add_u32 s20, s20, s8
	s_addc_u32 s21, s21, s9
	s_add_i32 s22, s23, s18
	global_load_lds_dwordx4 v[180:181], off
	v_lshl_add_u64 v[182:183], s[20:21], 0, v[176:177]
	s_mov_b32 m0, s22
	v_lshl_add_u64 v[216:217], s[20:21], 0, v[128:129]
	global_load_lds_dwordx4 v[182:183], off
	s_add_i32 m0, s22, 0x2000
	v_lshl_add_u64 v[218:219], s[40:41], 0, v[132:133]
	global_load_lds_dwordx4 v[216:217], off
	s_mov_b32 m0, s29
	v_lshl_add_u64 v[220:221], s[40:41], 0, v[130:131]
	global_load_lds_dwordx4 v[218:219], off
	s_mov_b32 m0, s30
	s_nop 0
	global_load_lds_dwordx4 v[220:221], off
	s_waitcnt vmcnt(8)
	s_waitcnt lgkmcnt(0)
	s_barrier
; #define PG8_STAGE(bufoff, gbase, voff) do { _Pragma("unroll") for (int _i = 0; _i < 2; ++_i) \
;         __builtin_amdgcn_global_load_lds((const unsigned*)((const char*)(gbase) + (voff)[_i]), (LAS unsigned*)(lds + (bufoff) + ldsw + _i * 8192), 16, 0, 0); } while (0)
; #define PG8_LDA(dst, b, h) do { _Pragma("unroll") for (int m = 0; m < 4; ++m) _Pragma("unroll") for (int k = 0; k < 2; ++k) dst[m][k] = *(const LAS bf16x8*)(lds + PG8_SA(b, h) + aoff + m * 2048 + k * 1024); } while (0)
; #define PG8_LDB(dst, b, h) do { _Pragma("unroll") for (int n = 0; n < 2; ++n) _Pragma("unroll") for (int k = 0; k < 2; ++k) dst[n][k] = *(const LAS bf16x8*)(lds + PG8_SB(b, h) + boff + n * 2048 + k * 1024); } while (0)
; #define PG8_MMA(ai, bj, At, Bt) do { __builtin_amdgcn_s_setprio(1); _Pragma("unroll") for (int m = 0; m < 4; ++m) _Pragma("unroll") for (int n = 0; n < 2; ++n) _Pragma("unroll") for (int k = 0; k < 2; ++k) \
;         acc[ai][bj][m][n] = __builtin_amdgcn_mfma_f32_16x16x32_bf16(Bt[n][k], At[m][k], acc[ai][bj][m][n], 0, 0, 0); __builtin_amdgcn_s_setprio(0); } while (0)
; #define PG8_WAIT_V(n) asm volatile("s_waitcnt vmcnt(" #n ")" ::: "memory")
; #define PG8_WAIT_L(n) asm volatile("s_waitcnt lgkmcnt(" #n ")" ::: "memory")
; #define PG8_BAR __builtin_amdgcn_s_barrier()
; #define PG8_SCHED __builtin_amdgcn_sched_barrier(0)
; template <class Epi, bool ALIGN_EPI = PG8_ALIGN>
; __device__ __forceinline__ void gemm_phase(LAS unsigned char* lds, const Gemm g, const StaticOrder& S, const Epi& E) {
;     ...
;             PG8_WAIT_V(8); PG8_WAIT_L(0); PG8_BAR; PG8_MMA(1, 0, At, B0); PG8_MMA(1, 1, At, B1); PG8_BAR; PG8_SCHED;
;             PG8_LDB(B0, 1, 0); PG8_LDB(B1, 1, 1); PG8_SCHED; PG8_LDA(At, 1, 0); PG8_STAGE(PG8_SA(0, 1), a2 + hstepA, voffA);
;             PG8_WAIT_V(8); PG8_WAIT_L(0); PG8_BAR; PG8_MMA(0, 0, At, B0); PG8_MMA(0, 1, At, B1); PG8_BAR; PG8_SCHED;
	s_waitcnt lgkmcnt(0)
	v_mfma_f32_16x16x32_bf16 v[60:63], v[142:145], v[184:187], v[60:63]
	v_mfma_f32_16x16x32_bf16 v[56:59], v[150:153], v[184:187], v[56:59]
	v_mfma_f32_16x16x32_bf16 v[44:47], v[142:145], v[192:195], v[44:47]
	v_mfma_f32_16x16x32_bf16 v[40:43], v[150:153], v[192:195], v[40:43]
	v_mfma_f32_16x16x32_bf16 v[28:31], v[142:145], v[200:203], v[28:31]
	v_mfma_f32_16x16x32_bf16 v[24:27], v[150:153], v[200:203], v[24:27]
	v_mfma_f32_16x16x32_bf16 v[12:15], v[142:145], v[208:211], v[12:15]
	v_mfma_f32_16x16x32_bf16 v[8:11], v[150:153], v[208:211], v[8:11]
	v_mfma_f32_16x16x32_bf16 v[60:63], v[146:149], v[188:191], v[60:63]
	v_mfma_f32_16x16x32_bf16 v[56:59], v[154:157], v[188:191], v[56:59]
	v_mfma_f32_16x16x32_bf16 v[44:47], v[146:149], v[196:199], v[44:47]
	v_mfma_f32_16x16x32_bf16 v[40:43], v[154:157], v[196:199], v[40:43]
	v_mfma_f32_16x16x32_bf16 v[28:31], v[146:149], v[204:207], v[28:31]
	v_mfma_f32_16x16x32_bf16 v[24:27], v[154:157], v[204:207], v[24:27]
	v_mfma_f32_16x16x32_bf16 v[12:15], v[146:149], v[212:215], v[12:15]
	v_mfma_f32_16x16x32_bf16 v[8:11], v[154:157], v[212:215], v[8:11]
	v_mfma_f32_16x16x32_bf16 v[52:55], v[158:161], v[184:187], v[52:55]
	v_mfma_f32_16x16x32_bf16 v[48:51], v[166:169], v[184:187], v[48:51]
	v_mfma_f32_16x16x32_bf16 v[36:39], v[158:161], v[192:195], v[36:39]
	v_mfma_f32_16x16x32_bf16 v[32:35], v[166:169], v[192:195], v[32:35]
	v_mfma_f32_16x16x32_bf16 v[20:23], v[158:161], v[200:203], v[20:23]
	v_mfma_f32_16x16x32_bf16 v[16:19], v[166:169], v[200:203], v[16:19]
	v_mfma_f32_16x16x32_bf16 v[4:7], v[158:161], v[208:211], v[4:7]
	v_mfma_f32_16x16x32_bf16 v[0:3], v[166:169], v[208:211], v[0:3]
	v_mfma_f32_16x16x32_bf16 v[52:55], v[162:165], v[188:191], v[52:55]
	v_mfma_f32_16x16x32_bf16 v[48:51], v[170:173], v[188:191], v[48:51]
	v_mfma_f32_16x16x32_bf16 v[36:39], v[162:165], v[196:199], v[36:39]
	v_mfma_f32_16x16x32_bf16 v[32:35], v[170:173], v[196:199], v[32:35]
	v_mfma_f32_16x16x32_bf16 v[20:23], v[162:165], v[204:207], v[20:23]
	v_mfma_f32_16x16x32_bf16 v[16:19], v[170:173], v[204:207], v[16:19]
	v_mfma_f32_16x16x32_bf16 v[4:7], v[162:165], v[212:215], v[4:7]
	v_mfma_f32_16x16x32_bf16 v[0:3], v[170:173], v[212:215], v[0:3]
	s_barrier
	s_add_i32 s22, 16, 0x18000
	s_add_i32 s23, 16, 0x1c000
	v_add_u32_e32 v154, s22, v139
	v_add_u32_e32 v170, s23, v139
	ds_read_b128 v[142:145], v154
	ds_read_b128 v[146:149], v154 offset:1024
	ds_read_b128 v[150:153], v154 offset:2048
	ds_read_b128 v[154:157], v154 offset:3072
	ds_read_b128 v[158:161], v170
	ds_read_b128 v[162:165], v170 offset:1024
	ds_read_b128 v[166:169], v170 offset:2048
	ds_read_b128 v[170:173], v170 offset:3072
	s_add_u32 s20, s40, 0x80000
	s_addc_u32 s21, s41, 0
	s_mov_b32 m0, s31
	v_lshl_add_u64 v[222:223], s[20:21], 0, v[132:133]
	ds_read_b128 v[184:187], v141 offset:32768
	ds_read_b128 v[188:191], v141 offset:33792
	ds_read_b128 v[192:195], v141 offset:34816
	ds_read_b128 v[196:199], v141 offset:35840
	ds_read_b128 v[200:203], v141 offset:36864
	ds_read_b128 v[204:207], v141 offset:37888
	ds_read_b128 v[208:211], v141 offset:38912
	ds_read_b128 v[212:215], v141 offset:39936
	global_load_lds_dwordx4 v[222:223], off
	v_lshl_add_u64 v[222:223], s[20:21], 0, v[130:131]
	s_mov_b32 m0, s44
	s_nop 0
	global_load_lds_dwordx4 v[222:223], off
	s_waitcnt vmcnt(8)
	s_waitcnt lgkmcnt(0)
	s_barrier
	s_waitcnt lgkmcnt(0)
	v_mfma_f32_16x16x32_bf16 v[120:123], v[142:145], v[184:187], v[120:123]
	v_mfma_f32_16x16x32_bf16 v[124:127], v[150:153], v[184:187], v[124:127]
	v_mfma_f32_16x16x32_bf16 v[108:111], v[142:145], v[192:195], v[108:111]
	v_mfma_f32_16x16x32_bf16 v[104:107], v[150:153], v[192:195], v[104:107]
	v_mfma_f32_16x16x32_bf16 v[92:95], v[142:145], v[200:203], v[92:95]
	v_mfma_f32_16x16x32_bf16 v[88:91], v[150:153], v[200:203], v[88:91]
	v_mfma_f32_16x16x32_bf16 v[76:79], v[142:145], v[208:211], v[76:79]
	v_mfma_f32_16x16x32_bf16 v[72:75], v[150:153], v[208:211], v[72:75]
	v_mfma_f32_16x16x32_bf16 v[120:123], v[146:149], v[188:191], v[120:123]
	v_mfma_f32_16x16x32_bf16 v[124:127], v[154:157], v[188:191], v[124:127]
	v_mfma_f32_16x16x32_bf16 v[108:111], v[146:149], v[196:199], v[108:111]
	v_mfma_f32_16x16x32_bf16 v[104:107], v[154:157], v[196:199], v[104:107]
	v_mfma_f32_16x16x32_bf16 v[92:95], v[146:149], v[204:207], v[92:95]
	v_mfma_f32_16x16x32_bf16 v[88:91], v[154:157], v[204:207], v[88:91]
	v_mfma_f32_16x16x32_bf16 v[76:79], v[146:149], v[212:215], v[76:79]
	v_mfma_f32_16x16x32_bf16 v[72:75], v[154:157], v[212:215], v[72:75]
	v_mfma_f32_16x16x32_bf16 v[116:119], v[158:161], v[184:187], v[116:119]
	v_mfma_f32_16x16x32_bf16 v[112:115], v[166:169], v[184:187], v[112:115]
	v_mfma_f32_16x16x32_bf16 v[100:103], v[158:161], v[192:195], v[100:103]
	v_mfma_f32_16x16x32_bf16 v[96:99], v[166:169], v[192:195], v[96:99]
	v_mfma_f32_16x16x32_bf16 v[84:87], v[158:161], v[200:203], v[84:87]
	v_mfma_f32_16x16x32_bf16 v[80:83], v[166:169], v[200:203], v[80:83]
	v_mfma_f32_16x16x32_bf16 v[68:71], v[158:161], v[208:211], v[68:71]
	v_mfma_f32_16x16x32_bf16 v[64:67], v[166:169], v[208:211], v[64:67]
	v_mfma_f32_16x16x32_bf16 v[116:119], v[162:165], v[188:191], v[116:119]
	v_mfma_f32_16x16x32_bf16 v[112:115], v[170:173], v[188:191], v[112:115]
	v_mfma_f32_16x16x32_bf16 v[100:103], v[162:165], v[196:199], v[100:103]
	v_mfma_f32_16x16x32_bf16 v[96:99], v[170:173], v[196:199], v[96:99]
	v_mfma_f32_16x16x32_bf16 v[84:87], v[162:165], v[204:207], v[84:87]
	v_mfma_f32_16x16x32_bf16 v[80:83], v[170:173], v[204:207], v[80:83]
	v_mfma_f32_16x16x32_bf16 v[68:71], v[162:165], v[212:215], v[68:71]
	v_mfma_f32_16x16x32_bf16 v[64:67], v[170:173], v[212:215], v[64:67]
	s_barrier
; #define PG8_STAGE(bufoff, gbase, voff) do { _Pragma("unroll") for (int _i = 0; _i < 2; ++_i) \
;         __builtin_amdgcn_global_load_lds((const unsigned*)((const char*)(gbase) + (voff)[_i]), (LAS unsigned*)(lds + (bufoff) + ldsw + _i * 8192), 16, 0, 0); } while (0)
; #define PG8_LDA(dst, b, h) do { _Pragma("unroll") for (int m = 0; m < 4; ++m) _Pragma("unroll") for (int k = 0; k < 2; ++k) dst[m][k] = *(const LAS bf16x8*)(lds + PG8_SA(b, h) + aoff + m * 2048 + k * 1024); } while (0)
; #define PG8_MMA(ai, bj, At, Bt) do { __builtin_amdgcn_s_setprio(1); _Pragma("unroll") for (int m = 0; m < 4; ++m) _Pragma("unroll") for (int n = 0; n < 2; ++n) _Pragma("unroll") for (int k = 0; k < 2; ++k) \
;         acc[ai][bj][m][n] = __builtin_amdgcn_mfma_f32_16x16x32_bf16(Bt[n][k], At[m][k], acc[ai][bj][m][n], 0, 0, 0); __builtin_amdgcn_s_setprio(0); } while (0)
; #define PG8_WAIT_V(n) asm volatile("s_waitcnt vmcnt(" #n ")" ::: "memory")
; #define PG8_WAIT_L(n) asm volatile("s_waitcnt lgkmcnt(" #n ")" ::: "memory")
; #define PG8_BAR __builtin_amdgcn_s_barrier()
; #define PG8_SCHED __builtin_amdgcn_sched_barrier(0)
; template <class Epi, bool ALIGN_EPI = PG8_ALIGN>
; __device__ __forceinline__ void gemm_phase(LAS unsigned char* lds, const Gemm g, const StaticOrder& S, const Epi& E) {
;     ...
;             PG8_LDA(At, 1, 1); PG8_STAGE(PG8_SB(1, 0), b3, voffB); PG8_STAGE(PG8_SB(1, 1), b3 + hstepB, voffB); PG8_STAGE(PG8_SA(1, 0), a3, voffA);
;             PG8_WAIT_V(8); PG8_WAIT_L(0); PG8_BAR; PG8_MMA(1, 0, At, B0); PG8_MMA(1, 1, At, B1); PG8_BAR; PG8_SCHED;
;         }
	s_add_i32 s20, s22, s18
	v_lshl_add_u64 v[174:175], v[174:175], 0, s[0:1]
	s_mov_b32 m0, s20
	ds_read_b128 v[184:187], v141 offset:49152
	ds_read_b128 v[188:191], v141 offset:50176
	ds_read_b128 v[192:195], v141 offset:51200
	ds_read_b128 v[196:199], v141 offset:52224
	ds_read_b128 v[200:203], v141 offset:53248
	ds_read_b128 v[204:207], v141 offset:54272
	ds_read_b128 v[208:211], v141 offset:55296
	ds_read_b128 v[212:215], v141 offset:56320
	global_load_lds_dwordx4 v[174:175], off
	v_lshl_add_u64 v[174:175], v[180:181], 0, s[0:1]
	s_add_i32 m0, s20, 0x2000
	s_add_i32 s20, s23, s18
	global_load_lds_dwordx4 v[174:175], off
	v_lshl_add_u64 v[174:175], v[182:183], 0, s[0:1]
	s_mov_b32 m0, s20
	s_nop 0
	global_load_lds_dwordx4 v[174:175], off
	v_lshl_add_u64 v[174:175], v[216:217], 0, s[0:1]
	s_add_i32 m0, s20, 0x2000
	s_nop 0
	global_load_lds_dwordx4 v[174:175], off
	v_lshl_add_u64 v[174:175], v[218:219], 0, s[0:1]
	s_mov_b32 m0, s45
	s_nop 0
	global_load_lds_dwordx4 v[174:175], off
	v_lshl_add_u64 v[174:175], v[220:221], 0, s[0:1]
	s_mov_b32 m0, s46
	s_nop 0
	global_load_lds_dwordx4 v[174:175], off
	s_waitcnt vmcnt(8)
	s_waitcnt lgkmcnt(0)
	s_barrier
	s_waitcnt lgkmcnt(0)
	v_mfma_f32_16x16x32_bf16 v[60:63], v[142:145], v[184:187], v[60:63]
	v_mfma_f32_16x16x32_bf16 v[56:59], v[150:153], v[184:187], v[56:59]
	v_mfma_f32_16x16x32_bf16 v[44:47], v[142:145], v[192:195], v[44:47]
	v_mfma_f32_16x16x32_bf16 v[40:43], v[150:153], v[192:195], v[40:43]
	v_mfma_f32_16x16x32_bf16 v[28:31], v[142:145], v[200:203], v[28:31]
	v_mfma_f32_16x16x32_bf16 v[24:27], v[150:153], v[200:203], v[24:27]
	v_mfma_f32_16x16x32_bf16 v[12:15], v[142:145], v[208:211], v[12:15]
	v_mfma_f32_16x16x32_bf16 v[8:11], v[150:153], v[208:211], v[8:11]
	v_mfma_f32_16x16x32_bf16 v[60:63], v[146:149], v[188:191], v[60:63]
	v_mfma_f32_16x16x32_bf16 v[56:59], v[154:157], v[188:191], v[56:59]
	v_mfma_f32_16x16x32_bf16 v[44:47], v[146:149], v[196:199], v[44:47]
	v_mfma_f32_16x16x32_bf16 v[40:43], v[154:157], v[196:199], v[40:43]
	v_mfma_f32_16x16x32_bf16 v[28:31], v[146:149], v[204:207], v[28:31]
	v_mfma_f32_16x16x32_bf16 v[24:27], v[154:157], v[204:207], v[24:27]
	v_mfma_f32_16x16x32_bf16 v[12:15], v[146:149], v[212:215], v[12:15]
	v_mfma_f32_16x16x32_bf16 v[8:11], v[154:157], v[212:215], v[8:11]
	v_mfma_f32_16x16x32_bf16 v[52:55], v[158:161], v[184:187], v[52:55]
	v_mfma_f32_16x16x32_bf16 v[48:51], v[166:169], v[184:187], v[48:51]
	v_mfma_f32_16x16x32_bf16 v[36:39], v[158:161], v[192:195], v[36:39]
	v_mfma_f32_16x16x32_bf16 v[32:35], v[166:169], v[192:195], v[32:35]
	v_mfma_f32_16x16x32_bf16 v[20:23], v[158:161], v[200:203], v[20:23]
	v_mfma_f32_16x16x32_bf16 v[16:19], v[166:169], v[200:203], v[16:19]
	v_mfma_f32_16x16x32_bf16 v[4:7], v[158:161], v[208:211], v[4:7]
	v_mfma_f32_16x16x32_bf16 v[0:3], v[166:169], v[208:211], v[0:3]
	v_mfma_f32_16x16x32_bf16 v[52:55], v[162:165], v[188:191], v[52:55]
	v_mfma_f32_16x16x32_bf16 v[48:51], v[170:173], v[188:191], v[48:51]
	v_mfma_f32_16x16x32_bf16 v[36:39], v[162:165], v[196:199], v[36:39]
	v_mfma_f32_16x16x32_bf16 v[32:35], v[170:173], v[196:199], v[32:35]
	v_mfma_f32_16x16x32_bf16 v[20:23], v[162:165], v[204:207], v[20:23]
	v_mfma_f32_16x16x32_bf16 v[16:19], v[170:173], v[204:207], v[16:19]
	v_mfma_f32_16x16x32_bf16 v[4:7], v[162:165], v[212:215], v[4:7]
	v_mfma_f32_16x16x32_bf16 v[0:3], v[170:173], v[212:215], v[0:3]
	s_barrier
	s_add_u32 s4, s4, 0x100
	s_addc_u32 s5, s5, 0
	s_add_u32 s42, s42, 0x100
	s_addc_u32 s43, s43, 0
	s_cmp_ge_i32 s53, s34
	s_mov_b32 s40, s53
	s_cbranch_scc0 .LBB0_901

; #define PG8_STAGE(bufoff, gbase, voff) do { _Pragma("unroll") for (int _i = 0; _i < 2; ++_i) \
;         __builtin_amdgcn_global_load_lds((const unsigned*)((const char*)(gbase) + (voff)[_i]), (LAS unsigned*)(lds + (bufoff) + ldsw + _i * 8192), 16, 0, 0); } while (0)
; #define PG8_LDA(dst, b, h) do { _Pragma("unroll") for (int m = 0; m < 4; ++m) _Pragma("unroll") for (int k = 0; k < 2; ++k) dst[m][k] = *(const LAS bf16x8*)(lds + PG8_SA(b, h) + aoff + m * 2048 + k * 1024); } while (0)
; #define PG8_LDB(dst, b, h) do { _Pragma("unroll") for (int n = 0; n < 2; ++n) _Pragma("unroll") for (int k = 0; k < 2; ++k) dst[n][k] = *(const LAS bf16x8*)(lds + PG8_SB(b, h) + boff + n * 2048 + k * 1024); } while (0)
; #define PG8_MMA(ai, bj, At, Bt) do { __builtin_amdgcn_s_setprio(1); _Pragma("unroll") for (int m = 0; m < 4; ++m) _Pragma("unroll") for (int n = 0; n < 2; ++n) _Pragma("unroll") for (int k = 0; k < 2; ++k) \
;         acc[ai][bj][m][n] = __builtin_amdgcn_mfma_f32_16x16x32_bf16(Bt[n][k], At[m][k], acc[ai][bj][m][n], 0, 0, 0); __builtin_amdgcn_s_setprio(0); } while (0)
; #define PG8_WAIT_V(n) asm volatile("s_waitcnt vmcnt(" #n ")" ::: "memory")
; #define PG8_WAIT_L(n) asm volatile("s_waitcnt lgkmcnt(" #n ")" ::: "memory")
; #define PG8_BAR __builtin_amdgcn_s_barrier()
; #define PG8_SCHED __builtin_amdgcn_sched_barrier(0)
; template <class Epi, bool ALIGN_EPI = PG8_ALIGN>
; __device__ __forceinline__ void gemm_phase(LAS unsigned char* lds, const Gemm g, const StaticOrder& S, const Epi& E) {
;     ...
;         for (int t = 0; t < nt; t += 2) {
;             const bool last = (t == nt - 2);
;             const char* a1 = cA + (size_t)(t + 1) * kstep;
;             const char* a2 = last ? nA : cA + (size_t)(t + 2) * kstep; const char* b2 = last ? nB : cB + (size_t)(t + 2) * kstep;
;             const char* a3 = a2 + kstep; const char* b3 = b2 + kstep;
;             PG8_LDB(B0, 0, 0); PG8_LDB(B1, 0, 1); PG8_SCHED; PG8_LDA(At, 0, 0); PG8_STAGE(PG8_SA(1, 1), a1 + hstepA, voffA);
;             PG8_WAIT_V(8); PG8_WAIT_L(0); PG8_BAR; PG8_MMA(0, 0, At, B0); PG8_MMA(0, 1, At, B1); PG8_BAR; PG8_SCHED;
;             PG8_LDA(At, 0, 1); PG8_STAGE(PG8_SB(0, 0), b2, voffB); PG8_STAGE(PG8_SB(0, 1), b2 + hstepB, voffB); PG8_STAGE(PG8_SA(0, 0), a2, voffA);
;             PG8_WAIT_V(8); PG8_WAIT_L(0); PG8_BAR; PG8_MMA(1, 0, At, B0); PG8_MMA(1, 1, At, B1); PG8_BAR; PG8_SCHED;
.LBB0_1028:
	s_add_i32 s31, s24, 2
	s_add_u32 s20, s2, 0xfff80080
	s_addc_u32 s21, s3, -1
	s_add_i32 s22, 16, 0x10000
	s_cmp_eq_u32 s53, s24
	s_cselect_b32 s25, s17, s21
	s_cselect_b32 s24, s27, s20
	s_cselect_b32 s21, s39, s30
	s_cselect_b32 s20, s38, s29
	s_add_i32 s23, 16, 0x14000
	v_add_u32_e32 v140, s22, v220
	v_add_u32_e32 v156, s23, v220
	ds_read_b128 v[128:131], v140
	ds_read_b128 v[132:135], v140 offset:1024
	ds_read_b128 v[136:139], v140 offset:2048
	ds_read_b128 v[140:143], v140 offset:3072
	ds_read_b128 v[144:147], v156
	ds_read_b128 v[148:151], v156 offset:1024
	ds_read_b128 v[152:155], v156 offset:2048
	ds_read_b128 v[156:159], v156 offset:3072
	v_lshl_add_u64 v[180:181], s[2:3], 0, v[192:193]
	s_add_i32 m0, s47, 0xc000
	ds_read_b128 v[160:163], v223
	ds_read_b128 v[164:167], v223 offset:1024
	ds_read_b128 v[168:171], v223 offset:2048
	ds_read_b128 v[172:175], v223 offset:3072
	ds_read_b128 v[196:199], v223 offset:4096
	ds_read_b128 v[200:203], v223 offset:5120
	ds_read_b128 v[204:207], v223 offset:6144
	ds_read_b128 v[208:211], v223 offset:7168
	global_load_lds_dwordx4 v[180:181], off
	v_lshl_add_u64 v[180:181], s[2:3], 0, v[194:195]
	s_add_i32 m0, s47, 0xe000
	s_nop 0
	global_load_lds_dwordx4 v[180:181], off
	s_waitcnt vmcnt(8)
	s_waitcnt lgkmcnt(0)
	s_barrier
	s_waitcnt lgkmcnt(0)
	v_mfma_f32_16x16x32_bf16 v[124:127], v[128:131], v[160:163], v[124:127]
	v_mfma_f32_16x16x32_bf16 v[116:119], v[136:139], v[160:163], v[116:119]
	v_mfma_f32_16x16x32_bf16 v[108:111], v[128:131], v[168:171], v[108:111]
	v_mfma_f32_16x16x32_bf16 v[100:103], v[136:139], v[168:171], v[100:103]
	v_mfma_f32_16x16x32_bf16 v[92:95], v[128:131], v[196:199], v[92:95]
	v_mfma_f32_16x16x32_bf16 v[84:87], v[136:139], v[196:199], v[84:87]
	v_mfma_f32_16x16x32_bf16 v[76:79], v[128:131], v[204:207], v[76:79]
	v_mfma_f32_16x16x32_bf16 v[68:71], v[136:139], v[204:207], v[68:71]
	v_mfma_f32_16x16x32_bf16 v[124:127], v[132:135], v[164:167], v[124:127]
	v_mfma_f32_16x16x32_bf16 v[116:119], v[140:143], v[164:167], v[116:119]
	v_mfma_f32_16x16x32_bf16 v[108:111], v[132:135], v[172:175], v[108:111]
	v_mfma_f32_16x16x32_bf16 v[100:103], v[140:143], v[172:175], v[100:103]
	v_mfma_f32_16x16x32_bf16 v[92:95], v[132:135], v[200:203], v[92:95]
	v_mfma_f32_16x16x32_bf16 v[84:87], v[140:143], v[200:203], v[84:87]
	v_mfma_f32_16x16x32_bf16 v[76:79], v[132:135], v[208:211], v[76:79]
	v_mfma_f32_16x16x32_bf16 v[68:71], v[140:143], v[208:211], v[68:71]
	v_mfma_f32_16x16x32_bf16 v[120:123], v[144:147], v[160:163], v[120:123]
	v_mfma_f32_16x16x32_bf16 v[112:115], v[152:155], v[160:163], v[112:115]
	v_mfma_f32_16x16x32_bf16 v[104:107], v[144:147], v[168:171], v[104:107]
	v_mfma_f32_16x16x32_bf16 v[96:99], v[152:155], v[168:171], v[96:99]
	v_mfma_f32_16x16x32_bf16 v[88:91], v[144:147], v[196:199], v[88:91]
	v_mfma_f32_16x16x32_bf16 v[80:83], v[152:155], v[196:199], v[80:83]
	v_mfma_f32_16x16x32_bf16 v[72:75], v[144:147], v[204:207], v[72:75]
	v_mfma_f32_16x16x32_bf16 v[64:67], v[152:155], v[204:207], v[64:67]
	v_mfma_f32_16x16x32_bf16 v[120:123], v[148:151], v[164:167], v[120:123]
	v_mfma_f32_16x16x32_bf16 v[112:115], v[156:159], v[164:167], v[112:115]
	v_mfma_f32_16x16x32_bf16 v[104:107], v[148:151], v[172:175], v[104:107]
	v_mfma_f32_16x16x32_bf16 v[96:99], v[156:159], v[172:175], v[96:99]
	v_mfma_f32_16x16x32_bf16 v[88:91], v[148:151], v[200:203], v[88:91]
	v_mfma_f32_16x16x32_bf16 v[80:83], v[156:159], v[200:203], v[80:83]
	v_mfma_f32_16x16x32_bf16 v[72:75], v[148:151], v[208:211], v[72:75]
	v_mfma_f32_16x16x32_bf16 v[64:67], v[156:159], v[208:211], v[64:67]
	s_barrier
	s_add_i32 s22, s22, s46
	v_lshl_add_u64 v[180:181], s[20:21], 0, v[188:189]
	s_mov_b32 m0, s22
	ds_read_b128 v[160:163], v223 offset:16384
	ds_read_b128 v[164:167], v223 offset:17408
	ds_read_b128 v[168:171], v223 offset:18432
	ds_read_b128 v[172:175], v223 offset:19456
	ds_read_b128 v[196:199], v223 offset:20480
	ds_read_b128 v[200:203], v223 offset:21504
	ds_read_b128 v[204:207], v223 offset:22528
	ds_read_b128 v[208:211], v223 offset:23552
	global_load_lds_dwordx4 v[180:181], off
	s_add_i32 m0, s22, 0x2000
	v_lshl_add_u64 v[182:183], s[20:21], 0, v[184:185]
	s_add_u32 s20, s20, s4
	s_addc_u32 s21, s21, s5
	s_add_i32 s22, s23, s46
	global_load_lds_dwordx4 v[182:183], off
	v_lshl_add_u64 v[212:213], s[20:21], 0, v[188:189]
	s_mov_b32 m0, s22
	v_lshl_add_u64 v[214:215], s[20:21], 0, v[184:185]
	global_load_lds_dwordx4 v[212:213], off
	s_add_i32 m0, s22, 0x2000
	v_lshl_add_u64 v[216:217], s[24:25], 0, v[190:191]
	global_load_lds_dwordx4 v[214:215], off
	s_mov_b32 m0, s47
	v_lshl_add_u64 v[218:219], s[24:25], 0, v[186:187]
	global_load_lds_dwordx4 v[216:217], off
	s_mov_b32 m0, s48
	s_nop 0
	global_load_lds_dwordx4 v[218:219], off
	s_waitcnt vmcnt(8)
	s_waitcnt lgkmcnt(0)
	s_barrier
; #define PG8_STAGE(bufoff, gbase, voff) do { _Pragma("unroll") for (int _i = 0; _i < 2; ++_i) \
;         __builtin_amdgcn_global_load_lds((const unsigned*)((const char*)(gbase) + (voff)[_i]), (LAS unsigned*)(lds + (bufoff) + ldsw + _i * 8192), 16, 0, 0); } while (0)
; #define PG8_LDA(dst, b, h) do { _Pragma("unroll") for (int m = 0; m < 4; ++m) _Pragma("unroll") for (int k = 0; k < 2; ++k) dst[m][k] = *(const LAS bf16x8*)(lds + PG8_SA(b, h) + aoff + m * 2048 + k * 1024); } while (0)
; #define PG8_LDB(dst, b, h) do { _Pragma("unroll") for (int n = 0; n < 2; ++n) _Pragma("unroll") for (int k = 0; k < 2; ++k) dst[n][k] = *(const LAS bf16x8*)(lds + PG8_SB(b, h) + boff + n * 2048 + k * 1024); } while (0)
; #define PG8_MMA(ai, bj, At, Bt) do { __builtin_amdgcn_s_setprio(1); _Pragma("unroll") for (int m = 0; m < 4; ++m) _Pragma("unroll") for (int n = 0; n < 2; ++n) _Pragma("unroll") for (int k = 0; k < 2; ++k) \
;         acc[ai][bj][m][n] = __builtin_amdgcn_mfma_f32_16x16x32_bf16(Bt[n][k], At[m][k], acc[ai][bj][m][n], 0, 0, 0); __builtin_amdgcn_s_setprio(0); } while (0)
; #define PG8_WAIT_V(n) asm volatile("s_waitcnt vmcnt(" #n ")" ::: "memory")
; #define PG8_WAIT_L(n) asm volatile("s_waitcnt lgkmcnt(" #n ")" ::: "memory")
; #define PG8_BAR __builtin_amdgcn_s_barrier()
; #define PG8_SCHED __builtin_amdgcn_sched_barrier(0)
; template <class Epi, bool ALIGN_EPI = PG8_ALIGN>
; __device__ __forceinline__ void gemm_phase(LAS unsigned char* lds, const Gemm g, const StaticOrder& S, const Epi& E) {
;     ...
;             PG8_WAIT_V(8); PG8_WAIT_L(0); PG8_BAR; PG8_MMA(1, 0, At, B0); PG8_MMA(1, 1, At, B1); PG8_BAR; PG8_SCHED;
;             PG8_LDB(B0, 1, 0); PG8_LDB(B1, 1, 1); PG8_SCHED; PG8_LDA(At, 1, 0); PG8_STAGE(PG8_SA(0, 1), a2 + hstepA, voffA);
;             PG8_WAIT_V(8); PG8_WAIT_L(0); PG8_BAR; PG8_MMA(0, 0, At, B0); PG8_MMA(0, 1, At, B1); PG8_BAR; PG8_SCHED;
	s_waitcnt lgkmcnt(0)
	v_mfma_f32_16x16x32_bf16 v[60:63], v[128:131], v[160:163], v[60:63]
	v_mfma_f32_16x16x32_bf16 v[52:55], v[136:139], v[160:163], v[52:55]
	v_mfma_f32_16x16x32_bf16 v[44:47], v[128:131], v[168:171], v[44:47]
	v_mfma_f32_16x16x32_bf16 v[36:39], v[136:139], v[168:171], v[36:39]
	v_mfma_f32_16x16x32_bf16 v[28:31], v[128:131], v[196:199], v[28:31]
	v_mfma_f32_16x16x32_bf16 v[20:23], v[136:139], v[196:199], v[20:23]
	v_mfma_f32_16x16x32_bf16 v[12:15], v[128:131], v[204:207], v[12:15]
	v_mfma_f32_16x16x32_bf16 v[4:7], v[136:139], v[204:207], v[4:7]
	v_mfma_f32_16x16x32_bf16 v[60:63], v[132:135], v[164:167], v[60:63]
	v_mfma_f32_16x16x32_bf16 v[52:55], v[140:143], v[164:167], v[52:55]
	v_mfma_f32_16x16x32_bf16 v[44:47], v[132:135], v[172:175], v[44:47]
	v_mfma_f32_16x16x32_bf16 v[36:39], v[140:143], v[172:175], v[36:39]
	v_mfma_f32_16x16x32_bf16 v[28:31], v[132:135], v[200:203], v[28:31]
	v_mfma_f32_16x16x32_bf16 v[20:23], v[140:143], v[200:203], v[20:23]
	v_mfma_f32_16x16x32_bf16 v[12:15], v[132:135], v[208:211], v[12:15]
	v_mfma_f32_16x16x32_bf16 v[4:7], v[140:143], v[208:211], v[4:7]
	v_mfma_f32_16x16x32_bf16 v[56:59], v[144:147], v[160:163], v[56:59]
	v_mfma_f32_16x16x32_bf16 v[48:51], v[152:155], v[160:163], v[48:51]
	v_mfma_f32_16x16x32_bf16 v[40:43], v[144:147], v[168:171], v[40:43]
	v_mfma_f32_16x16x32_bf16 v[32:35], v[152:155], v[168:171], v[32:35]
	v_mfma_f32_16x16x32_bf16 v[24:27], v[144:147], v[196:199], v[24:27]
	v_mfma_f32_16x16x32_bf16 v[16:19], v[152:155], v[196:199], v[16:19]
	v_mfma_f32_16x16x32_bf16 v[8:11], v[144:147], v[204:207], v[8:11]
	v_mfma_f32_16x16x32_bf16 v[0:3], v[152:155], v[204:207], v[0:3]
	v_mfma_f32_16x16x32_bf16 v[56:59], v[148:151], v[164:167], v[56:59]
	v_mfma_f32_16x16x32_bf16 v[48:51], v[156:159], v[164:167], v[48:51]
	v_mfma_f32_16x16x32_bf16 v[40:43], v[148:151], v[172:175], v[40:43]
	v_mfma_f32_16x16x32_bf16 v[32:35], v[156:159], v[172:175], v[32:35]
	v_mfma_f32_16x16x32_bf16 v[24:27], v[148:151], v[200:203], v[24:27]
	v_mfma_f32_16x16x32_bf16 v[16:19], v[156:159], v[200:203], v[16:19]
	v_mfma_f32_16x16x32_bf16 v[8:11], v[148:151], v[208:211], v[8:11]
	v_mfma_f32_16x16x32_bf16 v[0:3], v[156:159], v[208:211], v[0:3]
	s_barrier
	s_add_i32 s22, 16, 0x18000
	s_add_i32 s23, 16, 0x1c000
	v_add_u32_e32 v140, s22, v220
	v_add_u32_e32 v156, s23, v220
	ds_read_b128 v[128:131], v140
	ds_read_b128 v[132:135], v140 offset:1024
	ds_read_b128 v[136:139], v140 offset:2048
	ds_read_b128 v[140:143], v140 offset:3072
	ds_read_b128 v[144:147], v156
	ds_read_b128 v[148:151], v156 offset:1024
	ds_read_b128 v[152:155], v156 offset:2048
	ds_read_b128 v[156:159], v156 offset:3072
	s_add_u32 s20, s24, 0x80000
	s_addc_u32 s21, s25, 0
	s_mov_b32 m0, s49
	v_lshl_add_u64 v[224:225], s[20:21], 0, v[190:191]
	ds_read_b128 v[160:163], v223 offset:32768
	ds_read_b128 v[164:167], v223 offset:33792
	ds_read_b128 v[168:171], v223 offset:34816
	ds_read_b128 v[172:175], v223 offset:35840
	ds_read_b128 v[196:199], v223 offset:36864
	ds_read_b128 v[200:203], v223 offset:37888
	ds_read_b128 v[204:207], v223 offset:38912
	ds_read_b128 v[208:211], v223 offset:39936
	global_load_lds_dwordx4 v[224:225], off
	v_lshl_add_u64 v[224:225], s[20:21], 0, v[186:187]
	s_mov_b32 m0, s50
	s_nop 0
	global_load_lds_dwordx4 v[224:225], off
	s_waitcnt vmcnt(8)
	s_waitcnt lgkmcnt(0)
	s_barrier
	s_waitcnt lgkmcnt(0)
	v_mfma_f32_16x16x32_bf16 v[124:127], v[128:131], v[160:163], v[124:127]
	v_mfma_f32_16x16x32_bf16 v[116:119], v[136:139], v[160:163], v[116:119]
	v_mfma_f32_16x16x32_bf16 v[108:111], v[128:131], v[168:171], v[108:111]
	v_mfma_f32_16x16x32_bf16 v[100:103], v[136:139], v[168:171], v[100:103]
	v_mfma_f32_16x16x32_bf16 v[92:95], v[128:131], v[196:199], v[92:95]
	v_mfma_f32_16x16x32_bf16 v[84:87], v[136:139], v[196:199], v[84:87]
	v_mfma_f32_16x16x32_bf16 v[76:79], v[128:131], v[204:207], v[76:79]
	v_mfma_f32_16x16x32_bf16 v[68:71], v[136:139], v[204:207], v[68:71]
	v_mfma_f32_16x16x32_bf16 v[124:127], v[132:135], v[164:167], v[124:127]
	v_mfma_f32_16x16x32_bf16 v[116:119], v[140:143], v[164:167], v[116:119]
	v_mfma_f32_16x16x32_bf16 v[108:111], v[132:135], v[172:175], v[108:111]
	v_mfma_f32_16x16x32_bf16 v[100:103], v[140:143], v[172:175], v[100:103]
	v_mfma_f32_16x16x32_bf16 v[92:95], v[132:135], v[200:203], v[92:95]
	v_mfma_f32_16x16x32_bf16 v[84:87], v[140:143], v[200:203], v[84:87]
	v_mfma_f32_16x16x32_bf16 v[76:79], v[132:135], v[208:211], v[76:79]
	v_mfma_f32_16x16x32_bf16 v[68:71], v[140:143], v[208:211], v[68:71]
	v_mfma_f32_16x16x32_bf16 v[120:123], v[144:147], v[160:163], v[120:123]
	v_mfma_f32_16x16x32_bf16 v[112:115], v[152:155], v[160:163], v[112:115]
	v_mfma_f32_16x16x32_bf16 v[104:107], v[144:147], v[168:171], v[104:107]
	v_mfma_f32_16x16x32_bf16 v[96:99], v[152:155], v[168:171], v[96:99]
	v_mfma_f32_16x16x32_bf16 v[88:91], v[144:147], v[196:199], v[88:91]
	v_mfma_f32_16x16x32_bf16 v[80:83], v[152:155], v[196:199], v[80:83]
	v_mfma_f32_16x16x32_bf16 v[72:75], v[144:147], v[204:207], v[72:75]
	v_mfma_f32_16x16x32_bf16 v[64:67], v[152:155], v[204:207], v[64:67]
	v_mfma_f32_16x16x32_bf16 v[120:123], v[148:151], v[164:167], v[120:123]
	v_mfma_f32_16x16x32_bf16 v[112:115], v[156:159], v[164:167], v[112:115]
	v_mfma_f32_16x16x32_bf16 v[104:107], v[148:151], v[172:175], v[104:107]
	v_mfma_f32_16x16x32_bf16 v[96:99], v[156:159], v[172:175], v[96:99]
	v_mfma_f32_16x16x32_bf16 v[88:91], v[148:151], v[200:203], v[88:91]
	v_mfma_f32_16x16x32_bf16 v[80:83], v[156:159], v[200:203], v[80:83]
	v_mfma_f32_16x16x32_bf16 v[72:75], v[148:151], v[208:211], v[72:75]
	v_mfma_f32_16x16x32_bf16 v[64:67], v[156:159], v[208:211], v[64:67]
	s_barrier
; #define PG8_STAGE(bufoff, gbase, voff) do { _Pragma("unroll") for (int _i = 0; _i < 2; ++_i) \
;         __builtin_amdgcn_global_load_lds((const unsigned*)((const char*)(gbase) + (voff)[_i]), (LAS unsigned*)(lds + (bufoff) + ldsw + _i * 8192), 16, 0, 0); } while (0)
; #define PG8_LDA(dst, b, h) do { _Pragma("unroll") for (int m = 0; m < 4; ++m) _Pragma("unroll") for (int k = 0; k < 2; ++k) dst[m][k] = *(const LAS bf16x8*)(lds + PG8_SA(b, h) + aoff + m * 2048 + k * 1024); } while (0)
; #define PG8_MMA(ai, bj, At, Bt) do { __builtin_amdgcn_s_setprio(1); _Pragma("unroll") for (int m = 0; m < 4; ++m) _Pragma("unroll") for (int n = 0; n < 2; ++n) _Pragma("unroll") for (int k = 0; k < 2; ++k) \
;         acc[ai][bj][m][n] = __builtin_amdgcn_mfma_f32_16x16x32_bf16(Bt[n][k], At[m][k], acc[ai][bj][m][n], 0, 0, 0); __builtin_amdgcn_s_setprio(0); } while (0)
; #define PG8_WAIT_V(n) asm volatile("s_waitcnt vmcnt(" #n ")" ::: "memory")
; #define PG8_WAIT_L(n) asm volatile("s_waitcnt lgkmcnt(" #n ")" ::: "memory")
; #define PG8_BAR __builtin_amdgcn_s_barrier()
; #define PG8_SCHED __builtin_amdgcn_sched_barrier(0)
; template <class Epi, bool ALIGN_EPI = PG8_ALIGN>
; __device__ __forceinline__ void gemm_phase(LAS unsigned char* lds, const Gemm g, const StaticOrder& S, const Epi& E) {
;     ...
;             PG8_LDA(At, 1, 1); PG8_STAGE(PG8_SB(1, 0), b3, voffB); PG8_STAGE(PG8_SB(1, 1), b3 + hstepB, voffB); PG8_STAGE(PG8_SA(1, 0), a3, voffA);
;             PG8_WAIT_V(8); PG8_WAIT_L(0); PG8_BAR; PG8_MMA(1, 0, At, B0); PG8_MMA(1, 1, At, B1); PG8_BAR; PG8_SCHED;
;         }
	s_add_i32 s20, s22, s46
	v_lshl_add_u64 v[180:181], v[180:181], 0, s[0:1]
	s_mov_b32 m0, s20
	ds_read_b128 v[160:163], v223 offset:49152
	ds_read_b128 v[164:167], v223 offset:50176
	ds_read_b128 v[168:171], v223 offset:51200
	ds_read_b128 v[172:175], v223 offset:52224
	ds_read_b128 v[196:199], v223 offset:53248
	ds_read_b128 v[200:203], v223 offset:54272
	ds_read_b128 v[204:207], v223 offset:55296
	ds_read_b128 v[208:211], v223 offset:56320
	global_load_lds_dwordx4 v[180:181], off
	v_lshl_add_u64 v[180:181], v[182:183], 0, s[0:1]
	s_add_i32 m0, s20, 0x2000
	s_add_i32 s20, s23, s46
	global_load_lds_dwordx4 v[180:181], off
	v_lshl_add_u64 v[180:181], v[212:213], 0, s[0:1]
	s_mov_b32 m0, s20
	s_nop 0
	global_load_lds_dwordx4 v[180:181], off
	v_lshl_add_u64 v[180:181], v[214:215], 0, s[0:1]
	s_add_i32 m0, s20, 0x2000
	s_nop 0
	global_load_lds_dwordx4 v[180:181], off
	v_lshl_add_u64 v[180:181], v[216:217], 0, s[0:1]
	s_mov_b32 m0, s18
	s_nop 0
	global_load_lds_dwordx4 v[180:181], off
	v_lshl_add_u64 v[180:181], v[218:219], 0, s[0:1]
	s_mov_b32 m0, s51
	s_nop 0
	global_load_lds_dwordx4 v[180:181], off
	s_waitcnt vmcnt(8)
	s_waitcnt lgkmcnt(0)
	s_barrier
	s_waitcnt lgkmcnt(0)
	v_mfma_f32_16x16x32_bf16 v[60:63], v[128:131], v[160:163], v[60:63]
	v_mfma_f32_16x16x32_bf16 v[52:55], v[136:139], v[160:163], v[52:55]
	v_mfma_f32_16x16x32_bf16 v[44:47], v[128:131], v[168:171], v[44:47]
	v_mfma_f32_16x16x32_bf16 v[36:39], v[136:139], v[168:171], v[36:39]
	v_mfma_f32_16x16x32_bf16 v[28:31], v[128:131], v[196:199], v[28:31]
	v_mfma_f32_16x16x32_bf16 v[20:23], v[136:139], v[196:199], v[20:23]
	v_mfma_f32_16x16x32_bf16 v[12:15], v[128:131], v[204:207], v[12:15]
	v_mfma_f32_16x16x32_bf16 v[4:7], v[136:139], v[204:207], v[4:7]
	v_mfma_f32_16x16x32_bf16 v[60:63], v[132:135], v[164:167], v[60:63]
	v_mfma_f32_16x16x32_bf16 v[52:55], v[140:143], v[164:167], v[52:55]
	v_mfma_f32_16x16x32_bf16 v[44:47], v[132:135], v[172:175], v[44:47]
	v_mfma_f32_16x16x32_bf16 v[36:39], v[140:143], v[172:175], v[36:39]
	v_mfma_f32_16x16x32_bf16 v[28:31], v[132:135], v[200:203], v[28:31]
	v_mfma_f32_16x16x32_bf16 v[20:23], v[140:143], v[200:203], v[20:23]
	v_mfma_f32_16x16x32_bf16 v[12:15], v[132:135], v[208:211], v[12:15]
	v_mfma_f32_16x16x32_bf16 v[4:7], v[140:143], v[208:211], v[4:7]
	v_mfma_f32_16x16x32_bf16 v[56:59], v[144:147], v[160:163], v[56:59]
	v_mfma_f32_16x16x32_bf16 v[48:51], v[152:155], v[160:163], v[48:51]
	v_mfma_f32_16x16x32_bf16 v[40:43], v[144:147], v[168:171], v[40:43]
	v_mfma_f32_16x16x32_bf16 v[32:35], v[152:155], v[168:171], v[32:35]
	v_mfma_f32_16x16x32_bf16 v[24:27], v[144:147], v[196:199], v[24:27]
	v_mfma_f32_16x16x32_bf16 v[16:19], v[152:155], v[196:199], v[16:19]
	v_mfma_f32_16x16x32_bf16 v[8:11], v[144:147], v[204:207], v[8:11]
	v_mfma_f32_16x16x32_bf16 v[0:3], v[152:155], v[204:207], v[0:3]
	v_mfma_f32_16x16x32_bf16 v[56:59], v[148:151], v[164:167], v[56:59]
	v_mfma_f32_16x16x32_bf16 v[48:51], v[156:159], v[164:167], v[48:51]
	v_mfma_f32_16x16x32_bf16 v[40:43], v[148:151], v[172:175], v[40:43]
	v_mfma_f32_16x16x32_bf16 v[32:35], v[156:159], v[172:175], v[32:35]
	v_mfma_f32_16x16x32_bf16 v[24:27], v[148:151], v[200:203], v[24:27]
	v_mfma_f32_16x16x32_bf16 v[16:19], v[156:159], v[200:203], v[16:19]
	v_mfma_f32_16x16x32_bf16 v[8:11], v[148:151], v[208:211], v[8:11]
	v_mfma_f32_16x16x32_bf16 v[0:3], v[156:159], v[208:211], v[0:3]
	s_barrier
	s_add_u32 s2, s2, 0x100
	s_addc_u32 s3, s3, 0
	s_add_u32 s29, s29, 0x100
	s_addc_u32 s30, s30, 0
	s_cmp_ge_i32 s31, s52
	s_mov_b32 s24, s31
	s_cbranch_scc0 .LBB0_1028

; #define PG8_STAGE(bufoff, gbase, voff) do { _Pragma("unroll") for (int _i = 0; _i < 2; ++_i) \
;         __builtin_amdgcn_global_load_lds((const unsigned*)((const char*)(gbase) + (voff)[_i]), (LAS unsigned*)(lds + (bufoff) + ldsw + _i * 8192), 16, 0, 0); } while (0)
; #define PG8_LDA(dst, b, h) do { _Pragma("unroll") for (int m = 0; m < 4; ++m) _Pragma("unroll") for (int k = 0; k < 2; ++k) dst[m][k] = *(const LAS bf16x8*)(lds + PG8_SA(b, h) + aoff + m * 2048 + k * 1024); } while (0)
; #define PG8_LDB(dst, b, h) do { _Pragma("unroll") for (int n = 0; n < 2; ++n) _Pragma("unroll") for (int k = 0; k < 2; ++k) dst[n][k] = *(const LAS bf16x8*)(lds + PG8_SB(b, h) + boff + n * 2048 + k * 1024); } while (0)
; #define PG8_MMA(ai, bj, At, Bt) do { __builtin_amdgcn_s_setprio(1); _Pragma("unroll") for (int m = 0; m < 4; ++m) _Pragma("unroll") for (int n = 0; n < 2; ++n) _Pragma("unroll") for (int k = 0; k < 2; ++k) \
;         acc[ai][bj][m][n] = __builtin_amdgcn_mfma_f32_16x16x32_bf16(Bt[n][k], At[m][k], acc[ai][bj][m][n], 0, 0, 0); __builtin_amdgcn_s_setprio(0); } while (0)
; #define PG8_WAIT_V(n) asm volatile("s_waitcnt vmcnt(" #n ")" ::: "memory")
; #define PG8_WAIT_L(n) asm volatile("s_waitcnt lgkmcnt(" #n ")" ::: "memory")
; #define PG8_BAR __builtin_amdgcn_s_barrier()
; #define PG8_SCHED __builtin_amdgcn_sched_barrier(0)
; template <class Epi, bool ALIGN_EPI = PG8_ALIGN>
; __device__ __forceinline__ void gemm_phase(LAS unsigned char* lds, const Gemm g, const StaticOrder& S, const Epi& E) {
;     ...
;         for (int t = 0; t < nt; t += 2) {
;             const bool last = (t == nt - 2);
;             const char* a1 = cA + (size_t)(t + 1) * kstep;
;             const char* a2 = last ? nA : cA + (size_t)(t + 2) * kstep; const char* b2 = last ? nB : cB + (size_t)(t + 2) * kstep;
;             const char* a3 = a2 + kstep; const char* b3 = b2 + kstep;
;             PG8_LDB(B0, 0, 0); PG8_LDB(B1, 0, 1); PG8_SCHED; PG8_LDA(At, 0, 0); PG8_STAGE(PG8_SA(1, 1), a1 + hstepA, voffA);
;             PG8_WAIT_V(8); PG8_WAIT_L(0); PG8_BAR; PG8_MMA(0, 0, At, B0); PG8_MMA(0, 1, At, B1); PG8_BAR; PG8_SCHED;
;             PG8_LDA(At, 0, 1); PG8_STAGE(PG8_SB(0, 0), b2, voffB); PG8_STAGE(PG8_SB(0, 1), b2 + hstepB, voffB); PG8_STAGE(PG8_SA(0, 0), a2, voffA);
;             PG8_WAIT_V(8); PG8_WAIT_L(0); PG8_BAR; PG8_MMA(1, 0, At, B0); PG8_MMA(1, 1, At, B1); PG8_BAR; PG8_SCHED;
.LBB0_1108:
	s_add_i32 s53, s40, 2
	s_add_u32 s36, s24, 0x100
	s_addc_u32 s37, s25, 0
	s_add_i32 s22, 16, 0x10000
	s_cmp_eq_u32 s27, s40
	s_cselect_b32 s41, s3, s37
	s_cselect_b32 s40, s2, s36
	s_cselect_b32 s21, s17, s52
	s_cselect_b32 s20, s16, s51
	s_add_i32 s23, 16, 0x14000
	v_add_u32_e32 v154, s22, v147
	v_add_u32_e32 v170, s23, v147
	ds_read_b128 v[138:141], v154
	ds_read_b128 v[142:145], v154 offset:1024
	ds_read_b128 v[150:153], v154 offset:2048
	ds_read_b128 v[154:157], v154 offset:3072
	ds_read_b128 v[158:161], v170
	ds_read_b128 v[162:165], v170 offset:1024
	ds_read_b128 v[166:169], v170 offset:2048
	ds_read_b128 v[170:173], v170 offset:3072
	v_lshl_add_u64 v[174:175], s[24:25], 0, v[134:135]
	s_add_i32 m0, s31, 0xc000
	ds_read_b128 v[184:187], v149
	ds_read_b128 v[188:191], v149 offset:1024
	ds_read_b128 v[192:195], v149 offset:2048
	ds_read_b128 v[196:199], v149 offset:3072
	ds_read_b128 v[200:203], v149 offset:4096
	ds_read_b128 v[204:207], v149 offset:5120
	ds_read_b128 v[208:211], v149 offset:6144
	ds_read_b128 v[212:215], v149 offset:7168
	global_load_lds_dwordx4 v[174:175], off
	v_lshl_add_u64 v[174:175], s[24:25], 0, v[136:137]
	s_add_i32 m0, s31, 0xe000
	s_nop 0
	global_load_lds_dwordx4 v[174:175], off
	s_waitcnt vmcnt(8)
	s_waitcnt lgkmcnt(0)
	s_barrier
	s_waitcnt lgkmcnt(0)
	v_mfma_f32_16x16x32_bf16 v[124:127], v[138:141], v[184:187], v[124:127]
	v_mfma_f32_16x16x32_bf16 v[120:123], v[150:153], v[184:187], v[120:123]
	v_mfma_f32_16x16x32_bf16 v[116:119], v[138:141], v[192:195], v[116:119]
	v_mfma_f32_16x16x32_bf16 v[112:115], v[150:153], v[192:195], v[112:115]
	v_mfma_f32_16x16x32_bf16 v[104:107], v[138:141], v[200:203], v[104:107]
	v_mfma_f32_16x16x32_bf16 v[96:99], v[150:153], v[200:203], v[96:99]
	v_mfma_f32_16x16x32_bf16 v[88:91], v[138:141], v[208:211], v[88:91]
	v_mfma_f32_16x16x32_bf16 v[80:83], v[150:153], v[208:211], v[80:83]
	v_mfma_f32_16x16x32_bf16 v[124:127], v[142:145], v[188:191], v[124:127]
	v_mfma_f32_16x16x32_bf16 v[120:123], v[154:157], v[188:191], v[120:123]
	v_mfma_f32_16x16x32_bf16 v[116:119], v[142:145], v[196:199], v[116:119]
	v_mfma_f32_16x16x32_bf16 v[112:115], v[154:157], v[196:199], v[112:115]
	v_mfma_f32_16x16x32_bf16 v[104:107], v[142:145], v[204:207], v[104:107]
	v_mfma_f32_16x16x32_bf16 v[96:99], v[154:157], v[204:207], v[96:99]
	v_mfma_f32_16x16x32_bf16 v[88:91], v[142:145], v[212:215], v[88:91]
	v_mfma_f32_16x16x32_bf16 v[80:83], v[154:157], v[212:215], v[80:83]
	v_mfma_f32_16x16x32_bf16 v[108:111], v[158:161], v[184:187], v[108:111]
	v_mfma_f32_16x16x32_bf16 v[100:103], v[166:169], v[184:187], v[100:103]
	v_mfma_f32_16x16x32_bf16 v[92:95], v[158:161], v[192:195], v[92:95]
	v_mfma_f32_16x16x32_bf16 v[84:87], v[166:169], v[192:195], v[84:87]
	v_mfma_f32_16x16x32_bf16 v[76:79], v[158:161], v[200:203], v[76:79]
	v_mfma_f32_16x16x32_bf16 v[72:75], v[166:169], v[200:203], v[72:75]
	v_mfma_f32_16x16x32_bf16 v[68:71], v[158:161], v[208:211], v[68:71]
	v_mfma_f32_16x16x32_bf16 v[64:67], v[166:169], v[208:211], v[64:67]
	v_mfma_f32_16x16x32_bf16 v[108:111], v[162:165], v[188:191], v[108:111]
	v_mfma_f32_16x16x32_bf16 v[100:103], v[170:173], v[188:191], v[100:103]
	v_mfma_f32_16x16x32_bf16 v[92:95], v[162:165], v[196:199], v[92:95]
	v_mfma_f32_16x16x32_bf16 v[84:87], v[170:173], v[196:199], v[84:87]
	v_mfma_f32_16x16x32_bf16 v[76:79], v[162:165], v[204:207], v[76:79]
	v_mfma_f32_16x16x32_bf16 v[72:75], v[170:173], v[204:207], v[72:75]
	v_mfma_f32_16x16x32_bf16 v[68:71], v[162:165], v[212:215], v[68:71]
	v_mfma_f32_16x16x32_bf16 v[64:67], v[170:173], v[212:215], v[64:67]
	s_barrier
	s_add_i32 s22, s22, s18
	v_lshl_add_u64 v[174:175], s[20:21], 0, v[176:177]
	s_mov_b32 m0, s22
	ds_read_b128 v[184:187], v149 offset:16384
	ds_read_b128 v[188:191], v149 offset:17408
	ds_read_b128 v[192:195], v149 offset:18432
	ds_read_b128 v[196:199], v149 offset:19456
	ds_read_b128 v[200:203], v149 offset:20480
	ds_read_b128 v[204:207], v149 offset:21504
	ds_read_b128 v[208:211], v149 offset:22528
	ds_read_b128 v[212:215], v149 offset:23552
	global_load_lds_dwordx4 v[174:175], off
	s_add_i32 m0, s22, 0x2000
	v_lshl_add_u64 v[180:181], s[20:21], 0, v[128:129]
	s_add_u32 s20, s20, s6
	s_addc_u32 s21, s21, s7
	s_add_i32 s22, s23, s18
	global_load_lds_dwordx4 v[180:181], off
	v_lshl_add_u64 v[182:183], s[20:21], 0, v[176:177]
	s_mov_b32 m0, s22
	v_lshl_add_u64 v[216:217], s[20:21], 0, v[128:129]
	global_load_lds_dwordx4 v[182:183], off
	s_add_i32 m0, s22, 0x2000
	v_lshl_add_u64 v[218:219], s[40:41], 0, v[132:133]
	global_load_lds_dwordx4 v[216:217], off
	s_mov_b32 m0, s31
	v_lshl_add_u64 v[220:221], s[40:41], 0, v[130:131]
	global_load_lds_dwordx4 v[218:219], off
	s_mov_b32 m0, s42
	s_nop 0
	global_load_lds_dwordx4 v[220:221], off
	s_waitcnt vmcnt(8)
	s_waitcnt lgkmcnt(0)
	s_barrier
; #define PG8_STAGE(bufoff, gbase, voff) do { _Pragma("unroll") for (int _i = 0; _i < 2; ++_i) \
;         __builtin_amdgcn_global_load_lds((const unsigned*)((const char*)(gbase) + (voff)[_i]), (LAS unsigned*)(lds + (bufoff) + ldsw + _i * 8192), 16, 0, 0); } while (0)
; #define PG8_LDA(dst, b, h) do { _Pragma("unroll") for (int m = 0; m < 4; ++m) _Pragma("unroll") for (int k = 0; k < 2; ++k) dst[m][k] = *(const LAS bf16x8*)(lds + PG8_SA(b, h) + aoff + m * 2048 + k * 1024); } while (0)
; #define PG8_LDB(dst, b, h) do { _Pragma("unroll") for (int n = 0; n < 2; ++n) _Pragma("unroll") for (int k = 0; k < 2; ++k) dst[n][k] = *(const LAS bf16x8*)(lds + PG8_SB(b, h) + boff + n * 2048 + k * 1024); } while (0)
; #define PG8_MMA(ai, bj, At, Bt) do { __builtin_amdgcn_s_setprio(1); _Pragma("unroll") for (int m = 0; m < 4; ++m) _Pragma("unroll") for (int n = 0; n < 2; ++n) _Pragma("unroll") for (int k = 0; k < 2; ++k) \
;         acc[ai][bj][m][n] = __builtin_amdgcn_mfma_f32_16x16x32_bf16(Bt[n][k], At[m][k], acc[ai][bj][m][n], 0, 0, 0); __builtin_amdgcn_s_setprio(0); } while (0)
; #define PG8_WAIT_V(n) asm volatile("s_waitcnt vmcnt(" #n ")" ::: "memory")
; #define PG8_WAIT_L(n) asm volatile("s_waitcnt lgkmcnt(" #n ")" ::: "memory")
; #define PG8_BAR __builtin_amdgcn_s_barrier()
; #define PG8_SCHED __builtin_amdgcn_sched_barrier(0)
; template <class Epi, bool ALIGN_EPI = PG8_ALIGN>
; __device__ __forceinline__ void gemm_phase(LAS unsigned char* lds, const Gemm g, const StaticOrder& S, const Epi& E) {
;     ...
;             PG8_WAIT_V(8); PG8_WAIT_L(0); PG8_BAR; PG8_MMA(1, 0, At, B0); PG8_MMA(1, 1, At, B1); PG8_BAR; PG8_SCHED;
;             PG8_LDB(B0, 1, 0); PG8_LDB(B1, 1, 1); PG8_SCHED; PG8_LDA(At, 1, 0); PG8_STAGE(PG8_SA(0, 1), a2 + hstepA, voffA);
;             PG8_WAIT_V(8); PG8_WAIT_L(0); PG8_BAR; PG8_MMA(0, 0, At, B0); PG8_MMA(0, 1, At, B1); PG8_BAR; PG8_SCHED;
	s_waitcnt lgkmcnt(0)
	v_mfma_f32_16x16x32_bf16 v[60:63], v[138:141], v[184:187], v[60:63]
	v_mfma_f32_16x16x32_bf16 v[56:59], v[150:153], v[184:187], v[56:59]
	v_mfma_f32_16x16x32_bf16 v[52:55], v[138:141], v[192:195], v[52:55]
	v_mfma_f32_16x16x32_bf16 v[48:51], v[150:153], v[192:195], v[48:51]
	v_mfma_f32_16x16x32_bf16 v[40:43], v[138:141], v[200:203], v[40:43]
	v_mfma_f32_16x16x32_bf16 v[32:35], v[150:153], v[200:203], v[32:35]
	v_mfma_f32_16x16x32_bf16 v[24:27], v[138:141], v[208:211], v[24:27]
	v_mfma_f32_16x16x32_bf16 v[16:19], v[150:153], v[208:211], v[16:19]
	v_mfma_f32_16x16x32_bf16 v[60:63], v[142:145], v[188:191], v[60:63]
	v_mfma_f32_16x16x32_bf16 v[56:59], v[154:157], v[188:191], v[56:59]
	v_mfma_f32_16x16x32_bf16 v[52:55], v[142:145], v[196:199], v[52:55]
	v_mfma_f32_16x16x32_bf16 v[48:51], v[154:157], v[196:199], v[48:51]
	v_mfma_f32_16x16x32_bf16 v[40:43], v[142:145], v[204:207], v[40:43]
	v_mfma_f32_16x16x32_bf16 v[32:35], v[154:157], v[204:207], v[32:35]
	v_mfma_f32_16x16x32_bf16 v[24:27], v[142:145], v[212:215], v[24:27]
	v_mfma_f32_16x16x32_bf16 v[16:19], v[154:157], v[212:215], v[16:19]
	v_mfma_f32_16x16x32_bf16 v[44:47], v[158:161], v[184:187], v[44:47]
	v_mfma_f32_16x16x32_bf16 v[36:39], v[166:169], v[184:187], v[36:39]
	v_mfma_f32_16x16x32_bf16 v[28:31], v[158:161], v[192:195], v[28:31]
	v_mfma_f32_16x16x32_bf16 v[20:23], v[166:169], v[192:195], v[20:23]
	v_mfma_f32_16x16x32_bf16 v[12:15], v[158:161], v[200:203], v[12:15]
	v_mfma_f32_16x16x32_bf16 v[8:11], v[166:169], v[200:203], v[8:11]
	v_mfma_f32_16x16x32_bf16 v[4:7], v[158:161], v[208:211], v[4:7]
	v_mfma_f32_16x16x32_bf16 v[0:3], v[166:169], v[208:211], v[0:3]
	v_mfma_f32_16x16x32_bf16 v[44:47], v[162:165], v[188:191], v[44:47]
	v_mfma_f32_16x16x32_bf16 v[36:39], v[170:173], v[188:191], v[36:39]
	v_mfma_f32_16x16x32_bf16 v[28:31], v[162:165], v[196:199], v[28:31]
	v_mfma_f32_16x16x32_bf16 v[20:23], v[170:173], v[196:199], v[20:23]
	v_mfma_f32_16x16x32_bf16 v[12:15], v[162:165], v[204:207], v[12:15]
	v_mfma_f32_16x16x32_bf16 v[8:11], v[170:173], v[204:207], v[8:11]
	v_mfma_f32_16x16x32_bf16 v[4:7], v[162:165], v[212:215], v[4:7]
	v_mfma_f32_16x16x32_bf16 v[0:3], v[170:173], v[212:215], v[0:3]
	s_barrier
	s_add_i32 s22, 16, 0x18000
	s_add_i32 s23, 16, 0x1c000
	v_add_u32_e32 v154, s22, v147
	v_add_u32_e32 v170, s23, v147
	ds_read_b128 v[138:141], v154
	ds_read_b128 v[142:145], v154 offset:1024
	ds_read_b128 v[150:153], v154 offset:2048
	ds_read_b128 v[154:157], v154 offset:3072
	ds_read_b128 v[158:161], v170
	ds_read_b128 v[162:165], v170 offset:1024
	ds_read_b128 v[166:169], v170 offset:2048
	ds_read_b128 v[170:173], v170 offset:3072
	s_add_u32 s20, s40, 0x160000
	s_addc_u32 s21, s41, 0
	s_mov_b32 m0, s43
	v_lshl_add_u64 v[222:223], s[20:21], 0, v[132:133]
	ds_read_b128 v[184:187], v149 offset:32768
	ds_read_b128 v[188:191], v149 offset:33792
	ds_read_b128 v[192:195], v149 offset:34816
	ds_read_b128 v[196:199], v149 offset:35840
	ds_read_b128 v[200:203], v149 offset:36864
	ds_read_b128 v[204:207], v149 offset:37888
	ds_read_b128 v[208:211], v149 offset:38912
	ds_read_b128 v[212:215], v149 offset:39936
	global_load_lds_dwordx4 v[222:223], off
	v_lshl_add_u64 v[222:223], s[20:21], 0, v[130:131]
	s_mov_b32 m0, s44
	s_nop 0
	global_load_lds_dwordx4 v[222:223], off
	s_waitcnt vmcnt(8)
	s_waitcnt lgkmcnt(0)
	s_barrier
	s_waitcnt lgkmcnt(0)
	v_mfma_f32_16x16x32_bf16 v[124:127], v[138:141], v[184:187], v[124:127]
	v_mfma_f32_16x16x32_bf16 v[120:123], v[150:153], v[184:187], v[120:123]
	v_mfma_f32_16x16x32_bf16 v[116:119], v[138:141], v[192:195], v[116:119]
	v_mfma_f32_16x16x32_bf16 v[112:115], v[150:153], v[192:195], v[112:115]
	v_mfma_f32_16x16x32_bf16 v[104:107], v[138:141], v[200:203], v[104:107]
	v_mfma_f32_16x16x32_bf16 v[96:99], v[150:153], v[200:203], v[96:99]
	v_mfma_f32_16x16x32_bf16 v[88:91], v[138:141], v[208:211], v[88:91]
	v_mfma_f32_16x16x32_bf16 v[80:83], v[150:153], v[208:211], v[80:83]
	v_mfma_f32_16x16x32_bf16 v[124:127], v[142:145], v[188:191], v[124:127]
	v_mfma_f32_16x16x32_bf16 v[120:123], v[154:157], v[188:191], v[120:123]
	v_mfma_f32_16x16x32_bf16 v[116:119], v[142:145], v[196:199], v[116:119]
	v_mfma_f32_16x16x32_bf16 v[112:115], v[154:157], v[196:199], v[112:115]
	v_mfma_f32_16x16x32_bf16 v[104:107], v[142:145], v[204:207], v[104:107]
	v_mfma_f32_16x16x32_bf16 v[96:99], v[154:157], v[204:207], v[96:99]
	v_mfma_f32_16x16x32_bf16 v[88:91], v[142:145], v[212:215], v[88:91]
	v_mfma_f32_16x16x32_bf16 v[80:83], v[154:157], v[212:215], v[80:83]
	v_mfma_f32_16x16x32_bf16 v[108:111], v[158:161], v[184:187], v[108:111]
	v_mfma_f32_16x16x32_bf16 v[100:103], v[166:169], v[184:187], v[100:103]
	v_mfma_f32_16x16x32_bf16 v[92:95], v[158:161], v[192:195], v[92:95]
	v_mfma_f32_16x16x32_bf16 v[84:87], v[166:169], v[192:195], v[84:87]
	v_mfma_f32_16x16x32_bf16 v[76:79], v[158:161], v[200:203], v[76:79]
	v_mfma_f32_16x16x32_bf16 v[72:75], v[166:169], v[200:203], v[72:75]
	v_mfma_f32_16x16x32_bf16 v[68:71], v[158:161], v[208:211], v[68:71]
	v_mfma_f32_16x16x32_bf16 v[64:67], v[166:169], v[208:211], v[64:67]
	v_mfma_f32_16x16x32_bf16 v[108:111], v[162:165], v[188:191], v[108:111]
	v_mfma_f32_16x16x32_bf16 v[100:103], v[170:173], v[188:191], v[100:103]
	v_mfma_f32_16x16x32_bf16 v[92:95], v[162:165], v[196:199], v[92:95]
	v_mfma_f32_16x16x32_bf16 v[84:87], v[170:173], v[196:199], v[84:87]
	v_mfma_f32_16x16x32_bf16 v[76:79], v[162:165], v[204:207], v[76:79]
	v_mfma_f32_16x16x32_bf16 v[72:75], v[170:173], v[204:207], v[72:75]
	v_mfma_f32_16x16x32_bf16 v[68:71], v[162:165], v[212:215], v[68:71]
	v_mfma_f32_16x16x32_bf16 v[64:67], v[170:173], v[212:215], v[64:67]
	s_barrier
; #define PG8_STAGE(bufoff, gbase, voff) do { _Pragma("unroll") for (int _i = 0; _i < 2; ++_i) \
;         __builtin_amdgcn_global_load_lds((const unsigned*)((const char*)(gbase) + (voff)[_i]), (LAS unsigned*)(lds + (bufoff) + ldsw + _i * 8192), 16, 0, 0); } while (0)
; #define PG8_LDA(dst, b, h) do { _Pragma("unroll") for (int m = 0; m < 4; ++m) _Pragma("unroll") for (int k = 0; k < 2; ++k) dst[m][k] = *(const LAS bf16x8*)(lds + PG8_SA(b, h) + aoff + m * 2048 + k * 1024); } while (0)
; #define PG8_MMA(ai, bj, At, Bt) do { __builtin_amdgcn_s_setprio(1); _Pragma("unroll") for (int m = 0; m < 4; ++m) _Pragma("unroll") for (int n = 0; n < 2; ++n) _Pragma("unroll") for (int k = 0; k < 2; ++k) \
;         acc[ai][bj][m][n] = __builtin_amdgcn_mfma_f32_16x16x32_bf16(Bt[n][k], At[m][k], acc[ai][bj][m][n], 0, 0, 0); __builtin_amdgcn_s_setprio(0); } while (0)
; #define PG8_WAIT_V(n) asm volatile("s_waitcnt vmcnt(" #n ")" ::: "memory")
; #define PG8_WAIT_L(n) asm volatile("s_waitcnt lgkmcnt(" #n ")" ::: "memory")
; #define PG8_BAR __builtin_amdgcn_s_barrier()
; #define PG8_SCHED __builtin_amdgcn_sched_barrier(0)
;     __device__ __forceinline__ void operator()(const f32x4 (&acc)[2][2][4][2], const Unit& u, int wr, int wc, int fr, int fq) const {
;     ...
;                 for (int bj = 0; bj < 2; ++bj) { const f32x4 v0 = acc[ai][bj][m][0] * sc, v1 = acc[ai][bj][m][1] * sc;
; template <class Epi, bool ALIGN_EPI = PG8_ALIGN>
; __device__ __forceinline__ void gemm_phase(LAS unsigned char* lds, const Gemm g, const StaticOrder& S, const Epi& E) {
;     ...
;             PG8_LDA(At, 1, 1); PG8_STAGE(PG8_SB(1, 0), b3, voffB); PG8_STAGE(PG8_SB(1, 1), b3 + hstepB, voffB); PG8_STAGE(PG8_SA(1, 0), a3, voffA);
;             PG8_WAIT_V(8); PG8_WAIT_L(0); PG8_BAR; PG8_MMA(1, 0, At, B0); PG8_MMA(1, 1, At, B1); PG8_BAR; PG8_SCHED;
	s_add_i32 s20, s22, s18
	v_lshl_add_u64 v[174:175], v[174:175], 0, s[0:1]
	s_mov_b32 m0, s20
	ds_read_b128 v[184:187], v149 offset:49152
	ds_read_b128 v[188:191], v149 offset:50176
	ds_read_b128 v[192:195], v149 offset:51200
	ds_read_b128 v[196:199], v149 offset:52224
	ds_read_b128 v[200:203], v149 offset:53248
	ds_read_b128 v[204:207], v149 offset:54272
	ds_read_b128 v[208:211], v149 offset:55296
	ds_read_b128 v[212:215], v149 offset:56320
	global_load_lds_dwordx4 v[174:175], off
	v_lshl_add_u64 v[174:175], v[180:181], 0, s[0:1]
	s_add_i32 m0, s20, 0x2000
	s_add_i32 s20, s23, s18
	global_load_lds_dwordx4 v[174:175], off
	v_lshl_add_u64 v[174:175], v[182:183], 0, s[0:1]
	s_mov_b32 m0, s20
	s_nop 0
	global_load_lds_dwordx4 v[174:175], off
	v_lshl_add_u64 v[174:175], v[216:217], 0, s[0:1]
	s_add_i32 m0, s20, 0x2000
	s_nop 0
	global_load_lds_dwordx4 v[174:175], off
	v_lshl_add_u64 v[174:175], v[218:219], 0, s[0:1]
	s_mov_b32 m0, s45
	s_nop 0
	global_load_lds_dwordx4 v[174:175], off
	v_lshl_add_u64 v[174:175], v[220:221], 0, s[0:1]
	s_mov_b32 m0, s46
	s_nop 0
	global_load_lds_dwordx4 v[174:175], off
	s_waitcnt vmcnt(8)
	s_waitcnt lgkmcnt(0)
	s_barrier
	s_waitcnt lgkmcnt(0)
	v_mfma_f32_16x16x32_bf16 v[60:63], v[138:141], v[184:187], v[60:63]
	v_mfma_f32_16x16x32_bf16 v[56:59], v[150:153], v[184:187], v[56:59]
	v_mfma_f32_16x16x32_bf16 v[52:55], v[138:141], v[192:195], v[52:55]
	v_mfma_f32_16x16x32_bf16 v[48:51], v[150:153], v[192:195], v[48:51]
	v_mfma_f32_16x16x32_bf16 v[40:43], v[138:141], v[200:203], v[40:43]
	v_mfma_f32_16x16x32_bf16 v[32:35], v[150:153], v[200:203], v[32:35]
	v_mfma_f32_16x16x32_bf16 v[24:27], v[138:141], v[208:211], v[24:27]
	v_mfma_f32_16x16x32_bf16 v[16:19], v[150:153], v[208:211], v[16:19]
	v_mfma_f32_16x16x32_bf16 v[60:63], v[142:145], v[188:191], v[60:63]
	v_mfma_f32_16x16x32_bf16 v[56:59], v[154:157], v[188:191], v[56:59]
	v_mfma_f32_16x16x32_bf16 v[52:55], v[142:145], v[196:199], v[52:55]
	v_mfma_f32_16x16x32_bf16 v[48:51], v[154:157], v[196:199], v[48:51]
	v_mfma_f32_16x16x32_bf16 v[40:43], v[142:145], v[204:207], v[40:43]
	v_mfma_f32_16x16x32_bf16 v[32:35], v[154:157], v[204:207], v[32:35]
	v_mfma_f32_16x16x32_bf16 v[24:27], v[142:145], v[212:215], v[24:27]
	v_mfma_f32_16x16x32_bf16 v[16:19], v[154:157], v[212:215], v[16:19]
	v_mfma_f32_16x16x32_bf16 v[44:47], v[158:161], v[184:187], v[44:47]
	v_mfma_f32_16x16x32_bf16 v[36:39], v[166:169], v[184:187], v[36:39]
	v_mfma_f32_16x16x32_bf16 v[28:31], v[158:161], v[192:195], v[28:31]
	v_mfma_f32_16x16x32_bf16 v[20:23], v[166:169], v[192:195], v[20:23]
	v_mfma_f32_16x16x32_bf16 v[12:15], v[158:161], v[200:203], v[12:15]
	v_mfma_f32_16x16x32_bf16 v[8:11], v[166:169], v[200:203], v[8:11]
	v_mfma_f32_16x16x32_bf16 v[4:7], v[158:161], v[208:211], v[4:7]
	v_mfma_f32_16x16x32_bf16 v[0:3], v[166:169], v[208:211], v[0:3]
	v_mfma_f32_16x16x32_bf16 v[44:47], v[162:165], v[188:191], v[44:47]
	v_mfma_f32_16x16x32_bf16 v[36:39], v[170:173], v[188:191], v[36:39]
	v_mfma_f32_16x16x32_bf16 v[28:31], v[162:165], v[196:199], v[28:31]
	v_mfma_f32_16x16x32_bf16 v[20:23], v[170:173], v[196:199], v[20:23]
	v_mfma_f32_16x16x32_bf16 v[12:15], v[162:165], v[204:207], v[12:15]
	v_mfma_f32_16x16x32_bf16 v[8:11], v[170:173], v[204:207], v[8:11]
	v_mfma_f32_16x16x32_bf16 v[4:7], v[162:165], v[212:215], v[4:7]
	v_mfma_f32_16x16x32_bf16 v[0:3], v[170:173], v[212:215], v[0:3]
	s_barrier
	s_add_u32 s51, s51, 0x100
	s_addc_u32 s52, s52, 0
	s_cmp_ge_i32 s53, s26
	s_mov_b64 s[24:25], s[36:37]
	s_mov_b32 s40, s53
	s_cbranch_scc0 .LBB0_1108
	v_pk_mul_f32 v[126:127], v[126:127], 0.5 op_sel_hi:[1,0]
	v_pk_mul_f32 v[124:125], v[124:125], 0.5 op_sel_hi:[1,0]
	v_pk_mul_f32 v[122:123], v[122:123], 0.5 op_sel_hi:[1,0]
	v_pk_mul_f32 v[120:121], v[120:121], 0.5 op_sel_hi:[1,0]
	v_pk_mul_f32 v[138:139], v[110:111], 0.5 op_sel_hi:[1,0]
	v_pk_mul_f32 v[140:141], v[108:109], 0.5 op_sel_hi:[1,0]
	v_pk_mul_f32 v[142:143], v[102:103], 0.5 op_sel_hi:[1,0]
	v_pk_mul_f32 v[144:145], v[100:101], 0.5 op_sel_hi:[1,0]
	v_pk_mul_f32 v[100:101], v[118:119], 0.5 op_sel_hi:[1,0]
	v_pk_mul_f32 v[102:103], v[116:117], 0.5 op_sel_hi:[1,0]
	v_pk_mul_f32 v[108:109], v[114:115], 0.5 op_sel_hi:[1,0]
	v_pk_mul_f32 v[110:111], v[112:113], 0.5 op_sel_hi:[1,0]
	v_pk_mul_f32 v[112:113], v[94:95], 0.5 op_sel_hi:[1,0]
	v_pk_mul_f32 v[114:115], v[92:93], 0.5 op_sel_hi:[1,0]
	v_pk_mul_f32 v[116:117], v[86:87], 0.5 op_sel_hi:[1,0]
	v_pk_mul_f32 v[118:119], v[84:85], 0.5 op_sel_hi:[1,0]
	v_pk_mul_f32 v[84:85], v[106:107], 0.5 op_sel_hi:[1,0]
	v_pk_mul_f32 v[86:87], v[104:105], 0.5 op_sel_hi:[1,0]
	v_pk_mul_f32 v[92:93], v[98:99], 0.5 op_sel_hi:[1,0]
	v_pk_mul_f32 v[94:95], v[96:97], 0.5 op_sel_hi:[1,0]
	v_pk_mul_f32 v[96:97], v[78:79], 0.5 op_sel_hi:[1,0]
	v_pk_mul_f32 v[98:99], v[76:77], 0.5 op_sel_hi:[1,0]
	v_pk_mul_f32 v[104:105], v[74:75], 0.5 op_sel_hi:[1,0]
	v_pk_mul_f32 v[106:107], v[72:73], 0.5 op_sel_hi:[1,0]
	v_pk_mul_f32 v[72:73], v[90:91], 0.5 op_sel_hi:[1,0]
	v_pk_mul_f32 v[74:75], v[88:89], 0.5 op_sel_hi:[1,0]
	v_pk_mul_f32 v[76:77], v[82:83], 0.5 op_sel_hi:[1,0]
	v_pk_mul_f32 v[78:79], v[80:81], 0.5 op_sel_hi:[1,0]
	v_pk_mul_f32 v[70:71], v[70:71], 0.5 op_sel_hi:[1,0]
	v_pk_mul_f32 v[68:69], v[68:69], 0.5 op_sel_hi:[1,0]
	v_pk_mul_f32 v[66:67], v[66:67], 0.5 op_sel_hi:[1,0]
	v_pk_mul_f32 v[64:65], v[64:65], 0.5 op_sel_hi:[1,0]
	v_pk_mul_f32 v[62:63], v[62:63], 0.5 op_sel_hi:[1,0]
	v_pk_mul_f32 v[60:61], v[60:61], 0.5 op_sel_hi:[1,0]
	v_pk_mul_f32 v[58:59], v[58:59], 0.5 op_sel_hi:[1,0]
	v_pk_mul_f32 v[56:57], v[56:57], 0.5 op_sel_hi:[1,0]
	v_pk_mul_f32 v[80:81], v[46:47], 0.5 op_sel_hi:[1,0]
	v_pk_mul_f32 v[82:83], v[44:45], 0.5 op_sel_hi:[1,0]
	v_pk_mul_f32 v[88:89], v[38:39], 0.5 op_sel_hi:[1,0]
	v_pk_mul_f32 v[90:91], v[36:37], 0.5 op_sel_hi:[1,0]
	v_pk_mul_f32 v[36:37], v[54:55], 0.5 op_sel_hi:[1,0]
	v_pk_mul_f32 v[38:39], v[52:53], 0.5 op_sel_hi:[1,0]
	v_pk_mul_f32 v[44:45], v[50:51], 0.5 op_sel_hi:[1,0]
	v_pk_mul_f32 v[46:47], v[48:49], 0.5 op_sel_hi:[1,0]
	v_pk_mul_f32 v[48:49], v[30:31], 0.5 op_sel_hi:[1,0]
	v_pk_mul_f32 v[50:51], v[28:29], 0.5 op_sel_hi:[1,0]
	v_pk_mul_f32 v[52:53], v[22:23], 0.5 op_sel_hi:[1,0]
	v_pk_mul_f32 v[54:55], v[20:21], 0.5 op_sel_hi:[1,0]
	v_pk_mul_f32 v[20:21], v[42:43], 0.5 op_sel_hi:[1,0]
	v_pk_mul_f32 v[22:23], v[40:41], 0.5 op_sel_hi:[1,0]
	v_pk_mul_f32 v[28:29], v[34:35], 0.5 op_sel_hi:[1,0]
	v_pk_mul_f32 v[30:31], v[32:33], 0.5 op_sel_hi:[1,0]
	v_pk_mul_f32 v[32:33], v[14:15], 0.5 op_sel_hi:[1,0]
	v_pk_mul_f32 v[34:35], v[12:13], 0.5 op_sel_hi:[1,0]
	v_pk_mul_f32 v[40:41], v[10:11], 0.5 op_sel_hi:[1,0]
	v_pk_mul_f32 v[42:43], v[8:9], 0.5 op_sel_hi:[1,0]
	v_pk_mul_f32 v[8:9], v[26:27], 0.5 op_sel_hi:[1,0]
	v_pk_mul_f32 v[10:11], v[24:25], 0.5 op_sel_hi:[1,0]
	v_pk_mul_f32 v[12:13], v[18:19], 0.5 op_sel_hi:[1,0]
	v_pk_mul_f32 v[14:15], v[16:17], 0.5 op_sel_hi:[1,0]
	v_pk_mul_f32 v[6:7], v[6:7], 0.5 op_sel_hi:[1,0]
	v_pk_mul_f32 v[4:5], v[4:5], 0.5 op_sel_hi:[1,0]
	v_pk_mul_f32 v[2:3], v[2:3], 0.5 op_sel_hi:[1,0]
	v_pk_mul_f32 v[0:1], v[0:1], 0.5 op_sel_hi:[1,0]
